# retention: per-unit lane tables for DMA bases (v_readlane), conflict-free K swizzle, V DMA 3 sub-tiles ahead, wave halves run S/PV in opposite order
# speedup vs baseline: 1.0694x; 1.0079x over previous
; __device__ __forceinline__ void ret_unit(ldsp lds, bf16_t* R, const bf16_t* RC, int b, int h, int qblk, float lgf2, float lgb2, const int tid_in) {
;     int tl0_ = tid_in; asm volatile("" : "+v"(tl0_));
;     const int tid_outer = tl0_;
;     const int wid = __builtin_amdgcn_readfirstlane(tid_outer >> 6);
;     const ldsp Ks = lds, Vs = lds + 67584, Ps = lds + 134144;
;     const int q0 = qblk * 64, rowq0 = b * SEQ + q0;
;     const int qb = wid & 3, kbp = wid >> 2;
;     bf16x8 qf[8];
;     { const int l15 = tid_outer & 15, lg = (tid_outer & 63) >> 4;
; #pragma unroll
;       for (int ks = 0; ks < 8; ++ks) qf[ks] = *(const bf16x8*)(R + (size_t)(rowq0 + 16 * qb + l15) * 6144 + h * 256 + 32 * ks + 8 * lg); }
;     u32x4 vr[8];
.LBB0_590:
	s_and_b64 vcc, exec, s[8:9]
	s_cbranch_vccz .LBB0_810
	s_cmp_lt_i32 s47, 2
	s_mov_b64 s[4:5], -1
	s_cbranch_scc1 .LBB0_746
	s_cmp_eq_u32 s47, 2
	s_movk_i32 s4, 0x3000
	s_cbranch_scc0 .LBB0_745
	s_waitcnt lgkmcnt(0)
	s_load_dwordx2 s[0:1], s[62:63], 0xc0
	v_and_b32_e32 v211, 63, v196
	v_and_b32_e32 v209, 15, v196
	v_bfe_u32 v210, v196, 4, 2
	v_lshrrev_b32_e32 v212, 6, v196
	s_and_b32 s7, s96, 3
	s_lshr_b32 s9, s96, 3
	s_lshl_b32 s13, s9, 6
	v_readfirstlane_b32 s10, v212
	s_lshr_b32 s14, s10, 2
	s_and_b32 s41, s10, 3
	s_waitcnt lgkmcnt(0)
	s_lshl_b32 s46, s7, 2
	s_add_u32 s4, s0, 0xd8000
	s_addc_u32 s5, s1, 0
	s_add_u32 s4, s4, s46
	s_addc_u32 s5, s5, 0
	global_load_dword v207, v97, s[4:5]
	global_load_dword v208, v97, s[4:5] offset:16
	s_lshl_b32 s54, s10, 11
	s_mul_i32 s55, s10, 12288
	s_add_i32 s55, s55, 49152
	v_lshrrev_b32_e32 v212, 5, v211
	v_and_b32_e32 v213, 31, v211
	s_lshl_b32 s46, s10, 2
	v_add_u32_e32 v214, s46, v212
	v_and_b32_e32 v215, 15, v214
	v_xor_b32_e32 v215, v215, v213
	v_lshlrev_b32_e32 v215, 4, v215
	s_movk_i32 s48, 0x3000
	v_mad_u32_u24 v189, v214, s48, v215
	s_movk_i32 s48, 0x1800
	v_mad_u32_u24 v191, v214, s48, v215
	s_lshl_b32 s46, s10, 2
	s_add_i32 s46, s46, 2
	v_add_u32_e32 v214, s46, v212
	v_and_b32_e32 v215, 15, v214
	v_xor_b32_e32 v215, v215, v213
	v_lshlrev_b32_e32 v215, 4, v215
	s_movk_i32 s48, 0x3000
	v_mad_u32_u24 v190, v214, s48, v215
	s_movk_i32 s48, 0x1800
	v_mad_u32_u24 v192, v214, s48, v215
	v_lshrrev_b32_e32 v212, 3, v211
	v_and_b32_e32 v213, 7, v211
	v_bfe_u32 v214, v211, 4, 1
	v_lshlrev_b32_e32 v214, 1, v214
	v_xor_b32_e32 v213, v213, v214
	v_xor_b32_e32 v214, 4, v213
	v_lshlrev_b32_e32 v213, 4, v213
	v_lshlrev_b32_e32 v214, 4, v214
	s_lshl_b32 s46, s10, 7
	s_lshl_b32 s48, s7, 9
	s_add_i32 s46, s46, s48
	s_addk_i32 s46, 0x800
	s_movk_i32 s48, 0x3000
	v_mov_b32_e32 v215, s46
	v_mad_u32_u24 v215, v212, s48, v215
	v_add_u32_e32 v193, v215, v213
	v_add_u32_e32 v194, v215, v214
	v_add_u32_e32 v194, 0x18000, v194
	v_add_u32_e32 v195, v215, v213
	v_add_u32_e32 v195, 0x30000, v195
	v_add_u32_e32 v197, v215, v214
	v_add_u32_e32 v197, 0x48000, v197
	s_movk_i32 s48, 0x1800
	v_mov_b32_e32 v215, s46
	v_mad_u32_u24 v215, v212, s48, v215
	v_add_u32_e32 v198, v215, v213
	v_add_u32_e32 v199, v215, v214
	v_add_u32_e32 v199, 0xc000, v199
	v_add_u32_e32 v200, v215, v213
	v_add_u32_e32 v200, 0x18000, v200
	v_add_u32_e32 v202, v215, v214
	v_add_u32_e32 v202, 0x24000, v202
	s_lshl_b32 s46, s41, 4
	s_add_i32 s46, s46, s13
	s_lshl_b32 s48, s14, 4
	s_sub_i32 s46, s46, s48
	v_lshlrev_b32_e32 v212, 2, v210
	v_sub_u32_e32 v212, v209, v212
	v_add_u32_e32 v203, s46, v212
	v_add_u32_e32 v204, -1, v203
	v_add_u32_e32 v205, -2, v203
	v_add_u32_e32 v206, -3, v203
	s_lshl_b32 s46, s14, 4
	v_add_u32_e32 v213, s46, v209
	v_lshlrev_b32_e32 v213, 9, v213
	v_and_b32_e32 v214, 3, v209
	v_xor_b32_e32 v214, v214, v210
	v_lshl_add_u32 v213, v214, 4, v213
	v_lshrrev_b32_e32 v214, 2, v209
	v_xor_b32_e32 v215, 0, v214
	v_lshl_add_u32 v182, v215, 6, v213
	v_xor_b32_e32 v215, 1, v214
	v_lshl_add_u32 v246, v215, 6, v213
	v_xor_b32_e32 v215, 2, v214
	v_lshl_add_u32 v247, v215, 6, v213
	v_xor_b32_e32 v215, 3, v214
	v_lshl_add_u32 v248, v215, 6, v213
	v_lshrrev_b32_e32 v212, 3, v209
	v_lshlrev_b32_e32 v213, 10, v210
	v_lshrrev_b32_e32 v214, 2, v209
	v_lshl_add_u32 v213, v214, 7, v213
	v_bfe_u32 v214, v209, 1, 1
	v_lshl_add_u32 v213, v214, 4, v213
	v_and_b32_e32 v214, 1, v209
	v_lshl_add_u32 v213, v214, 3, v213
	v_add_u32_e32 v213, s55, v213
	v_and_b32_e32 v214, 1, v210
	v_lshl_or_b32 v214, v214, 1, v212
	v_xor_b32_e32 v215, 0, v214
	v_lshl_add_u32 v183, v215, 5, v213
	v_xor_b32_e32 v215, 1, v214
	v_lshl_add_u32 v184, v215, 5, v213
	v_xor_b32_e32 v215, 2, v214
	v_lshl_add_u32 v185, v215, 5, v213
	v_xor_b32_e32 v215, 3, v214
	v_lshl_add_u32 v186, v215, 5, v213
	v_mul_u32_u24_e32 v212, 0x50, v209
	v_lshl_add_u32 v187, v210, 4, v212
	v_add_u32_e32 v187, 0x24000, v187
	s_mul_i32 s46, s41, 1280
	s_lshl_b32 s48, s14, 5
	s_add_i32 s46, s46, s48
	s_add_i32 s46, s46, 0x24000
	v_lshl_add_u32 v188, v210, 3, v212
	v_add_u32_e32 v188, s46, v188
	s_lshl_b32 s46, s41, 4
	v_add_u32_e32 v212, s46, v209
	v_mul_u32_u24_e32 v212, 0x3000, v212
	v_lshl_add_u32 v219, v210, 4, v212
	v_mul_u32_u24_e32 v212, 0x3000, v209
	s_lshl_b32 s46, s10, 7
	v_lshl_add_u32 v212, v210, 3, v212
	v_add_u32_e32 v226, s46, v212
	v_add_u32_e32 v227, 0x30000, v226
	v_add_u32_e32 v228, 0x60000, v226
	v_add_u32_e32 v229, 0x90000, v226
	s_waitcnt vmcnt(0)
	v_readfirstlane_b32 s11, v207
	v_readfirstlane_b32 s12, v208
	s_mov_b32 s3, 0
	s_lshr_b32 s38, s10, 2
	s_mov_b32 s31, 0
	s_mov_b32 s29, s9
; #define RET_BAR() do { asm volatile("s_waitcnt lgkmcnt(0)" ::: "memory"); __builtin_amdgcn_s_barrier(); asm volatile("" ::: "memory"); } while (0)
; #define RET_LOADV(t) do { RET_KV(t) const char* vb_ = kb_ + (1024 + h * 256) * 2; const unsigned lo_ = (unsigned)(tid >> 6) * kp_ + (unsigned)(tid & 63) * 16u; \
;         _Pragma("unroll") for (int i_ = 0; i_ < 8; ++i_) vr[i_] = *(const u32x4*)(vb_ + (size_t)(8u * i_) * kp_ + lo_); } while (0)
; #define RET_STOREV() do { _Pragma("unroll") for (int i_ = 0; i_ < 8; ++i_) *(LAS u32x4*)(Vs + ((tid >> 6) + 8 * i_) * 1040 + (tid & 63) * 16) = vr[i_]; } while (0)
; __device__ __forceinline__ void ret_unit(ldsp lds, bf16_t* R, const bf16_t* RC, int b, int h, int qblk, float lgf2, float lgb2, const int tid_in) {
;     ...
;     { const int tid = tid_outer, lane = tid & 63, l15 = lane & 15, lg = lane >> 4;
;       RET_BAR();
;       RET_DMAK(TI(0), 0); RET_DMAK(TI(1), 1); RET_LOADV(TI(0));
;       asm volatile("s_waitcnt vmcnt(0)" ::: "memory");
;       RET_STOREV();
;       RET_BAR();
;       RET_S(0, TI(0));
;       RET_LOADV(TI(1));
;       RET_BAR();
;       RET_DMAK(TI(2), 0); }
.Lret_unit:
	s_bfe_u32 s8, s96, 0x10002
	s_lshl_b32 s41, s3, 1
	s_or_b32 s8, s8, s41
	s_mul_i32 s41, s8, 0x1800000
	s_add_u32 s22, s0, 0x9400000
	s_addc_u32 s23, s1, 0
	s_add_u32 s22, s22, s41
	s_addc_u32 s23, s23, 0
	s_mul_i32 s41, s8, 0x180000
	s_add_u32 s24, s0, 0x15400000
	s_addc_u32 s25, s1, 0
	s_add_u32 s24, s24, s41
	s_addc_u32 s25, s25, 0
	s_lshl_b32 s46, s7, 9
	s_add_u32 s78, s22, s46
	s_addc_u32 s79, s23, 0
	s_add_u32 s78, s78, 0x800
	s_addc_u32 s79, s79, 0
	s_add_u32 s80, s24, s46
	s_addc_u32 s81, s25, 0
	s_mul_i32 s41, s13, 0x3000
	s_add_u32 s86, s22, s41
	s_addc_u32 s87, s23, 0
	s_add_u32 s86, s86, s46
	s_addc_u32 s87, s87, 0
	v_add_u32_e32 v212, s29, v211
	v_add_u32_e32 v213, -36, v212
	v_cmp_gt_u32_e32 vcc, 36, v212
	s_nop 1
	v_cndmask_b32_e32 v236, v213, v212, vcc
	v_cmp_gt_u32_e32 vcc, 32, v236
	v_add_u32_e32 v213, -32, v236
	v_mul_u32_u24_e32 v212, 0xc0000, v236
	v_mul_u32_u24_e32 v213, 0x60000, v213
	v_cndmask_b32_e64 v237, 0, -1, vcc
	v_cndmask_b32_e32 v212, v213, v212, vcc
	v_mov_b32_e32 v213, 0x30000
	v_mov_b32_e32 v214, 0x60000
	v_cndmask_b32_e32 v213, v213, v214, vcc
	v_add_u32_e32 v213, v212, v213
	v_mov_b32_e32 v214, s80
	v_mov_b32_e32 v215, s78
	v_cndmask_b32_e32 v214, v214, v215, vcc
	v_mov_b32_e32 v239, s81
	v_mov_b32_e32 v215, s79
	v_cndmask_b32_e32 v215, v239, v215, vcc
	v_add_co_u32_e32 v238, vcc, v214, v212
	s_nop 1
	v_addc_co_u32_e32 v239, vcc, 0, v215, vcc
	v_add_co_u32_e32 v240, vcc, v214, v213
	s_nop 1
	v_addc_co_u32_e32 v241, vcc, 0, v215, vcc
	s_barrier
	global_load_dwordx4 v[64:67], v219, s[86:87] offset:0
	global_load_dwordx4 v[68:71], v219, s[86:87] offset:64
	global_load_dwordx4 v[72:75], v219, s[86:87] offset:128
	global_load_dwordx4 v[76:79], v219, s[86:87] offset:192
	global_load_dwordx4 v[80:83], v219, s[86:87] offset:256
	global_load_dwordx4 v[84:87], v219, s[86:87] offset:320
	global_load_dwordx4 v[88:91], v219, s[86:87] offset:384
	global_load_dwordx4 v[92:95], v219, s[86:87] offset:448
	s_mov_b32 s41, 0
	v_readlane_b32 s42, v238, s41
	v_readlane_b32 s43, v239, s41
	v_readlane_b32 s4, v237, s41
	s_mov_b32 s5, s4
	s_nop 0
	v_cndmask_b32_e64 v230, v191, v189, s[4:5]
	v_cndmask_b32_e64 v231, v192, v190, s[4:5]
	v_cndmask_b32_e64 v232, v198, v193, s[4:5]
	v_cndmask_b32_e64 v233, v199, v194, s[4:5]
	v_cndmask_b32_e64 v234, v200, v195, s[4:5]
	v_cndmask_b32_e64 v235, v202, v197, s[4:5]
	s_add_i32 m0, s54, 0
	s_nop 0
	global_load_lds_dwordx4 v230, s[42:43]
	s_add_i32 m0, s54, 1024
	s_nop 0
	global_load_lds_dwordx4 v231, s[42:43]
	s_add_i32 m0, s55, 0
	s_nop 0
	global_load_lds_dwordx4 v232, s[42:43]
	s_add_i32 m0, s55, 1024
	s_nop 0
	global_load_lds_dwordx4 v233, s[42:43]
	s_add_i32 m0, s55, 2048
	s_nop 0
	global_load_lds_dwordx4 v234, s[42:43]
	s_add_i32 m0, s55, 3072
	s_nop 0
	global_load_lds_dwordx4 v235, s[42:43]
	s_mov_b32 s41, 0
	v_readlane_b32 s42, v240, s41
	v_readlane_b32 s43, v241, s41
	v_readlane_b32 s4, v237, s41
	s_mov_b32 s5, s4
	s_nop 0
	v_cndmask_b32_e64 v230, v191, v189, s[4:5]
	v_cndmask_b32_e64 v231, v192, v190, s[4:5]
	v_cndmask_b32_e64 v232, v198, v193, s[4:5]
	v_cndmask_b32_e64 v233, v199, v194, s[4:5]
	v_cndmask_b32_e64 v234, v200, v195, s[4:5]
	v_cndmask_b32_e64 v235, v202, v197, s[4:5]
	s_add_i32 m0, s54, 16384
	s_nop 0
	global_load_lds_dwordx4 v230, s[42:43]
	s_add_i32 m0, s54, 17408
	s_nop 0
	global_load_lds_dwordx4 v231, s[42:43]
	s_add_i32 m0, s55, 4096
	s_nop 0
	global_load_lds_dwordx4 v232, s[42:43]
	s_add_i32 m0, s55, 5120
	s_nop 0
	global_load_lds_dwordx4 v233, s[42:43]
	s_add_i32 m0, s55, 6144
	s_nop 0
	global_load_lds_dwordx4 v234, s[42:43]
	s_add_i32 m0, s55, 7168
	s_nop 0
	global_load_lds_dwordx4 v235, s[42:43]
	s_mov_b32 s41, 1
	v_readlane_b32 s42, v238, s41
	v_readlane_b32 s43, v239, s41
	v_readlane_b32 s4, v237, s41
	s_mov_b32 s5, s4
	s_nop 0
	v_cndmask_b32_e64 v230, v191, v189, s[4:5]
	v_cndmask_b32_e64 v231, v192, v190, s[4:5]
	v_cndmask_b32_e64 v232, v198, v193, s[4:5]
	v_cndmask_b32_e64 v233, v199, v194, s[4:5]
	v_cndmask_b32_e64 v234, v200, v195, s[4:5]
	v_cndmask_b32_e64 v235, v202, v197, s[4:5]
	s_add_i32 m0, s54, 32768
	s_nop 0
	global_load_lds_dwordx4 v230, s[42:43]
	s_add_i32 m0, s54, 33792
	s_nop 0
	global_load_lds_dwordx4 v231, s[42:43]
	s_add_i32 m0, s55, 8192
	s_nop 0
	global_load_lds_dwordx4 v232, s[42:43]
	s_add_i32 m0, s55, 9216
	s_nop 0
	global_load_lds_dwordx4 v233, s[42:43]
	s_add_i32 m0, s55, 10240
	s_nop 0
	global_load_lds_dwordx4 v234, s[42:43]
	s_add_i32 m0, s55, 11264
	s_nop 0
	global_load_lds_dwordx4 v235, s[42:43]
	v_mov_b64_e32 v[0:1], 0
	v_mov_b64_e32 v[2:3], 0
	v_mov_b64_e32 v[4:5], 0
	v_mov_b64_e32 v[6:7], 0
	v_mov_b64_e32 v[8:9], 0
	v_mov_b64_e32 v[10:11], 0
	v_mov_b64_e32 v[12:13], 0
	v_mov_b64_e32 v[14:15], 0
	v_mov_b64_e32 v[16:17], 0
	v_mov_b64_e32 v[18:19], 0
	v_mov_b64_e32 v[20:21], 0
	v_mov_b64_e32 v[22:23], 0
	v_mov_b64_e32 v[24:25], 0
	v_mov_b64_e32 v[26:27], 0
	v_mov_b64_e32 v[28:29], 0
	v_mov_b64_e32 v[30:31], 0
	v_mov_b64_e32 v[32:33], 0
	v_mov_b64_e32 v[34:35], 0
	v_mov_b64_e32 v[36:37], 0
	v_mov_b64_e32 v[38:39], 0
	v_mov_b64_e32 v[40:41], 0
	v_mov_b64_e32 v[42:43], 0
	v_mov_b64_e32 v[44:45], 0
	v_mov_b64_e32 v[46:47], 0
	v_mov_b64_e32 v[48:49], 0
	v_mov_b64_e32 v[50:51], 0
	v_mov_b64_e32 v[52:53], 0
	v_mov_b64_e32 v[54:55], 0
	v_mov_b64_e32 v[56:57], 0
	v_mov_b64_e32 v[58:59], 0
	v_mov_b64_e32 v[60:61], 0
	v_mov_b64_e32 v[62:63], 0
	s_waitcnt vmcnt(16)
	s_barrier
	ds_read_b128 v[102:105], v182 offset:0
	ds_read_b128 v[106:109], v246 offset:0
	ds_read_b128 v[110:113], v247 offset:0
	ds_read_b128 v[114:117], v248 offset:0
	ds_read_b128 v[118:121], v182 offset:256
	ds_read_b128 v[122:125], v246 offset:256
	ds_read_b128 v[126:129], v247 offset:256
	ds_read_b128 v[130:133], v248 offset:256
	s_mov_b32 s41, 0
	v_readlane_b32 s37, v236, s41
	s_cmp_lt_u32 s37, 32
	s_cbranch_scc0 .Lret_wctx_1
	s_lshl_b32 s100, s37, 6
	s_cmp_eq_u32 s37, s9
	s_cbranch_scc1 .Lret_wdiag_2
	s_cmp_lt_u32 s37, s9
	s_cselect_b32 s101, s11, s12
	v_subrev_u32_e32 v170, s100, v203
	v_subrev_u32_e32 v171, s100, v204
	v_subrev_u32_e32 v172, s100, v205
	v_subrev_u32_e32 v173, s100, v206
	v_cvt_f32_i32_e32 v174, v170
	v_cvt_f32_i32_e32 v175, v171
	v_cvt_f32_i32_e32 v176, v172
	v_cvt_f32_i32_e32 v177, v173
	v_mul_f32_e64 v178, s101, |v174|
	v_mul_f32_e64 v179, s101, |v175|
	v_mul_f32_e64 v180, s101, |v176|
	v_mul_f32_e64 v181, s101, |v177|
	v_exp_f32_e32 v166, v178
	v_exp_f32_e32 v167, v179
	v_exp_f32_e32 v168, v180
	v_exp_f32_e32 v169, v181
	s_branch .Lret_wdone_3
.Lret_wdiag_2:
	v_subrev_u32_e32 v170, s100, v203
	v_subrev_u32_e32 v171, s100, v204
	v_subrev_u32_e32 v172, s100, v205
	v_subrev_u32_e32 v173, s100, v206
	v_cvt_f32_i32_e32 v174, v170
	v_cvt_f32_i32_e32 v175, v171
	v_cvt_f32_i32_e32 v176, v172
	v_cvt_f32_i32_e32 v177, v173
	v_cmp_gt_i32_e32 vcc, 0, v170
	s_nop 1
	v_cndmask_b32_e32 v178, v207, v208, vcc
	v_cmp_gt_i32_e32 vcc, 0, v171
	s_nop 1
	v_cndmask_b32_e32 v179, v207, v208, vcc
	v_cmp_gt_i32_e32 vcc, 0, v172
	s_nop 1
	v_cndmask_b32_e32 v180, v207, v208, vcc
	v_cmp_gt_i32_e32 vcc, 0, v173
	s_nop 1
	v_cndmask_b32_e32 v181, v207, v208, vcc
	v_mul_f32_e64 v178, v178, |v174|
	v_mul_f32_e64 v179, v179, |v175|
	v_mul_f32_e64 v180, v180, |v176|
	v_mul_f32_e64 v181, v181, |v177|
	v_exp_f32_e32 v166, v178
	v_exp_f32_e32 v167, v179
	v_exp_f32_e32 v168, v180
	v_exp_f32_e32 v169, v181
	s_branch .Lret_wdone_3
.Lret_wctx_1:
	s_sub_i32 s100, s37, 32
	s_lshl_b32 s100, s100, 6
	s_add_i32 s101, s100, 0x800
	s_sub_i32 s100, s100, 0x100
	v_subrev_u32_e32 v170, s100, v203
	v_sub_u32_e32 v174, s101, v203
	v_subrev_u32_e32 v171, s100, v204
	v_sub_u32_e32 v175, s101, v204
	v_subrev_u32_e32 v172, s100, v205
	v_sub_u32_e32 v176, s101, v205
	v_subrev_u32_e32 v173, s100, v206
	v_sub_u32_e32 v177, s101, v206
	v_cvt_f32_i32_e32 v170, v170
	v_cvt_f32_i32_e32 v174, v174
	v_cvt_f32_i32_e32 v171, v171
	v_cvt_f32_i32_e32 v175, v175
	v_cvt_f32_i32_e32 v172, v172
	v_cvt_f32_i32_e32 v176, v176
	v_cvt_f32_i32_e32 v173, v173
	v_cvt_f32_i32_e32 v177, v177
	v_mul_f32_e32 v170, s11, v170
	v_mul_f32_e32 v174, s12, v174
	v_mul_f32_e32 v171, s11, v171
	v_mul_f32_e32 v175, s12, v175
	v_mul_f32_e32 v172, s11, v172
	v_mul_f32_e32 v176, s12, v176
	v_mul_f32_e32 v173, s11, v173
	v_mul_f32_e32 v177, s12, v177
	v_exp_f32_e32 v170, v170
	v_exp_f32_e32 v174, v174
	v_exp_f32_e32 v171, v171
	v_exp_f32_e32 v175, v175
	v_exp_f32_e32 v172, v172
	v_exp_f32_e32 v176, v176
	v_exp_f32_e32 v173, v173
	v_exp_f32_e32 v177, v177
	s_nop 0
	v_add_f32_e32 v166, v170, v174
	v_add_f32_e32 v167, v171, v175
	v_add_f32_e32 v168, v172, v176
	v_add_f32_e32 v169, v173, v177
.Lret_wdone_3:
	s_waitcnt lgkmcnt(7)
	v_mfma_f32_16x16x32_bf16 v[98:101], v[102:105], v[64:67], 0
	s_waitcnt lgkmcnt(6)
	v_mfma_f32_16x16x32_bf16 v[98:101], v[106:109], v[68:71], v[98:101]
	s_waitcnt lgkmcnt(5)
	v_mfma_f32_16x16x32_bf16 v[98:101], v[110:113], v[72:75], v[98:101]
	s_waitcnt lgkmcnt(4)
	v_mfma_f32_16x16x32_bf16 v[98:101], v[114:117], v[76:79], v[98:101]
	s_waitcnt lgkmcnt(3)
	v_mfma_f32_16x16x32_bf16 v[98:101], v[118:121], v[80:83], v[98:101]
	s_waitcnt lgkmcnt(2)
	v_mfma_f32_16x16x32_bf16 v[98:101], v[122:125], v[84:87], v[98:101]
	s_waitcnt lgkmcnt(1)
	v_mfma_f32_16x16x32_bf16 v[98:101], v[126:129], v[88:91], v[98:101]
	s_waitcnt lgkmcnt(0)
	v_mfma_f32_16x16x32_bf16 v[98:101], v[130:133], v[92:95], v[98:101]
	s_nop 7
	s_nop 1
	v_mul_f32_e32 v170, v98, v166
	v_mul_f32_e32 v171, v99, v167
	v_mul_f32_e32 v172, v100, v168
	v_mul_f32_e32 v173, v101, v169
	v_cvt_pk_bf16_f32 v174, v170, v171
	v_cvt_pk_bf16_f32 v175, v172, v173
	ds_write_b64 v188, v[174:175] offset:0
	s_waitcnt vmcnt(10)
	ds_read_b64_tr_b16 v[150:151], v183 offset:0
	ds_read_b64_tr_b16 v[152:153], v183 offset:512
	ds_read_b64_tr_b16 v[154:155], v184 offset:0
	ds_read_b64_tr_b16 v[156:157], v184 offset:512
	ds_read_b64_tr_b16 v[158:159], v185 offset:0
	ds_read_b64_tr_b16 v[160:161], v185 offset:512
	ds_read_b64_tr_b16 v[162:163], v186 offset:0
	ds_read_b64_tr_b16 v[164:165], v186 offset:512
	s_mov_b32 s41, 0
	v_readlane_b32 s37, v236, s41
	s_cmp_lt_u32 s37, 32
	s_cbranch_scc0 .Lret_wctx_4
	s_lshl_b32 s100, s37, 6
	s_add_i32 s100, s100, 32
	s_cmp_eq_u32 s37, s9
	s_cbranch_scc1 .Lret_wdiag_5
	s_cmp_lt_u32 s37, s9
	s_cselect_b32 s101, s11, s12
	v_subrev_u32_e32 v170, s100, v203
	v_subrev_u32_e32 v171, s100, v204
	v_subrev_u32_e32 v172, s100, v205
	v_subrev_u32_e32 v173, s100, v206
	v_cvt_f32_i32_e32 v174, v170
	v_cvt_f32_i32_e32 v175, v171
	v_cvt_f32_i32_e32 v176, v172
	v_cvt_f32_i32_e32 v177, v173
	v_mul_f32_e64 v178, s101, |v174|
	v_mul_f32_e64 v179, s101, |v175|
	v_mul_f32_e64 v180, s101, |v176|
	v_mul_f32_e64 v181, s101, |v177|
	v_exp_f32_e32 v242, v178
	v_exp_f32_e32 v243, v179
	v_exp_f32_e32 v244, v180
	v_exp_f32_e32 v245, v181
	s_branch .Lret_wdone_6
.Lret_wdiag_5:
	v_subrev_u32_e32 v170, s100, v203
	v_subrev_u32_e32 v171, s100, v204
	v_subrev_u32_e32 v172, s100, v205
	v_subrev_u32_e32 v173, s100, v206
	v_cvt_f32_i32_e32 v174, v170
	v_cvt_f32_i32_e32 v175, v171
	v_cvt_f32_i32_e32 v176, v172
	v_cvt_f32_i32_e32 v177, v173
	v_cmp_gt_i32_e32 vcc, 0, v170
	s_nop 1
	v_cndmask_b32_e32 v178, v207, v208, vcc
	v_cmp_gt_i32_e32 vcc, 0, v171
	s_nop 1
	v_cndmask_b32_e32 v179, v207, v208, vcc
	v_cmp_gt_i32_e32 vcc, 0, v172
	s_nop 1
	v_cndmask_b32_e32 v180, v207, v208, vcc
	v_cmp_gt_i32_e32 vcc, 0, v173
	s_nop 1
	v_cndmask_b32_e32 v181, v207, v208, vcc
	v_mul_f32_e64 v178, v178, |v174|
	v_mul_f32_e64 v179, v179, |v175|
	v_mul_f32_e64 v180, v180, |v176|
	v_mul_f32_e64 v181, v181, |v177|
	v_exp_f32_e32 v242, v178
	v_exp_f32_e32 v243, v179
	v_exp_f32_e32 v244, v180
	v_exp_f32_e32 v245, v181
	s_branch .Lret_wdone_6
; #define RET_BAR() do { asm volatile("s_waitcnt lgkmcnt(0)" ::: "memory"); __builtin_amdgcn_s_barrier(); asm volatile("" ::: "memory"); } while (0)
; #define RET_LOADV(t) do { RET_KV(t) const char* vb_ = kb_ + (1024 + h * 256) * 2; const unsigned lo_ = (unsigned)(tid >> 6) * kp_ + (unsigned)(tid & 63) * 16u; \
;         _Pragma("unroll") for (int i_ = 0; i_ < 8; ++i_) vr[i_] = *(const u32x4*)(vb_ + (size_t)(8u * i_) * kp_ + lo_); } while (0)
; #define RET_STOREV() do { _Pragma("unroll") for (int i_ = 0; i_ < 8; ++i_) *(LAS u32x4*)(Vs + ((tid >> 6) + 8 * i_) * 1040 + (tid & 63) * 16) = vr[i_]; } while (0)
; __device__ __forceinline__ void ret_unit(ldsp lds, bf16_t* R, const bf16_t* RC, int b, int h, int qblk, float lgf2, float lgb2, const int tid_in) {
;     ...
;     for (int t = 0; t < 36; ++t) {
;         int tl_ = tid_outer; asm volatile("" : "+v"(tl_));
;         const int tid = tl_, lane = tid & 63, l15 = lane & 15, lg = lane >> 4;
;         if (wid < 4) { RET_PV(t); if (t + 1 < 36) RET_S(t + 1, TI(t + 1)); }
;         else { if (t + 1 < 36) RET_S(t + 1, TI(t + 1)); RET_PV(t); }
;         RET_BAR();
;         asm volatile("s_waitcnt vmcnt(0)" ::: "memory");
;         if (t + 1 < 36) RET_STOREV();
;         if (t + 2 < 36) RET_LOADV(TI(t + 2));
;         if (t + 3 < 36) RET_DMAK(TI(t + 3), (t + 1) & 1);
.Lret_wctx_4:
	s_sub_i32 s100, s37, 32
	s_lshl_b32 s100, s100, 6
	s_add_i32 s100, s100, 32
	s_add_i32 s101, s100, 0x800
	s_sub_i32 s100, s100, 0x100
	v_subrev_u32_e32 v170, s100, v203
	v_sub_u32_e32 v174, s101, v203
	v_subrev_u32_e32 v171, s100, v204
	v_sub_u32_e32 v175, s101, v204
	v_subrev_u32_e32 v172, s100, v205
	v_sub_u32_e32 v176, s101, v205
	v_subrev_u32_e32 v173, s100, v206
	v_sub_u32_e32 v177, s101, v206
	v_cvt_f32_i32_e32 v170, v170
	v_cvt_f32_i32_e32 v174, v174
	v_cvt_f32_i32_e32 v171, v171
	v_cvt_f32_i32_e32 v175, v175
	v_cvt_f32_i32_e32 v172, v172
	v_cvt_f32_i32_e32 v176, v176
	v_cvt_f32_i32_e32 v173, v173
	v_cvt_f32_i32_e32 v177, v177
	v_mul_f32_e32 v170, s11, v170
	v_mul_f32_e32 v174, s12, v174
	v_mul_f32_e32 v171, s11, v171
	v_mul_f32_e32 v175, s12, v175
	v_mul_f32_e32 v172, s11, v172
	v_mul_f32_e32 v176, s12, v176
	v_mul_f32_e32 v173, s11, v173
	v_mul_f32_e32 v177, s12, v177
	v_exp_f32_e32 v170, v170
	v_exp_f32_e32 v174, v174
	v_exp_f32_e32 v171, v171
	v_exp_f32_e32 v175, v175
	v_exp_f32_e32 v172, v172
	v_exp_f32_e32 v176, v176
	v_exp_f32_e32 v173, v173
	v_exp_f32_e32 v177, v177
	s_nop 0
	v_add_f32_e32 v242, v170, v174
	v_add_f32_e32 v243, v171, v175
	v_add_f32_e32 v244, v172, v176
	v_add_f32_e32 v245, v173, v177
.Lret_wdone_6:
	s_waitcnt lgkmcnt(8)
	s_barrier
	s_mov_b32 s27, 0
.Lret_loop:
	s_cmp_eq_u32 s38, 0
	s_cbranch_scc0 .Lret_regY_7
	ds_read_b128 v[102:105], v182 offset:16384
	ds_read_b128 v[106:109], v246 offset:16384
	ds_read_b128 v[110:113], v247 offset:16384
	ds_read_b128 v[114:117], v248 offset:16384
	ds_read_b128 v[118:121], v182 offset:16640
	ds_read_b128 v[122:125], v246 offset:16640
	ds_read_b128 v[126:129], v247 offset:16640
	ds_read_b128 v[130:133], v248 offset:16640
	ds_read_b128 v[134:137], v187 offset:0
	ds_read_b128 v[138:141], v187 offset:1280
	ds_read_b128 v[142:145], v187 offset:2560
	ds_read_b128 v[146:149], v187 offset:3840
	s_add_i32 s41, s27, 1
	v_readlane_b32 s42, v240, s41
	v_readlane_b32 s43, v241, s41
	v_readlane_b32 s4, v237, s41
	s_mov_b32 s5, s4
	s_nop 0
	v_cndmask_b32_e64 v230, v191, v189, s[4:5]
	v_cndmask_b32_e64 v231, v192, v190, s[4:5]
	v_cndmask_b32_e64 v232, v198, v193, s[4:5]
	v_cndmask_b32_e64 v233, v199, v194, s[4:5]
	v_cndmask_b32_e64 v234, v200, v195, s[4:5]
	v_cndmask_b32_e64 v235, v202, v197, s[4:5]
	s_add_i32 m0, s54, 0
	s_nop 0
	global_load_lds_dwordx4 v230, s[42:43]
	s_add_i32 m0, s54, 1024
	s_nop 0
	global_load_lds_dwordx4 v231, s[42:43]
	s_waitcnt lgkmcnt(11)
	v_mfma_f32_16x16x32_bf16 v[98:101], v[102:105], v[64:67], 0
	s_waitcnt lgkmcnt(10)
	s_add_i32 m0, s55, 0
	v_mfma_f32_16x16x32_bf16 v[98:101], v[106:109], v[68:71], v[98:101]
	global_load_lds_dwordx4 v232, s[42:43]
	s_waitcnt lgkmcnt(9)
	s_add_i32 m0, s55, 1024
	v_mfma_f32_16x16x32_bf16 v[98:101], v[110:113], v[72:75], v[98:101]
	global_load_lds_dwordx4 v233, s[42:43]
	s_waitcnt lgkmcnt(8)
	s_add_i32 m0, s55, 2048
	v_mfma_f32_16x16x32_bf16 v[98:101], v[114:117], v[76:79], v[98:101]
	global_load_lds_dwordx4 v234, s[42:43]
	s_waitcnt lgkmcnt(7)
	s_add_i32 m0, s55, 3072
	v_mfma_f32_16x16x32_bf16 v[98:101], v[118:121], v[80:83], v[98:101]
	global_load_lds_dwordx4 v235, s[42:43]
	s_waitcnt lgkmcnt(6)
	v_mfma_f32_16x16x32_bf16 v[98:101], v[122:125], v[84:87], v[98:101]
	s_waitcnt lgkmcnt(5)
	v_mfma_f32_16x16x32_bf16 v[98:101], v[126:129], v[88:91], v[98:101]
	s_waitcnt lgkmcnt(4)
	v_mfma_f32_16x16x32_bf16 v[98:101], v[130:133], v[92:95], v[98:101]
	s_waitcnt lgkmcnt(0)
	v_mfma_f32_16x16x32_bf16 v[0:3], v[150:153], v[134:137], v[0:3]
	v_mfma_f32_16x16x32_bf16 v[16:19], v[154:157], v[134:137], v[16:19]
	v_mfma_f32_16x16x32_bf16 v[32:35], v[158:161], v[134:137], v[32:35]
	v_mfma_f32_16x16x32_bf16 v[48:51], v[162:165], v[134:137], v[48:51]
	v_mfma_f32_16x16x32_bf16 v[4:7], v[150:153], v[138:141], v[4:7]
	v_mfma_f32_16x16x32_bf16 v[20:23], v[154:157], v[138:141], v[20:23]
	v_mfma_f32_16x16x32_bf16 v[36:39], v[158:161], v[138:141], v[36:39]
	v_mfma_f32_16x16x32_bf16 v[52:55], v[162:165], v[138:141], v[52:55]
	v_mfma_f32_16x16x32_bf16 v[8:11], v[150:153], v[142:145], v[8:11]
	v_mfma_f32_16x16x32_bf16 v[24:27], v[154:157], v[142:145], v[24:27]
	v_mfma_f32_16x16x32_bf16 v[40:43], v[158:161], v[142:145], v[40:43]
	v_mfma_f32_16x16x32_bf16 v[56:59], v[162:165], v[142:145], v[56:59]
	v_mfma_f32_16x16x32_bf16 v[12:15], v[150:153], v[146:149], v[12:15]
	v_mfma_f32_16x16x32_bf16 v[28:31], v[154:157], v[146:149], v[28:31]
	v_mfma_f32_16x16x32_bf16 v[44:47], v[158:161], v[146:149], v[44:47]
	v_mfma_f32_16x16x32_bf16 v[60:63], v[162:165], v[146:149], v[60:63]
	v_mul_f32_e32 v170, v98, v242
	v_mul_f32_e32 v171, v99, v243
	v_mul_f32_e32 v172, v100, v244
	v_mul_f32_e32 v173, v101, v245
	v_cvt_pk_bf16_f32 v174, v170, v171
	v_cvt_pk_bf16_f32 v175, v172, v173
	ds_write_b64 v188, v[174:175] offset:5120
	s_waitcnt vmcnt(10)
	ds_read_b64_tr_b16 v[150:151], v183 offset:4096
	ds_read_b64_tr_b16 v[152:153], v183 offset:4608
	ds_read_b64_tr_b16 v[154:155], v184 offset:4096
	ds_read_b64_tr_b16 v[156:157], v184 offset:4608
	ds_read_b64_tr_b16 v[158:159], v185 offset:4096
	ds_read_b64_tr_b16 v[160:161], v185 offset:4608
	ds_read_b64_tr_b16 v[162:163], v186 offset:4096
	ds_read_b64_tr_b16 v[164:165], v186 offset:4608
	s_add_i32 s41, s27, 1
	v_readlane_b32 s37, v236, s41
	s_cmp_lt_u32 s37, 32
	s_cbranch_scc0 .Lret_wctx_9
	s_lshl_b32 s100, s37, 6
	s_cmp_eq_u32 s37, s9
	s_cbranch_scc1 .Lret_wdiag_10
	s_cmp_lt_u32 s37, s9
	s_cselect_b32 s101, s11, s12
	v_subrev_u32_e32 v170, s100, v203
	v_subrev_u32_e32 v171, s100, v204
	v_subrev_u32_e32 v172, s100, v205
	v_subrev_u32_e32 v173, s100, v206
	v_cvt_f32_i32_e32 v174, v170
	v_cvt_f32_i32_e32 v175, v171
	v_cvt_f32_i32_e32 v176, v172
	v_cvt_f32_i32_e32 v177, v173
	v_mul_f32_e64 v178, s101, |v174|
	v_mul_f32_e64 v179, s101, |v175|
	v_mul_f32_e64 v180, s101, |v176|
	v_mul_f32_e64 v181, s101, |v177|
	v_exp_f32_e32 v166, v178
	v_exp_f32_e32 v167, v179
	v_exp_f32_e32 v168, v180
	v_exp_f32_e32 v169, v181
	s_branch .Lret_wdone_11

; #define RET_BAR() do { asm volatile("s_waitcnt lgkmcnt(0)" ::: "memory"); __builtin_amdgcn_s_barrier(); asm volatile("" ::: "memory"); } while (0)
; #define RET_LOADV(t) do { RET_KV(t) const char* vb_ = kb_ + (1024 + h * 256) * 2; const unsigned lo_ = (unsigned)(tid >> 6) * kp_ + (unsigned)(tid & 63) * 16u; \
;         _Pragma("unroll") for (int i_ = 0; i_ < 8; ++i_) vr[i_] = *(const u32x4*)(vb_ + (size_t)(8u * i_) * kp_ + lo_); } while (0)
; #define RET_STOREV() do { _Pragma("unroll") for (int i_ = 0; i_ < 8; ++i_) *(LAS u32x4*)(Vs + ((tid >> 6) + 8 * i_) * 1040 + (tid & 63) * 16) = vr[i_]; } while (0)
; __device__ __forceinline__ void ret_unit(ldsp lds, bf16_t* R, const bf16_t* RC, int b, int h, int qblk, float lgf2, float lgb2, const int tid_in) {
;     ...
;     for (int t = 0; t < 36; ++t) {
;         int tl_ = tid_outer; asm volatile("" : "+v"(tl_));
;         const int tid = tl_, lane = tid & 63, l15 = lane & 15, lg = lane >> 4;
;         if (wid < 4) { RET_PV(t); if (t + 1 < 36) RET_S(t + 1, TI(t + 1)); }
;         else { if (t + 1 < 36) RET_S(t + 1, TI(t + 1)); RET_PV(t); }
;         RET_BAR();
;         asm volatile("s_waitcnt vmcnt(0)" ::: "memory");
;         if (t + 1 < 36) RET_STOREV();
;         if (t + 2 < 36) RET_LOADV(TI(t + 2));
;         if (t + 3 < 36) RET_DMAK(TI(t + 3), (t + 1) & 1);
.Lret_wdone_11:
	s_waitcnt lgkmcnt(8)
	s_branch .Lret_regJ_8
.Lret_regY_7:
	ds_read_b128 v[134:137], v187 offset:0
	ds_read_b128 v[138:141], v187 offset:1280
	ds_read_b128 v[142:145], v187 offset:2560
	ds_read_b128 v[146:149], v187 offset:3840
	ds_read_b128 v[102:105], v182 offset:16384
	ds_read_b128 v[106:109], v246 offset:16384
	ds_read_b128 v[110:113], v247 offset:16384
	ds_read_b128 v[114:117], v248 offset:16384
	ds_read_b128 v[118:121], v182 offset:16640
	ds_read_b128 v[122:125], v246 offset:16640
	ds_read_b128 v[126:129], v247 offset:16640
	ds_read_b128 v[130:133], v248 offset:16640
	s_add_i32 s41, s27, 1
	v_readlane_b32 s42, v240, s41
	v_readlane_b32 s43, v241, s41
	v_readlane_b32 s4, v237, s41
	s_mov_b32 s5, s4
	s_nop 0
	v_cndmask_b32_e64 v230, v191, v189, s[4:5]
	v_cndmask_b32_e64 v231, v192, v190, s[4:5]
	v_cndmask_b32_e64 v232, v198, v193, s[4:5]
	v_cndmask_b32_e64 v233, v199, v194, s[4:5]
	v_cndmask_b32_e64 v234, v200, v195, s[4:5]
	v_cndmask_b32_e64 v235, v202, v197, s[4:5]
	s_add_i32 m0, s54, 0
	s_nop 0
	global_load_lds_dwordx4 v230, s[42:43]
	s_add_i32 m0, s54, 1024
	s_nop 0
	global_load_lds_dwordx4 v231, s[42:43]
	s_waitcnt lgkmcnt(8)
	s_add_i32 m0, s55, 0
	v_mfma_f32_16x16x32_bf16 v[0:3], v[150:153], v[134:137], v[0:3]
	v_mfma_f32_16x16x32_bf16 v[16:19], v[154:157], v[134:137], v[16:19]
	global_load_lds_dwordx4 v232, s[42:43]
	v_mfma_f32_16x16x32_bf16 v[32:35], v[158:161], v[134:137], v[32:35]
	v_mfma_f32_16x16x32_bf16 v[48:51], v[162:165], v[134:137], v[48:51]
	s_add_i32 m0, s55, 1024
	v_mfma_f32_16x16x32_bf16 v[4:7], v[150:153], v[138:141], v[4:7]
	v_mfma_f32_16x16x32_bf16 v[20:23], v[154:157], v[138:141], v[20:23]
	global_load_lds_dwordx4 v233, s[42:43]
	v_mfma_f32_16x16x32_bf16 v[36:39], v[158:161], v[138:141], v[36:39]
	v_mfma_f32_16x16x32_bf16 v[52:55], v[162:165], v[138:141], v[52:55]
	s_add_i32 m0, s55, 2048
	v_mfma_f32_16x16x32_bf16 v[8:11], v[150:153], v[142:145], v[8:11]
	v_mfma_f32_16x16x32_bf16 v[24:27], v[154:157], v[142:145], v[24:27]
	global_load_lds_dwordx4 v234, s[42:43]
	v_mfma_f32_16x16x32_bf16 v[40:43], v[158:161], v[142:145], v[40:43]
	v_mfma_f32_16x16x32_bf16 v[56:59], v[162:165], v[142:145], v[56:59]
	s_add_i32 m0, s55, 3072
	v_mfma_f32_16x16x32_bf16 v[12:15], v[150:153], v[146:149], v[12:15]
	v_mfma_f32_16x16x32_bf16 v[28:31], v[154:157], v[146:149], v[28:31]
	global_load_lds_dwordx4 v235, s[42:43]
	v_mfma_f32_16x16x32_bf16 v[44:47], v[158:161], v[146:149], v[44:47]
	v_mfma_f32_16x16x32_bf16 v[60:63], v[162:165], v[146:149], v[60:63]
	s_waitcnt lgkmcnt(7)
	v_mfma_f32_16x16x32_bf16 v[98:101], v[102:105], v[64:67], 0
	s_waitcnt lgkmcnt(6)
	v_mfma_f32_16x16x32_bf16 v[98:101], v[106:109], v[68:71], v[98:101]
	s_waitcnt lgkmcnt(5)
	v_mfma_f32_16x16x32_bf16 v[98:101], v[110:113], v[72:75], v[98:101]
	s_waitcnt lgkmcnt(4)
	v_mfma_f32_16x16x32_bf16 v[98:101], v[114:117], v[76:79], v[98:101]
	s_waitcnt lgkmcnt(3)
	v_mfma_f32_16x16x32_bf16 v[98:101], v[118:121], v[80:83], v[98:101]
	s_waitcnt lgkmcnt(2)
	v_mfma_f32_16x16x32_bf16 v[98:101], v[122:125], v[84:87], v[98:101]
	s_waitcnt lgkmcnt(1)
	v_mfma_f32_16x16x32_bf16 v[98:101], v[126:129], v[88:91], v[98:101]
	s_waitcnt lgkmcnt(0)
	v_mfma_f32_16x16x32_bf16 v[98:101], v[130:133], v[92:95], v[98:101]
	s_add_i32 s41, s27, 1
	v_readlane_b32 s37, v236, s41
	s_cmp_lt_u32 s37, 32
	s_cbranch_scc0 .Lret_wctx_12
	s_lshl_b32 s100, s37, 6
	s_cmp_eq_u32 s37, s9
	s_cbranch_scc1 .Lret_wdiag_13
	s_cmp_lt_u32 s37, s9
	s_cselect_b32 s101, s11, s12
	v_subrev_u32_e32 v170, s100, v203
	v_subrev_u32_e32 v171, s100, v204
	v_subrev_u32_e32 v172, s100, v205
	v_subrev_u32_e32 v173, s100, v206
	v_cvt_f32_i32_e32 v174, v170
	v_cvt_f32_i32_e32 v175, v171
	v_cvt_f32_i32_e32 v176, v172
	v_cvt_f32_i32_e32 v177, v173
	v_mul_f32_e64 v178, s101, |v174|
	v_mul_f32_e64 v179, s101, |v175|
	v_mul_f32_e64 v180, s101, |v176|
	v_mul_f32_e64 v181, s101, |v177|
	v_exp_f32_e32 v166, v178
	v_exp_f32_e32 v167, v179
	v_exp_f32_e32 v168, v180
	v_exp_f32_e32 v169, v181
	s_branch .Lret_wdone_14

; #define RET_BAR() do { asm volatile("s_waitcnt lgkmcnt(0)" ::: "memory"); __builtin_amdgcn_s_barrier(); asm volatile("" ::: "memory"); } while (0)
; #define RET_LOADV(t) do { RET_KV(t) const char* vb_ = kb_ + (1024 + h * 256) * 2; const unsigned lo_ = (unsigned)(tid >> 6) * kp_ + (unsigned)(tid & 63) * 16u; \
;         _Pragma("unroll") for (int i_ = 0; i_ < 8; ++i_) vr[i_] = *(const u32x4*)(vb_ + (size_t)(8u * i_) * kp_ + lo_); } while (0)
; #define RET_STOREV() do { _Pragma("unroll") for (int i_ = 0; i_ < 8; ++i_) *(LAS u32x4*)(Vs + ((tid >> 6) + 8 * i_) * 1040 + (tid & 63) * 16) = vr[i_]; } while (0)
; __device__ __forceinline__ void ret_unit(ldsp lds, bf16_t* R, const bf16_t* RC, int b, int h, int qblk, float lgf2, float lgb2, const int tid_in) {
;     ...
;     for (int t = 0; t < 36; ++t) {
;         int tl_ = tid_outer; asm volatile("" : "+v"(tl_));
;         const int tid = tl_, lane = tid & 63, l15 = lane & 15, lg = lane >> 4;
;         if (wid < 4) { RET_PV(t); if (t + 1 < 36) RET_S(t + 1, TI(t + 1)); }
;         else { if (t + 1 < 36) RET_S(t + 1, TI(t + 1)); RET_PV(t); }
;         RET_BAR();
;         asm volatile("s_waitcnt vmcnt(0)" ::: "memory");
;         if (t + 1 < 36) RET_STOREV();
;         if (t + 2 < 36) RET_LOADV(TI(t + 2));
;         if (t + 3 < 36) RET_DMAK(TI(t + 3), (t + 1) & 1);
.Lret_wdone_14:
	v_mul_f32_e32 v170, v98, v242
	v_mul_f32_e32 v171, v99, v243
	v_mul_f32_e32 v172, v100, v244
	v_mul_f32_e32 v173, v101, v245
	v_cvt_pk_bf16_f32 v174, v170, v171
	v_cvt_pk_bf16_f32 v175, v172, v173
	ds_write_b64 v188, v[174:175] offset:5120
	s_waitcnt vmcnt(10)
	ds_read_b64_tr_b16 v[150:151], v183 offset:4096
	ds_read_b64_tr_b16 v[152:153], v183 offset:4608
	ds_read_b64_tr_b16 v[154:155], v184 offset:4096
	ds_read_b64_tr_b16 v[156:157], v184 offset:4608
	ds_read_b64_tr_b16 v[158:159], v185 offset:4096
	ds_read_b64_tr_b16 v[160:161], v185 offset:4608
	ds_read_b64_tr_b16 v[162:163], v186 offset:4096
	ds_read_b64_tr_b16 v[164:165], v186 offset:4608
	s_waitcnt lgkmcnt(8)
.Lret_regJ_8:
	s_barrier
	s_cmp_eq_u32 s38, 0
	s_cbranch_scc0 .Lret_regY_15
	ds_read_b128 v[102:105], v182 offset:32768
	ds_read_b128 v[106:109], v246 offset:32768
	ds_read_b128 v[110:113], v247 offset:32768
	ds_read_b128 v[114:117], v248 offset:32768
	ds_read_b128 v[118:121], v182 offset:33024
	ds_read_b128 v[122:125], v246 offset:33024
	ds_read_b128 v[126:129], v247 offset:33024
	ds_read_b128 v[130:133], v248 offset:33024
	ds_read_b128 v[134:137], v187 offset:5120
	ds_read_b128 v[138:141], v187 offset:6400
	ds_read_b128 v[142:145], v187 offset:7680
	ds_read_b128 v[146:149], v187 offset:8960
	s_add_i32 s41, s27, 2
	v_readlane_b32 s42, v238, s41
	v_readlane_b32 s43, v239, s41
	v_readlane_b32 s4, v237, s41
	s_mov_b32 s5, s4
	s_nop 0
	v_cndmask_b32_e64 v230, v191, v189, s[4:5]
	v_cndmask_b32_e64 v231, v192, v190, s[4:5]
	v_cndmask_b32_e64 v232, v198, v193, s[4:5]
	v_cndmask_b32_e64 v233, v199, v194, s[4:5]
	v_cndmask_b32_e64 v234, v200, v195, s[4:5]
	v_cndmask_b32_e64 v235, v202, v197, s[4:5]
	s_add_i32 m0, s54, 16384
	s_nop 0
	global_load_lds_dwordx4 v230, s[42:43]
	s_add_i32 m0, s54, 17408
	s_nop 0
	global_load_lds_dwordx4 v231, s[42:43]
	s_waitcnt lgkmcnt(11)
	v_mfma_f32_16x16x32_bf16 v[98:101], v[102:105], v[64:67], 0
	s_waitcnt lgkmcnt(10)
	s_add_i32 m0, s55, 4096
	v_mfma_f32_16x16x32_bf16 v[98:101], v[106:109], v[68:71], v[98:101]
	global_load_lds_dwordx4 v232, s[42:43]
	s_waitcnt lgkmcnt(9)
	s_add_i32 m0, s55, 5120
	v_mfma_f32_16x16x32_bf16 v[98:101], v[110:113], v[72:75], v[98:101]
	global_load_lds_dwordx4 v233, s[42:43]
	s_waitcnt lgkmcnt(8)
	s_add_i32 m0, s55, 6144
	v_mfma_f32_16x16x32_bf16 v[98:101], v[114:117], v[76:79], v[98:101]
	global_load_lds_dwordx4 v234, s[42:43]
	s_waitcnt lgkmcnt(7)
	s_add_i32 m0, s55, 7168
	v_mfma_f32_16x16x32_bf16 v[98:101], v[118:121], v[80:83], v[98:101]
	global_load_lds_dwordx4 v235, s[42:43]
	s_waitcnt lgkmcnt(6)
	v_mfma_f32_16x16x32_bf16 v[98:101], v[122:125], v[84:87], v[98:101]
	s_waitcnt lgkmcnt(5)
	v_mfma_f32_16x16x32_bf16 v[98:101], v[126:129], v[88:91], v[98:101]
	s_waitcnt lgkmcnt(4)
	v_mfma_f32_16x16x32_bf16 v[98:101], v[130:133], v[92:95], v[98:101]
	s_waitcnt lgkmcnt(0)
	v_mfma_f32_16x16x32_bf16 v[0:3], v[150:153], v[134:137], v[0:3]
	v_mfma_f32_16x16x32_bf16 v[16:19], v[154:157], v[134:137], v[16:19]
	v_mfma_f32_16x16x32_bf16 v[32:35], v[158:161], v[134:137], v[32:35]
	v_mfma_f32_16x16x32_bf16 v[48:51], v[162:165], v[134:137], v[48:51]
	v_mfma_f32_16x16x32_bf16 v[4:7], v[150:153], v[138:141], v[4:7]
	v_mfma_f32_16x16x32_bf16 v[20:23], v[154:157], v[138:141], v[20:23]
	v_mfma_f32_16x16x32_bf16 v[36:39], v[158:161], v[138:141], v[36:39]
	v_mfma_f32_16x16x32_bf16 v[52:55], v[162:165], v[138:141], v[52:55]
	v_mfma_f32_16x16x32_bf16 v[8:11], v[150:153], v[142:145], v[8:11]
	v_mfma_f32_16x16x32_bf16 v[24:27], v[154:157], v[142:145], v[24:27]
	v_mfma_f32_16x16x32_bf16 v[40:43], v[158:161], v[142:145], v[40:43]
	v_mfma_f32_16x16x32_bf16 v[56:59], v[162:165], v[142:145], v[56:59]
	v_mfma_f32_16x16x32_bf16 v[12:15], v[150:153], v[146:149], v[12:15]
	v_mfma_f32_16x16x32_bf16 v[28:31], v[154:157], v[146:149], v[28:31]
	v_mfma_f32_16x16x32_bf16 v[44:47], v[158:161], v[146:149], v[44:47]
	v_mfma_f32_16x16x32_bf16 v[60:63], v[162:165], v[146:149], v[60:63]
	v_mul_f32_e32 v170, v98, v166
	v_mul_f32_e32 v171, v99, v167
	v_mul_f32_e32 v172, v100, v168
	v_mul_f32_e32 v173, v101, v169
	v_cvt_pk_bf16_f32 v174, v170, v171
	v_cvt_pk_bf16_f32 v175, v172, v173
	ds_write_b64 v188, v[174:175] offset:0
	s_waitcnt vmcnt(10)
	ds_read_b64_tr_b16 v[150:151], v183 offset:8192
	ds_read_b64_tr_b16 v[152:153], v183 offset:8704
	ds_read_b64_tr_b16 v[154:155], v184 offset:8192
	ds_read_b64_tr_b16 v[156:157], v184 offset:8704
	ds_read_b64_tr_b16 v[158:159], v185 offset:8192
	ds_read_b64_tr_b16 v[160:161], v185 offset:8704
	ds_read_b64_tr_b16 v[162:163], v186 offset:8192
	ds_read_b64_tr_b16 v[164:165], v186 offset:8704
	s_add_i32 s41, s27, 1
	v_readlane_b32 s37, v236, s41
	s_cmp_lt_u32 s37, 32
	s_cbranch_scc0 .Lret_wctx_17
	s_lshl_b32 s100, s37, 6
	s_add_i32 s100, s100, 32
	s_cmp_eq_u32 s37, s9
	s_cbranch_scc1 .Lret_wdiag_18
	s_cmp_lt_u32 s37, s9
	s_cselect_b32 s101, s11, s12
	v_subrev_u32_e32 v170, s100, v203
	v_subrev_u32_e32 v171, s100, v204
	v_subrev_u32_e32 v172, s100, v205
	v_subrev_u32_e32 v173, s100, v206
	v_cvt_f32_i32_e32 v174, v170
	v_cvt_f32_i32_e32 v175, v171
	v_cvt_f32_i32_e32 v176, v172
	v_cvt_f32_i32_e32 v177, v173
	v_mul_f32_e64 v178, s101, |v174|
	v_mul_f32_e64 v179, s101, |v175|
	v_mul_f32_e64 v180, s101, |v176|
	v_mul_f32_e64 v181, s101, |v177|
	v_exp_f32_e32 v242, v178
	v_exp_f32_e32 v243, v179
	v_exp_f32_e32 v244, v180
	v_exp_f32_e32 v245, v181
	s_branch .Lret_wdone_19

; #define RET_BAR() do { asm volatile("s_waitcnt lgkmcnt(0)" ::: "memory"); __builtin_amdgcn_s_barrier(); asm volatile("" ::: "memory"); } while (0)
; #define RET_LOADV(t) do { RET_KV(t) const char* vb_ = kb_ + (1024 + h * 256) * 2; const unsigned lo_ = (unsigned)(tid >> 6) * kp_ + (unsigned)(tid & 63) * 16u; \
;         _Pragma("unroll") for (int i_ = 0; i_ < 8; ++i_) vr[i_] = *(const u32x4*)(vb_ + (size_t)(8u * i_) * kp_ + lo_); } while (0)
; #define RET_STOREV() do { _Pragma("unroll") for (int i_ = 0; i_ < 8; ++i_) *(LAS u32x4*)(Vs + ((tid >> 6) + 8 * i_) * 1040 + (tid & 63) * 16) = vr[i_]; } while (0)
; __device__ __forceinline__ void ret_unit(ldsp lds, bf16_t* R, const bf16_t* RC, int b, int h, int qblk, float lgf2, float lgb2, const int tid_in) {
;     ...
;     for (int t = 0; t < 36; ++t) {
;         int tl_ = tid_outer; asm volatile("" : "+v"(tl_));
;         const int tid = tl_, lane = tid & 63, l15 = lane & 15, lg = lane >> 4;
;         if (wid < 4) { RET_PV(t); if (t + 1 < 36) RET_S(t + 1, TI(t + 1)); }
;         else { if (t + 1 < 36) RET_S(t + 1, TI(t + 1)); RET_PV(t); }
;         RET_BAR();
;         asm volatile("s_waitcnt vmcnt(0)" ::: "memory");
;         if (t + 1 < 36) RET_STOREV();
;         if (t + 2 < 36) RET_LOADV(TI(t + 2));
;         if (t + 3 < 36) RET_DMAK(TI(t + 3), (t + 1) & 1);
.Lret_regY_15:
	ds_read_b128 v[134:137], v187 offset:5120
	ds_read_b128 v[138:141], v187 offset:6400
	ds_read_b128 v[142:145], v187 offset:7680
	ds_read_b128 v[146:149], v187 offset:8960
	ds_read_b128 v[102:105], v182 offset:32768
	ds_read_b128 v[106:109], v246 offset:32768
	ds_read_b128 v[110:113], v247 offset:32768
	ds_read_b128 v[114:117], v248 offset:32768
	ds_read_b128 v[118:121], v182 offset:33024
	ds_read_b128 v[122:125], v246 offset:33024
	ds_read_b128 v[126:129], v247 offset:33024
	ds_read_b128 v[130:133], v248 offset:33024
	s_add_i32 s41, s27, 2
	v_readlane_b32 s42, v238, s41
	v_readlane_b32 s43, v239, s41
	v_readlane_b32 s4, v237, s41
	s_mov_b32 s5, s4
	s_nop 0
	v_cndmask_b32_e64 v230, v191, v189, s[4:5]
	v_cndmask_b32_e64 v231, v192, v190, s[4:5]
	v_cndmask_b32_e64 v232, v198, v193, s[4:5]
	v_cndmask_b32_e64 v233, v199, v194, s[4:5]
	v_cndmask_b32_e64 v234, v200, v195, s[4:5]
	v_cndmask_b32_e64 v235, v202, v197, s[4:5]
	s_add_i32 m0, s54, 16384
	s_nop 0
	global_load_lds_dwordx4 v230, s[42:43]
	s_add_i32 m0, s54, 17408
	s_nop 0
	global_load_lds_dwordx4 v231, s[42:43]
	s_waitcnt lgkmcnt(8)
	s_add_i32 m0, s55, 4096
	v_mfma_f32_16x16x32_bf16 v[0:3], v[150:153], v[134:137], v[0:3]
	v_mfma_f32_16x16x32_bf16 v[16:19], v[154:157], v[134:137], v[16:19]
	global_load_lds_dwordx4 v232, s[42:43]
	v_mfma_f32_16x16x32_bf16 v[32:35], v[158:161], v[134:137], v[32:35]
	v_mfma_f32_16x16x32_bf16 v[48:51], v[162:165], v[134:137], v[48:51]
	s_add_i32 m0, s55, 5120
	v_mfma_f32_16x16x32_bf16 v[4:7], v[150:153], v[138:141], v[4:7]
	v_mfma_f32_16x16x32_bf16 v[20:23], v[154:157], v[138:141], v[20:23]
	global_load_lds_dwordx4 v233, s[42:43]
	v_mfma_f32_16x16x32_bf16 v[36:39], v[158:161], v[138:141], v[36:39]
	v_mfma_f32_16x16x32_bf16 v[52:55], v[162:165], v[138:141], v[52:55]
	s_add_i32 m0, s55, 6144
	v_mfma_f32_16x16x32_bf16 v[8:11], v[150:153], v[142:145], v[8:11]
	v_mfma_f32_16x16x32_bf16 v[24:27], v[154:157], v[142:145], v[24:27]
	global_load_lds_dwordx4 v234, s[42:43]
	v_mfma_f32_16x16x32_bf16 v[40:43], v[158:161], v[142:145], v[40:43]
	v_mfma_f32_16x16x32_bf16 v[56:59], v[162:165], v[142:145], v[56:59]
	s_add_i32 m0, s55, 7168
	v_mfma_f32_16x16x32_bf16 v[12:15], v[150:153], v[146:149], v[12:15]
	v_mfma_f32_16x16x32_bf16 v[28:31], v[154:157], v[146:149], v[28:31]
	global_load_lds_dwordx4 v235, s[42:43]
	v_mfma_f32_16x16x32_bf16 v[44:47], v[158:161], v[146:149], v[44:47]
	v_mfma_f32_16x16x32_bf16 v[60:63], v[162:165], v[146:149], v[60:63]
	s_waitcnt lgkmcnt(7)
	v_mfma_f32_16x16x32_bf16 v[98:101], v[102:105], v[64:67], 0
	s_waitcnt lgkmcnt(6)
	v_mfma_f32_16x16x32_bf16 v[98:101], v[106:109], v[68:71], v[98:101]
	s_waitcnt lgkmcnt(5)
	v_mfma_f32_16x16x32_bf16 v[98:101], v[110:113], v[72:75], v[98:101]
	s_waitcnt lgkmcnt(4)
	v_mfma_f32_16x16x32_bf16 v[98:101], v[114:117], v[76:79], v[98:101]
	s_waitcnt lgkmcnt(3)
	v_mfma_f32_16x16x32_bf16 v[98:101], v[118:121], v[80:83], v[98:101]
	s_waitcnt lgkmcnt(2)
	v_mfma_f32_16x16x32_bf16 v[98:101], v[122:125], v[84:87], v[98:101]
	s_waitcnt lgkmcnt(1)
	v_mfma_f32_16x16x32_bf16 v[98:101], v[126:129], v[88:91], v[98:101]
	s_waitcnt lgkmcnt(0)
	v_mfma_f32_16x16x32_bf16 v[98:101], v[130:133], v[92:95], v[98:101]
	s_add_i32 s41, s27, 1
	v_readlane_b32 s37, v236, s41
	s_cmp_lt_u32 s37, 32
	s_cbranch_scc0 .Lret_wctx_20
	s_lshl_b32 s100, s37, 6
	s_add_i32 s100, s100, 32
	s_cmp_eq_u32 s37, s9
	s_cbranch_scc1 .Lret_wdiag_21
	s_cmp_lt_u32 s37, s9
	s_cselect_b32 s101, s11, s12
	v_subrev_u32_e32 v170, s100, v203
	v_subrev_u32_e32 v171, s100, v204
	v_subrev_u32_e32 v172, s100, v205
	v_subrev_u32_e32 v173, s100, v206
	v_cvt_f32_i32_e32 v174, v170
	v_cvt_f32_i32_e32 v175, v171
	v_cvt_f32_i32_e32 v176, v172
	v_cvt_f32_i32_e32 v177, v173
	v_mul_f32_e64 v178, s101, |v174|
	v_mul_f32_e64 v179, s101, |v175|
	v_mul_f32_e64 v180, s101, |v176|
	v_mul_f32_e64 v181, s101, |v177|
	v_exp_f32_e32 v242, v178
	v_exp_f32_e32 v243, v179
	v_exp_f32_e32 v244, v180
	v_exp_f32_e32 v245, v181
	s_branch .Lret_wdone_22

; #define RET_BAR() do { asm volatile("s_waitcnt lgkmcnt(0)" ::: "memory"); __builtin_amdgcn_s_barrier(); asm volatile("" ::: "memory"); } while (0)
; #define RET_LOADV(t) do { RET_KV(t) const char* vb_ = kb_ + (1024 + h * 256) * 2; const unsigned lo_ = (unsigned)(tid >> 6) * kp_ + (unsigned)(tid & 63) * 16u; \
;         _Pragma("unroll") for (int i_ = 0; i_ < 8; ++i_) vr[i_] = *(const u32x4*)(vb_ + (size_t)(8u * i_) * kp_ + lo_); } while (0)
; #define RET_STOREV() do { _Pragma("unroll") for (int i_ = 0; i_ < 8; ++i_) *(LAS u32x4*)(Vs + ((tid >> 6) + 8 * i_) * 1040 + (tid & 63) * 16) = vr[i_]; } while (0)
; __device__ __forceinline__ void ret_unit(ldsp lds, bf16_t* R, const bf16_t* RC, int b, int h, int qblk, float lgf2, float lgb2, const int tid_in) {
;     ...
;     for (int t = 0; t < 36; ++t) {
;         int tl_ = tid_outer; asm volatile("" : "+v"(tl_));
;         const int tid = tl_, lane = tid & 63, l15 = lane & 15, lg = lane >> 4;
;         if (wid < 4) { RET_PV(t); if (t + 1 < 36) RET_S(t + 1, TI(t + 1)); }
;         else { if (t + 1 < 36) RET_S(t + 1, TI(t + 1)); RET_PV(t); }
;         RET_BAR();
;         asm volatile("s_waitcnt vmcnt(0)" ::: "memory");
;         if (t + 1 < 36) RET_STOREV();
;         if (t + 2 < 36) RET_LOADV(TI(t + 2));
;         if (t + 3 < 36) RET_DMAK(TI(t + 3), (t + 1) & 1);
.Lret_wdone_22:
	v_mul_f32_e32 v170, v98, v166
	v_mul_f32_e32 v171, v99, v167
	v_mul_f32_e32 v172, v100, v168
	v_mul_f32_e32 v173, v101, v169
	v_cvt_pk_bf16_f32 v174, v170, v171
	v_cvt_pk_bf16_f32 v175, v172, v173
	ds_write_b64 v188, v[174:175] offset:0
	s_waitcnt vmcnt(10)
	ds_read_b64_tr_b16 v[150:151], v183 offset:8192
	ds_read_b64_tr_b16 v[152:153], v183 offset:8704
	ds_read_b64_tr_b16 v[154:155], v184 offset:8192
	ds_read_b64_tr_b16 v[156:157], v184 offset:8704
	ds_read_b64_tr_b16 v[158:159], v185 offset:8192
	ds_read_b64_tr_b16 v[160:161], v185 offset:8704
	ds_read_b64_tr_b16 v[162:163], v186 offset:8192
	ds_read_b64_tr_b16 v[164:165], v186 offset:8704
	s_waitcnt lgkmcnt(8)
.Lret_regJ_16:
	s_barrier
	s_cmp_eq_u32 s38, 0
	s_cbranch_scc0 .Lret_regY_23
	ds_read_b128 v[102:105], v182 offset:0
	ds_read_b128 v[106:109], v246 offset:0
	ds_read_b128 v[110:113], v247 offset:0
	ds_read_b128 v[114:117], v248 offset:0
	ds_read_b128 v[118:121], v182 offset:256
	ds_read_b128 v[122:125], v246 offset:256
	ds_read_b128 v[126:129], v247 offset:256
	ds_read_b128 v[130:133], v248 offset:256
	ds_read_b128 v[134:137], v187 offset:0
	ds_read_b128 v[138:141], v187 offset:1280
	ds_read_b128 v[142:145], v187 offset:2560
	ds_read_b128 v[146:149], v187 offset:3840
	s_add_i32 s41, s27, 2
	v_readlane_b32 s42, v240, s41
	v_readlane_b32 s43, v241, s41
	v_readlane_b32 s4, v237, s41
	s_mov_b32 s5, s4
	s_nop 0
	v_cndmask_b32_e64 v230, v191, v189, s[4:5]
	v_cndmask_b32_e64 v231, v192, v190, s[4:5]
	v_cndmask_b32_e64 v232, v198, v193, s[4:5]
	v_cndmask_b32_e64 v233, v199, v194, s[4:5]
	v_cndmask_b32_e64 v234, v200, v195, s[4:5]
	v_cndmask_b32_e64 v235, v202, v197, s[4:5]
	s_add_i32 m0, s54, 32768
	s_nop 0
	global_load_lds_dwordx4 v230, s[42:43]
	s_add_i32 m0, s54, 33792
	s_nop 0
	global_load_lds_dwordx4 v231, s[42:43]
	s_waitcnt lgkmcnt(11)
	v_mfma_f32_16x16x32_bf16 v[98:101], v[102:105], v[64:67], 0
	s_waitcnt lgkmcnt(10)
	s_add_i32 m0, s55, 8192
	v_mfma_f32_16x16x32_bf16 v[98:101], v[106:109], v[68:71], v[98:101]
	global_load_lds_dwordx4 v232, s[42:43]
	s_waitcnt lgkmcnt(9)
	s_add_i32 m0, s55, 9216
	v_mfma_f32_16x16x32_bf16 v[98:101], v[110:113], v[72:75], v[98:101]
	global_load_lds_dwordx4 v233, s[42:43]
	s_waitcnt lgkmcnt(8)
	s_add_i32 m0, s55, 10240
	v_mfma_f32_16x16x32_bf16 v[98:101], v[114:117], v[76:79], v[98:101]
	global_load_lds_dwordx4 v234, s[42:43]
	s_waitcnt lgkmcnt(7)
	s_add_i32 m0, s55, 11264
	v_mfma_f32_16x16x32_bf16 v[98:101], v[118:121], v[80:83], v[98:101]
	global_load_lds_dwordx4 v235, s[42:43]
	s_waitcnt lgkmcnt(6)
	v_mfma_f32_16x16x32_bf16 v[98:101], v[122:125], v[84:87], v[98:101]
	s_waitcnt lgkmcnt(5)
	v_mfma_f32_16x16x32_bf16 v[98:101], v[126:129], v[88:91], v[98:101]
	s_waitcnt lgkmcnt(4)
	v_mfma_f32_16x16x32_bf16 v[98:101], v[130:133], v[92:95], v[98:101]
	s_waitcnt lgkmcnt(0)
	v_mfma_f32_16x16x32_bf16 v[0:3], v[150:153], v[134:137], v[0:3]
	v_mfma_f32_16x16x32_bf16 v[16:19], v[154:157], v[134:137], v[16:19]
	v_mfma_f32_16x16x32_bf16 v[32:35], v[158:161], v[134:137], v[32:35]
	v_mfma_f32_16x16x32_bf16 v[48:51], v[162:165], v[134:137], v[48:51]
	v_mfma_f32_16x16x32_bf16 v[4:7], v[150:153], v[138:141], v[4:7]
	v_mfma_f32_16x16x32_bf16 v[20:23], v[154:157], v[138:141], v[20:23]
	v_mfma_f32_16x16x32_bf16 v[36:39], v[158:161], v[138:141], v[36:39]
	v_mfma_f32_16x16x32_bf16 v[52:55], v[162:165], v[138:141], v[52:55]
	v_mfma_f32_16x16x32_bf16 v[8:11], v[150:153], v[142:145], v[8:11]
	v_mfma_f32_16x16x32_bf16 v[24:27], v[154:157], v[142:145], v[24:27]
	v_mfma_f32_16x16x32_bf16 v[40:43], v[158:161], v[142:145], v[40:43]
	v_mfma_f32_16x16x32_bf16 v[56:59], v[162:165], v[142:145], v[56:59]
	v_mfma_f32_16x16x32_bf16 v[12:15], v[150:153], v[146:149], v[12:15]
	v_mfma_f32_16x16x32_bf16 v[28:31], v[154:157], v[146:149], v[28:31]
	v_mfma_f32_16x16x32_bf16 v[44:47], v[158:161], v[146:149], v[44:47]
	v_mfma_f32_16x16x32_bf16 v[60:63], v[162:165], v[146:149], v[60:63]
	v_mul_f32_e32 v170, v98, v242
	v_mul_f32_e32 v171, v99, v243
	v_mul_f32_e32 v172, v100, v244
	v_mul_f32_e32 v173, v101, v245
	v_cvt_pk_bf16_f32 v174, v170, v171
	v_cvt_pk_bf16_f32 v175, v172, v173
	ds_write_b64 v188, v[174:175] offset:5120
	s_waitcnt vmcnt(10)
	ds_read_b64_tr_b16 v[150:151], v183 offset:0
	ds_read_b64_tr_b16 v[152:153], v183 offset:512
	ds_read_b64_tr_b16 v[154:155], v184 offset:0
	ds_read_b64_tr_b16 v[156:157], v184 offset:512
	ds_read_b64_tr_b16 v[158:159], v185 offset:0
	ds_read_b64_tr_b16 v[160:161], v185 offset:512
	ds_read_b64_tr_b16 v[162:163], v186 offset:0
	ds_read_b64_tr_b16 v[164:165], v186 offset:512
	s_add_i32 s41, s27, 2
	v_readlane_b32 s37, v236, s41
	s_cmp_lt_u32 s37, 32
	s_cbranch_scc0 .Lret_wctx_25
	s_lshl_b32 s100, s37, 6
	s_cmp_eq_u32 s37, s9
	s_cbranch_scc1 .Lret_wdiag_26
	s_cmp_lt_u32 s37, s9
	s_cselect_b32 s101, s11, s12
	v_subrev_u32_e32 v170, s100, v203
	v_subrev_u32_e32 v171, s100, v204
	v_subrev_u32_e32 v172, s100, v205
	v_subrev_u32_e32 v173, s100, v206
	v_cvt_f32_i32_e32 v174, v170
	v_cvt_f32_i32_e32 v175, v171
	v_cvt_f32_i32_e32 v176, v172
	v_cvt_f32_i32_e32 v177, v173
	v_mul_f32_e64 v178, s101, |v174|
	v_mul_f32_e64 v179, s101, |v175|
	v_mul_f32_e64 v180, s101, |v176|
	v_mul_f32_e64 v181, s101, |v177|
	v_exp_f32_e32 v166, v178
	v_exp_f32_e32 v167, v179
	v_exp_f32_e32 v168, v180
	v_exp_f32_e32 v169, v181
	s_branch .Lret_wdone_27

; #define RET_BAR() do { asm volatile("s_waitcnt lgkmcnt(0)" ::: "memory"); __builtin_amdgcn_s_barrier(); asm volatile("" ::: "memory"); } while (0)
; #define RET_LOADV(t) do { RET_KV(t) const char* vb_ = kb_ + (1024 + h * 256) * 2; const unsigned lo_ = (unsigned)(tid >> 6) * kp_ + (unsigned)(tid & 63) * 16u; \
;         _Pragma("unroll") for (int i_ = 0; i_ < 8; ++i_) vr[i_] = *(const u32x4*)(vb_ + (size_t)(8u * i_) * kp_ + lo_); } while (0)
; #define RET_STOREV() do { _Pragma("unroll") for (int i_ = 0; i_ < 8; ++i_) *(LAS u32x4*)(Vs + ((tid >> 6) + 8 * i_) * 1040 + (tid & 63) * 16) = vr[i_]; } while (0)
; __device__ __forceinline__ void ret_unit(ldsp lds, bf16_t* R, const bf16_t* RC, int b, int h, int qblk, float lgf2, float lgb2, const int tid_in) {
;     ...
;     for (int t = 0; t < 36; ++t) {
;         int tl_ = tid_outer; asm volatile("" : "+v"(tl_));
;         const int tid = tl_, lane = tid & 63, l15 = lane & 15, lg = lane >> 4;
;         if (wid < 4) { RET_PV(t); if (t + 1 < 36) RET_S(t + 1, TI(t + 1)); }
;         else { if (t + 1 < 36) RET_S(t + 1, TI(t + 1)); RET_PV(t); }
;         RET_BAR();
;         asm volatile("s_waitcnt vmcnt(0)" ::: "memory");
;         if (t + 1 < 36) RET_STOREV();
;         if (t + 2 < 36) RET_LOADV(TI(t + 2));
;         if (t + 3 < 36) RET_DMAK(TI(t + 3), (t + 1) & 1);
.Lret_regY_23:
	ds_read_b128 v[134:137], v187 offset:0
	ds_read_b128 v[138:141], v187 offset:1280
	ds_read_b128 v[142:145], v187 offset:2560
	ds_read_b128 v[146:149], v187 offset:3840
	ds_read_b128 v[102:105], v182 offset:0
	ds_read_b128 v[106:109], v246 offset:0
	ds_read_b128 v[110:113], v247 offset:0
	ds_read_b128 v[114:117], v248 offset:0
	ds_read_b128 v[118:121], v182 offset:256
	ds_read_b128 v[122:125], v246 offset:256
	ds_read_b128 v[126:129], v247 offset:256
	ds_read_b128 v[130:133], v248 offset:256
	s_add_i32 s41, s27, 2
	v_readlane_b32 s42, v240, s41
	v_readlane_b32 s43, v241, s41
	v_readlane_b32 s4, v237, s41
	s_mov_b32 s5, s4
	s_nop 0
	v_cndmask_b32_e64 v230, v191, v189, s[4:5]
	v_cndmask_b32_e64 v231, v192, v190, s[4:5]
	v_cndmask_b32_e64 v232, v198, v193, s[4:5]
	v_cndmask_b32_e64 v233, v199, v194, s[4:5]
	v_cndmask_b32_e64 v234, v200, v195, s[4:5]
	v_cndmask_b32_e64 v235, v202, v197, s[4:5]
	s_add_i32 m0, s54, 32768
	s_nop 0
	global_load_lds_dwordx4 v230, s[42:43]
	s_add_i32 m0, s54, 33792
	s_nop 0
	global_load_lds_dwordx4 v231, s[42:43]
	s_waitcnt lgkmcnt(8)
	s_add_i32 m0, s55, 8192
	v_mfma_f32_16x16x32_bf16 v[0:3], v[150:153], v[134:137], v[0:3]
	v_mfma_f32_16x16x32_bf16 v[16:19], v[154:157], v[134:137], v[16:19]
	global_load_lds_dwordx4 v232, s[42:43]
	v_mfma_f32_16x16x32_bf16 v[32:35], v[158:161], v[134:137], v[32:35]
	v_mfma_f32_16x16x32_bf16 v[48:51], v[162:165], v[134:137], v[48:51]
	s_add_i32 m0, s55, 9216
	v_mfma_f32_16x16x32_bf16 v[4:7], v[150:153], v[138:141], v[4:7]
	v_mfma_f32_16x16x32_bf16 v[20:23], v[154:157], v[138:141], v[20:23]
	global_load_lds_dwordx4 v233, s[42:43]
	v_mfma_f32_16x16x32_bf16 v[36:39], v[158:161], v[138:141], v[36:39]
	v_mfma_f32_16x16x32_bf16 v[52:55], v[162:165], v[138:141], v[52:55]
	s_add_i32 m0, s55, 10240
	v_mfma_f32_16x16x32_bf16 v[8:11], v[150:153], v[142:145], v[8:11]
	v_mfma_f32_16x16x32_bf16 v[24:27], v[154:157], v[142:145], v[24:27]
	global_load_lds_dwordx4 v234, s[42:43]
	v_mfma_f32_16x16x32_bf16 v[40:43], v[158:161], v[142:145], v[40:43]
	v_mfma_f32_16x16x32_bf16 v[56:59], v[162:165], v[142:145], v[56:59]
	s_add_i32 m0, s55, 11264
	v_mfma_f32_16x16x32_bf16 v[12:15], v[150:153], v[146:149], v[12:15]
	v_mfma_f32_16x16x32_bf16 v[28:31], v[154:157], v[146:149], v[28:31]
	global_load_lds_dwordx4 v235, s[42:43]
	v_mfma_f32_16x16x32_bf16 v[44:47], v[158:161], v[146:149], v[44:47]
	v_mfma_f32_16x16x32_bf16 v[60:63], v[162:165], v[146:149], v[60:63]
	s_waitcnt lgkmcnt(7)
	v_mfma_f32_16x16x32_bf16 v[98:101], v[102:105], v[64:67], 0
	s_waitcnt lgkmcnt(6)
	v_mfma_f32_16x16x32_bf16 v[98:101], v[106:109], v[68:71], v[98:101]
	s_waitcnt lgkmcnt(5)
	v_mfma_f32_16x16x32_bf16 v[98:101], v[110:113], v[72:75], v[98:101]
	s_waitcnt lgkmcnt(4)
	v_mfma_f32_16x16x32_bf16 v[98:101], v[114:117], v[76:79], v[98:101]
	s_waitcnt lgkmcnt(3)
	v_mfma_f32_16x16x32_bf16 v[98:101], v[118:121], v[80:83], v[98:101]
	s_waitcnt lgkmcnt(2)
	v_mfma_f32_16x16x32_bf16 v[98:101], v[122:125], v[84:87], v[98:101]
	s_waitcnt lgkmcnt(1)
	v_mfma_f32_16x16x32_bf16 v[98:101], v[126:129], v[88:91], v[98:101]
	s_waitcnt lgkmcnt(0)
	v_mfma_f32_16x16x32_bf16 v[98:101], v[130:133], v[92:95], v[98:101]
	s_add_i32 s41, s27, 2
	v_readlane_b32 s37, v236, s41
	s_cmp_lt_u32 s37, 32
	s_cbranch_scc0 .Lret_wctx_28
	s_lshl_b32 s100, s37, 6
	s_cmp_eq_u32 s37, s9
	s_cbranch_scc1 .Lret_wdiag_29
	s_cmp_lt_u32 s37, s9
	s_cselect_b32 s101, s11, s12
	v_subrev_u32_e32 v170, s100, v203
	v_subrev_u32_e32 v171, s100, v204
	v_subrev_u32_e32 v172, s100, v205
	v_subrev_u32_e32 v173, s100, v206
	v_cvt_f32_i32_e32 v174, v170
	v_cvt_f32_i32_e32 v175, v171
	v_cvt_f32_i32_e32 v176, v172
	v_cvt_f32_i32_e32 v177, v173
	v_mul_f32_e64 v178, s101, |v174|
	v_mul_f32_e64 v179, s101, |v175|
	v_mul_f32_e64 v180, s101, |v176|
	v_mul_f32_e64 v181, s101, |v177|
	v_exp_f32_e32 v166, v178
	v_exp_f32_e32 v167, v179
	v_exp_f32_e32 v168, v180
	v_exp_f32_e32 v169, v181
	s_branch .Lret_wdone_30

; #define RET_BAR() do { asm volatile("s_waitcnt lgkmcnt(0)" ::: "memory"); __builtin_amdgcn_s_barrier(); asm volatile("" ::: "memory"); } while (0)
; #define RET_LOADV(t) do { RET_KV(t) const char* vb_ = kb_ + (1024 + h * 256) * 2; const unsigned lo_ = (unsigned)(tid >> 6) * kp_ + (unsigned)(tid & 63) * 16u; \
;         _Pragma("unroll") for (int i_ = 0; i_ < 8; ++i_) vr[i_] = *(const u32x4*)(vb_ + (size_t)(8u * i_) * kp_ + lo_); } while (0)
; #define RET_STOREV() do { _Pragma("unroll") for (int i_ = 0; i_ < 8; ++i_) *(LAS u32x4*)(Vs + ((tid >> 6) + 8 * i_) * 1040 + (tid & 63) * 16) = vr[i_]; } while (0)
; __device__ __forceinline__ void ret_unit(ldsp lds, bf16_t* R, const bf16_t* RC, int b, int h, int qblk, float lgf2, float lgb2, const int tid_in) {
;     ...
;     for (int t = 0; t < 36; ++t) {
;         int tl_ = tid_outer; asm volatile("" : "+v"(tl_));
;         const int tid = tl_, lane = tid & 63, l15 = lane & 15, lg = lane >> 4;
;         if (wid < 4) { RET_PV(t); if (t + 1 < 36) RET_S(t + 1, TI(t + 1)); }
;         else { if (t + 1 < 36) RET_S(t + 1, TI(t + 1)); RET_PV(t); }
;         RET_BAR();
;         asm volatile("s_waitcnt vmcnt(0)" ::: "memory");
;         if (t + 1 < 36) RET_STOREV();
;         if (t + 2 < 36) RET_LOADV(TI(t + 2));
;         if (t + 3 < 36) RET_DMAK(TI(t + 3), (t + 1) & 1);
.Lret_wdone_30:
	v_mul_f32_e32 v170, v98, v242
	v_mul_f32_e32 v171, v99, v243
	v_mul_f32_e32 v172, v100, v244
	v_mul_f32_e32 v173, v101, v245
	v_cvt_pk_bf16_f32 v174, v170, v171
	v_cvt_pk_bf16_f32 v175, v172, v173
	ds_write_b64 v188, v[174:175] offset:5120
	s_waitcnt vmcnt(10)
	ds_read_b64_tr_b16 v[150:151], v183 offset:0
	ds_read_b64_tr_b16 v[152:153], v183 offset:512
	ds_read_b64_tr_b16 v[154:155], v184 offset:0
	ds_read_b64_tr_b16 v[156:157], v184 offset:512
	ds_read_b64_tr_b16 v[158:159], v185 offset:0
	ds_read_b64_tr_b16 v[160:161], v185 offset:512
	ds_read_b64_tr_b16 v[162:163], v186 offset:0
	ds_read_b64_tr_b16 v[164:165], v186 offset:512
	s_waitcnt lgkmcnt(8)
.Lret_regJ_24:
	s_barrier
	s_cmp_eq_u32 s38, 0
	s_cbranch_scc0 .Lret_regY_31
	ds_read_b128 v[102:105], v182 offset:16384
	ds_read_b128 v[106:109], v246 offset:16384
	ds_read_b128 v[110:113], v247 offset:16384
	ds_read_b128 v[114:117], v248 offset:16384
	ds_read_b128 v[118:121], v182 offset:16640
	ds_read_b128 v[122:125], v246 offset:16640
	ds_read_b128 v[126:129], v247 offset:16640
	ds_read_b128 v[130:133], v248 offset:16640
	ds_read_b128 v[134:137], v187 offset:5120
	ds_read_b128 v[138:141], v187 offset:6400
	ds_read_b128 v[142:145], v187 offset:7680
	ds_read_b128 v[146:149], v187 offset:8960
	s_add_i32 s41, s27, 3
	v_readlane_b32 s42, v238, s41
	v_readlane_b32 s43, v239, s41
	v_readlane_b32 s4, v237, s41
	s_mov_b32 s5, s4
	s_nop 0
	v_cndmask_b32_e64 v230, v191, v189, s[4:5]
	v_cndmask_b32_e64 v231, v192, v190, s[4:5]
	v_cndmask_b32_e64 v232, v198, v193, s[4:5]
	v_cndmask_b32_e64 v233, v199, v194, s[4:5]
	v_cndmask_b32_e64 v234, v200, v195, s[4:5]
	v_cndmask_b32_e64 v235, v202, v197, s[4:5]
	s_add_i32 m0, s54, 0
	s_nop 0
	global_load_lds_dwordx4 v230, s[42:43]
	s_add_i32 m0, s54, 1024
	s_nop 0
	global_load_lds_dwordx4 v231, s[42:43]
	s_waitcnt lgkmcnt(11)
	v_mfma_f32_16x16x32_bf16 v[98:101], v[102:105], v[64:67], 0
	s_waitcnt lgkmcnt(10)
	s_add_i32 m0, s55, 0
	v_mfma_f32_16x16x32_bf16 v[98:101], v[106:109], v[68:71], v[98:101]
	global_load_lds_dwordx4 v232, s[42:43]
	s_waitcnt lgkmcnt(9)
	s_add_i32 m0, s55, 1024
	v_mfma_f32_16x16x32_bf16 v[98:101], v[110:113], v[72:75], v[98:101]
	global_load_lds_dwordx4 v233, s[42:43]
	s_waitcnt lgkmcnt(8)
	s_add_i32 m0, s55, 2048
	v_mfma_f32_16x16x32_bf16 v[98:101], v[114:117], v[76:79], v[98:101]
	global_load_lds_dwordx4 v234, s[42:43]
	s_waitcnt lgkmcnt(7)
	s_add_i32 m0, s55, 3072
	v_mfma_f32_16x16x32_bf16 v[98:101], v[118:121], v[80:83], v[98:101]
	global_load_lds_dwordx4 v235, s[42:43]
	s_waitcnt lgkmcnt(6)
	v_mfma_f32_16x16x32_bf16 v[98:101], v[122:125], v[84:87], v[98:101]
	s_waitcnt lgkmcnt(5)
	v_mfma_f32_16x16x32_bf16 v[98:101], v[126:129], v[88:91], v[98:101]
	s_waitcnt lgkmcnt(4)
	v_mfma_f32_16x16x32_bf16 v[98:101], v[130:133], v[92:95], v[98:101]
	s_waitcnt lgkmcnt(0)
	v_mfma_f32_16x16x32_bf16 v[0:3], v[150:153], v[134:137], v[0:3]
	v_mfma_f32_16x16x32_bf16 v[16:19], v[154:157], v[134:137], v[16:19]
	v_mfma_f32_16x16x32_bf16 v[32:35], v[158:161], v[134:137], v[32:35]
	v_mfma_f32_16x16x32_bf16 v[48:51], v[162:165], v[134:137], v[48:51]
	v_mfma_f32_16x16x32_bf16 v[4:7], v[150:153], v[138:141], v[4:7]
	v_mfma_f32_16x16x32_bf16 v[20:23], v[154:157], v[138:141], v[20:23]
	v_mfma_f32_16x16x32_bf16 v[36:39], v[158:161], v[138:141], v[36:39]
	v_mfma_f32_16x16x32_bf16 v[52:55], v[162:165], v[138:141], v[52:55]
	v_mfma_f32_16x16x32_bf16 v[8:11], v[150:153], v[142:145], v[8:11]
	v_mfma_f32_16x16x32_bf16 v[24:27], v[154:157], v[142:145], v[24:27]
	v_mfma_f32_16x16x32_bf16 v[40:43], v[158:161], v[142:145], v[40:43]
	v_mfma_f32_16x16x32_bf16 v[56:59], v[162:165], v[142:145], v[56:59]
	v_mfma_f32_16x16x32_bf16 v[12:15], v[150:153], v[146:149], v[12:15]
	v_mfma_f32_16x16x32_bf16 v[28:31], v[154:157], v[146:149], v[28:31]
	v_mfma_f32_16x16x32_bf16 v[44:47], v[158:161], v[146:149], v[44:47]
	v_mfma_f32_16x16x32_bf16 v[60:63], v[162:165], v[146:149], v[60:63]
	v_mul_f32_e32 v170, v98, v166
	v_mul_f32_e32 v171, v99, v167
	v_mul_f32_e32 v172, v100, v168
	v_mul_f32_e32 v173, v101, v169
	v_cvt_pk_bf16_f32 v174, v170, v171
	v_cvt_pk_bf16_f32 v175, v172, v173
	ds_write_b64 v188, v[174:175] offset:0
	s_waitcnt vmcnt(10)
	ds_read_b64_tr_b16 v[150:151], v183 offset:4096
	ds_read_b64_tr_b16 v[152:153], v183 offset:4608
	ds_read_b64_tr_b16 v[154:155], v184 offset:4096
	ds_read_b64_tr_b16 v[156:157], v184 offset:4608
	ds_read_b64_tr_b16 v[158:159], v185 offset:4096
	ds_read_b64_tr_b16 v[160:161], v185 offset:4608
	ds_read_b64_tr_b16 v[162:163], v186 offset:4096
	ds_read_b64_tr_b16 v[164:165], v186 offset:4608
	s_add_i32 s41, s27, 2
	v_readlane_b32 s37, v236, s41
	s_cmp_lt_u32 s37, 32
	s_cbranch_scc0 .Lret_wctx_33
	s_lshl_b32 s100, s37, 6
	s_add_i32 s100, s100, 32
	s_cmp_eq_u32 s37, s9
	s_cbranch_scc1 .Lret_wdiag_34
	s_cmp_lt_u32 s37, s9
	s_cselect_b32 s101, s11, s12
	v_subrev_u32_e32 v170, s100, v203
	v_subrev_u32_e32 v171, s100, v204
	v_subrev_u32_e32 v172, s100, v205
	v_subrev_u32_e32 v173, s100, v206
	v_cvt_f32_i32_e32 v174, v170
	v_cvt_f32_i32_e32 v175, v171
	v_cvt_f32_i32_e32 v176, v172
	v_cvt_f32_i32_e32 v177, v173
	v_mul_f32_e64 v178, s101, |v174|
	v_mul_f32_e64 v179, s101, |v175|
	v_mul_f32_e64 v180, s101, |v176|
	v_mul_f32_e64 v181, s101, |v177|
	v_exp_f32_e32 v242, v178
	v_exp_f32_e32 v243, v179
	v_exp_f32_e32 v244, v180
	v_exp_f32_e32 v245, v181
	s_branch .Lret_wdone_35

; #define RET_BAR() do { asm volatile("s_waitcnt lgkmcnt(0)" ::: "memory"); __builtin_amdgcn_s_barrier(); asm volatile("" ::: "memory"); } while (0)
; #define RET_LOADV(t) do { RET_KV(t) const char* vb_ = kb_ + (1024 + h * 256) * 2; const unsigned lo_ = (unsigned)(tid >> 6) * kp_ + (unsigned)(tid & 63) * 16u; \
;         _Pragma("unroll") for (int i_ = 0; i_ < 8; ++i_) vr[i_] = *(const u32x4*)(vb_ + (size_t)(8u * i_) * kp_ + lo_); } while (0)
; #define RET_STOREV() do { _Pragma("unroll") for (int i_ = 0; i_ < 8; ++i_) *(LAS u32x4*)(Vs + ((tid >> 6) + 8 * i_) * 1040 + (tid & 63) * 16) = vr[i_]; } while (0)
; __device__ __forceinline__ void ret_unit(ldsp lds, bf16_t* R, const bf16_t* RC, int b, int h, int qblk, float lgf2, float lgb2, const int tid_in) {
;     ...
;     for (int t = 0; t < 36; ++t) {
;         int tl_ = tid_outer; asm volatile("" : "+v"(tl_));
;         const int tid = tl_, lane = tid & 63, l15 = lane & 15, lg = lane >> 4;
;         if (wid < 4) { RET_PV(t); if (t + 1 < 36) RET_S(t + 1, TI(t + 1)); }
;         else { if (t + 1 < 36) RET_S(t + 1, TI(t + 1)); RET_PV(t); }
;         RET_BAR();
;         asm volatile("s_waitcnt vmcnt(0)" ::: "memory");
;         if (t + 1 < 36) RET_STOREV();
;         if (t + 2 < 36) RET_LOADV(TI(t + 2));
;         if (t + 3 < 36) RET_DMAK(TI(t + 3), (t + 1) & 1);
.Lret_regY_31:
	ds_read_b128 v[134:137], v187 offset:5120
	ds_read_b128 v[138:141], v187 offset:6400
	ds_read_b128 v[142:145], v187 offset:7680
	ds_read_b128 v[146:149], v187 offset:8960
	ds_read_b128 v[102:105], v182 offset:16384
	ds_read_b128 v[106:109], v246 offset:16384
	ds_read_b128 v[110:113], v247 offset:16384
	ds_read_b128 v[114:117], v248 offset:16384
	ds_read_b128 v[118:121], v182 offset:16640
	ds_read_b128 v[122:125], v246 offset:16640
	ds_read_b128 v[126:129], v247 offset:16640
	ds_read_b128 v[130:133], v248 offset:16640
	s_add_i32 s41, s27, 3
	v_readlane_b32 s42, v238, s41
	v_readlane_b32 s43, v239, s41
	v_readlane_b32 s4, v237, s41
	s_mov_b32 s5, s4
	s_nop 0
	v_cndmask_b32_e64 v230, v191, v189, s[4:5]
	v_cndmask_b32_e64 v231, v192, v190, s[4:5]
	v_cndmask_b32_e64 v232, v198, v193, s[4:5]
	v_cndmask_b32_e64 v233, v199, v194, s[4:5]
	v_cndmask_b32_e64 v234, v200, v195, s[4:5]
	v_cndmask_b32_e64 v235, v202, v197, s[4:5]
	s_add_i32 m0, s54, 0
	s_nop 0
	global_load_lds_dwordx4 v230, s[42:43]
	s_add_i32 m0, s54, 1024
	s_nop 0
	global_load_lds_dwordx4 v231, s[42:43]
	s_waitcnt lgkmcnt(8)
	s_add_i32 m0, s55, 0
	v_mfma_f32_16x16x32_bf16 v[0:3], v[150:153], v[134:137], v[0:3]
	v_mfma_f32_16x16x32_bf16 v[16:19], v[154:157], v[134:137], v[16:19]
	global_load_lds_dwordx4 v232, s[42:43]
	v_mfma_f32_16x16x32_bf16 v[32:35], v[158:161], v[134:137], v[32:35]
	v_mfma_f32_16x16x32_bf16 v[48:51], v[162:165], v[134:137], v[48:51]
	s_add_i32 m0, s55, 1024
	v_mfma_f32_16x16x32_bf16 v[4:7], v[150:153], v[138:141], v[4:7]
	v_mfma_f32_16x16x32_bf16 v[20:23], v[154:157], v[138:141], v[20:23]
	global_load_lds_dwordx4 v233, s[42:43]
	v_mfma_f32_16x16x32_bf16 v[36:39], v[158:161], v[138:141], v[36:39]
	v_mfma_f32_16x16x32_bf16 v[52:55], v[162:165], v[138:141], v[52:55]
	s_add_i32 m0, s55, 2048
	v_mfma_f32_16x16x32_bf16 v[8:11], v[150:153], v[142:145], v[8:11]
	v_mfma_f32_16x16x32_bf16 v[24:27], v[154:157], v[142:145], v[24:27]
	global_load_lds_dwordx4 v234, s[42:43]
	v_mfma_f32_16x16x32_bf16 v[40:43], v[158:161], v[142:145], v[40:43]
	v_mfma_f32_16x16x32_bf16 v[56:59], v[162:165], v[142:145], v[56:59]
	s_add_i32 m0, s55, 3072
	v_mfma_f32_16x16x32_bf16 v[12:15], v[150:153], v[146:149], v[12:15]
	v_mfma_f32_16x16x32_bf16 v[28:31], v[154:157], v[146:149], v[28:31]
	global_load_lds_dwordx4 v235, s[42:43]
	v_mfma_f32_16x16x32_bf16 v[44:47], v[158:161], v[146:149], v[44:47]
	v_mfma_f32_16x16x32_bf16 v[60:63], v[162:165], v[146:149], v[60:63]
	s_waitcnt lgkmcnt(7)
	v_mfma_f32_16x16x32_bf16 v[98:101], v[102:105], v[64:67], 0
	s_waitcnt lgkmcnt(6)
	v_mfma_f32_16x16x32_bf16 v[98:101], v[106:109], v[68:71], v[98:101]
	s_waitcnt lgkmcnt(5)
	v_mfma_f32_16x16x32_bf16 v[98:101], v[110:113], v[72:75], v[98:101]
	s_waitcnt lgkmcnt(4)
	v_mfma_f32_16x16x32_bf16 v[98:101], v[114:117], v[76:79], v[98:101]
	s_waitcnt lgkmcnt(3)
	v_mfma_f32_16x16x32_bf16 v[98:101], v[118:121], v[80:83], v[98:101]
	s_waitcnt lgkmcnt(2)
	v_mfma_f32_16x16x32_bf16 v[98:101], v[122:125], v[84:87], v[98:101]
	s_waitcnt lgkmcnt(1)
	v_mfma_f32_16x16x32_bf16 v[98:101], v[126:129], v[88:91], v[98:101]
	s_waitcnt lgkmcnt(0)
	v_mfma_f32_16x16x32_bf16 v[98:101], v[130:133], v[92:95], v[98:101]
	s_add_i32 s41, s27, 2
	v_readlane_b32 s37, v236, s41
	s_cmp_lt_u32 s37, 32
	s_cbranch_scc0 .Lret_wctx_36
	s_lshl_b32 s100, s37, 6
	s_add_i32 s100, s100, 32
	s_cmp_eq_u32 s37, s9
	s_cbranch_scc1 .Lret_wdiag_37
	s_cmp_lt_u32 s37, s9
	s_cselect_b32 s101, s11, s12
	v_subrev_u32_e32 v170, s100, v203
	v_subrev_u32_e32 v171, s100, v204
	v_subrev_u32_e32 v172, s100, v205
	v_subrev_u32_e32 v173, s100, v206
	v_cvt_f32_i32_e32 v174, v170
	v_cvt_f32_i32_e32 v175, v171
	v_cvt_f32_i32_e32 v176, v172
	v_cvt_f32_i32_e32 v177, v173
	v_mul_f32_e64 v178, s101, |v174|
	v_mul_f32_e64 v179, s101, |v175|
	v_mul_f32_e64 v180, s101, |v176|
	v_mul_f32_e64 v181, s101, |v177|
	v_exp_f32_e32 v242, v178
	v_exp_f32_e32 v243, v179
	v_exp_f32_e32 v244, v180
	v_exp_f32_e32 v245, v181
	s_branch .Lret_wdone_38

; #define RET_BAR() do { asm volatile("s_waitcnt lgkmcnt(0)" ::: "memory"); __builtin_amdgcn_s_barrier(); asm volatile("" ::: "memory"); } while (0)
; #define RET_LOADV(t) do { RET_KV(t) const char* vb_ = kb_ + (1024 + h * 256) * 2; const unsigned lo_ = (unsigned)(tid >> 6) * kp_ + (unsigned)(tid & 63) * 16u; \
;         _Pragma("unroll") for (int i_ = 0; i_ < 8; ++i_) vr[i_] = *(const u32x4*)(vb_ + (size_t)(8u * i_) * kp_ + lo_); } while (0)
; #define RET_STOREV() do { _Pragma("unroll") for (int i_ = 0; i_ < 8; ++i_) *(LAS u32x4*)(Vs + ((tid >> 6) + 8 * i_) * 1040 + (tid & 63) * 16) = vr[i_]; } while (0)
; __device__ __forceinline__ void ret_unit(ldsp lds, bf16_t* R, const bf16_t* RC, int b, int h, int qblk, float lgf2, float lgb2, const int tid_in) {
;     ...
;     for (int t = 0; t < 36; ++t) {
;         int tl_ = tid_outer; asm volatile("" : "+v"(tl_));
;         const int tid = tl_, lane = tid & 63, l15 = lane & 15, lg = lane >> 4;
;         if (wid < 4) { RET_PV(t); if (t + 1 < 36) RET_S(t + 1, TI(t + 1)); }
;         else { if (t + 1 < 36) RET_S(t + 1, TI(t + 1)); RET_PV(t); }
;         RET_BAR();
;         asm volatile("s_waitcnt vmcnt(0)" ::: "memory");
;         if (t + 1 < 36) RET_STOREV();
;         if (t + 2 < 36) RET_LOADV(TI(t + 2));
;         if (t + 3 < 36) RET_DMAK(TI(t + 3), (t + 1) & 1);
.Lret_wdone_38:
	v_mul_f32_e32 v170, v98, v166
	v_mul_f32_e32 v171, v99, v167
	v_mul_f32_e32 v172, v100, v168
	v_mul_f32_e32 v173, v101, v169
	v_cvt_pk_bf16_f32 v174, v170, v171
	v_cvt_pk_bf16_f32 v175, v172, v173
	ds_write_b64 v188, v[174:175] offset:0
	s_waitcnt vmcnt(10)
	ds_read_b64_tr_b16 v[150:151], v183 offset:4096
	ds_read_b64_tr_b16 v[152:153], v183 offset:4608
	ds_read_b64_tr_b16 v[154:155], v184 offset:4096
	ds_read_b64_tr_b16 v[156:157], v184 offset:4608
	ds_read_b64_tr_b16 v[158:159], v185 offset:4096
	ds_read_b64_tr_b16 v[160:161], v185 offset:4608
	ds_read_b64_tr_b16 v[162:163], v186 offset:4096
	ds_read_b64_tr_b16 v[164:165], v186 offset:4608
	s_waitcnt lgkmcnt(8)
.Lret_regJ_32:
	s_barrier
	s_cmp_eq_u32 s38, 0
	s_cbranch_scc0 .Lret_regY_39
	ds_read_b128 v[102:105], v182 offset:32768
	ds_read_b128 v[106:109], v246 offset:32768
	ds_read_b128 v[110:113], v247 offset:32768
	ds_read_b128 v[114:117], v248 offset:32768
	ds_read_b128 v[118:121], v182 offset:33024
	ds_read_b128 v[122:125], v246 offset:33024
	ds_read_b128 v[126:129], v247 offset:33024
	ds_read_b128 v[130:133], v248 offset:33024
	ds_read_b128 v[134:137], v187 offset:0
	ds_read_b128 v[138:141], v187 offset:1280
	ds_read_b128 v[142:145], v187 offset:2560
	ds_read_b128 v[146:149], v187 offset:3840
	s_add_i32 s41, s27, 3
	v_readlane_b32 s42, v240, s41
	v_readlane_b32 s43, v241, s41
	v_readlane_b32 s4, v237, s41
	s_mov_b32 s5, s4
	s_nop 0
	v_cndmask_b32_e64 v230, v191, v189, s[4:5]
	v_cndmask_b32_e64 v231, v192, v190, s[4:5]
	v_cndmask_b32_e64 v232, v198, v193, s[4:5]
	v_cndmask_b32_e64 v233, v199, v194, s[4:5]
	v_cndmask_b32_e64 v234, v200, v195, s[4:5]
	v_cndmask_b32_e64 v235, v202, v197, s[4:5]
	s_add_i32 m0, s54, 16384
	s_nop 0
	global_load_lds_dwordx4 v230, s[42:43]
	s_add_i32 m0, s54, 17408
	s_nop 0
	global_load_lds_dwordx4 v231, s[42:43]
	s_waitcnt lgkmcnt(11)
	v_mfma_f32_16x16x32_bf16 v[98:101], v[102:105], v[64:67], 0
	s_waitcnt lgkmcnt(10)
	s_add_i32 m0, s55, 4096
	v_mfma_f32_16x16x32_bf16 v[98:101], v[106:109], v[68:71], v[98:101]
	global_load_lds_dwordx4 v232, s[42:43]
	s_waitcnt lgkmcnt(9)
	s_add_i32 m0, s55, 5120
	v_mfma_f32_16x16x32_bf16 v[98:101], v[110:113], v[72:75], v[98:101]
	global_load_lds_dwordx4 v233, s[42:43]
	s_waitcnt lgkmcnt(8)
	s_add_i32 m0, s55, 6144
	v_mfma_f32_16x16x32_bf16 v[98:101], v[114:117], v[76:79], v[98:101]
	global_load_lds_dwordx4 v234, s[42:43]
	s_waitcnt lgkmcnt(7)
	s_add_i32 m0, s55, 7168
	v_mfma_f32_16x16x32_bf16 v[98:101], v[118:121], v[80:83], v[98:101]
	global_load_lds_dwordx4 v235, s[42:43]
	s_waitcnt lgkmcnt(6)
	v_mfma_f32_16x16x32_bf16 v[98:101], v[122:125], v[84:87], v[98:101]
	s_waitcnt lgkmcnt(5)
	v_mfma_f32_16x16x32_bf16 v[98:101], v[126:129], v[88:91], v[98:101]
	s_waitcnt lgkmcnt(4)
	v_mfma_f32_16x16x32_bf16 v[98:101], v[130:133], v[92:95], v[98:101]
	s_waitcnt lgkmcnt(0)
	v_mfma_f32_16x16x32_bf16 v[0:3], v[150:153], v[134:137], v[0:3]
	v_mfma_f32_16x16x32_bf16 v[16:19], v[154:157], v[134:137], v[16:19]
	v_mfma_f32_16x16x32_bf16 v[32:35], v[158:161], v[134:137], v[32:35]
	v_mfma_f32_16x16x32_bf16 v[48:51], v[162:165], v[134:137], v[48:51]
	v_mfma_f32_16x16x32_bf16 v[4:7], v[150:153], v[138:141], v[4:7]
	v_mfma_f32_16x16x32_bf16 v[20:23], v[154:157], v[138:141], v[20:23]
	v_mfma_f32_16x16x32_bf16 v[36:39], v[158:161], v[138:141], v[36:39]
	v_mfma_f32_16x16x32_bf16 v[52:55], v[162:165], v[138:141], v[52:55]
	v_mfma_f32_16x16x32_bf16 v[8:11], v[150:153], v[142:145], v[8:11]
	v_mfma_f32_16x16x32_bf16 v[24:27], v[154:157], v[142:145], v[24:27]
	v_mfma_f32_16x16x32_bf16 v[40:43], v[158:161], v[142:145], v[40:43]
	v_mfma_f32_16x16x32_bf16 v[56:59], v[162:165], v[142:145], v[56:59]
	v_mfma_f32_16x16x32_bf16 v[12:15], v[150:153], v[146:149], v[12:15]
	v_mfma_f32_16x16x32_bf16 v[28:31], v[154:157], v[146:149], v[28:31]
	v_mfma_f32_16x16x32_bf16 v[44:47], v[158:161], v[146:149], v[44:47]
	v_mfma_f32_16x16x32_bf16 v[60:63], v[162:165], v[146:149], v[60:63]
	v_mul_f32_e32 v170, v98, v242
	v_mul_f32_e32 v171, v99, v243
	v_mul_f32_e32 v172, v100, v244
	v_mul_f32_e32 v173, v101, v245
	v_cvt_pk_bf16_f32 v174, v170, v171
	v_cvt_pk_bf16_f32 v175, v172, v173
	ds_write_b64 v188, v[174:175] offset:5120
	s_waitcnt vmcnt(10)
	ds_read_b64_tr_b16 v[150:151], v183 offset:8192
	ds_read_b64_tr_b16 v[152:153], v183 offset:8704
	ds_read_b64_tr_b16 v[154:155], v184 offset:8192
	ds_read_b64_tr_b16 v[156:157], v184 offset:8704
	ds_read_b64_tr_b16 v[158:159], v185 offset:8192
	ds_read_b64_tr_b16 v[160:161], v185 offset:8704
	ds_read_b64_tr_b16 v[162:163], v186 offset:8192
	ds_read_b64_tr_b16 v[164:165], v186 offset:8704
	s_add_i32 s41, s27, 3
	v_readlane_b32 s37, v236, s41
	s_cmp_lt_u32 s37, 32
	s_cbranch_scc0 .Lret_wctx_41
	s_lshl_b32 s100, s37, 6
	s_cmp_eq_u32 s37, s9
	s_cbranch_scc1 .Lret_wdiag_42
	s_cmp_lt_u32 s37, s9
	s_cselect_b32 s101, s11, s12
	v_subrev_u32_e32 v170, s100, v203
	v_subrev_u32_e32 v171, s100, v204
	v_subrev_u32_e32 v172, s100, v205
	v_subrev_u32_e32 v173, s100, v206
	v_cvt_f32_i32_e32 v174, v170
	v_cvt_f32_i32_e32 v175, v171
	v_cvt_f32_i32_e32 v176, v172
	v_cvt_f32_i32_e32 v177, v173
	v_mul_f32_e64 v178, s101, |v174|
	v_mul_f32_e64 v179, s101, |v175|
	v_mul_f32_e64 v180, s101, |v176|
	v_mul_f32_e64 v181, s101, |v177|
	v_exp_f32_e32 v166, v178
	v_exp_f32_e32 v167, v179
	v_exp_f32_e32 v168, v180
	v_exp_f32_e32 v169, v181
	s_branch .Lret_wdone_43

; #define RET_BAR() do { asm volatile("s_waitcnt lgkmcnt(0)" ::: "memory"); __builtin_amdgcn_s_barrier(); asm volatile("" ::: "memory"); } while (0)
; #define RET_LOADV(t) do { RET_KV(t) const char* vb_ = kb_ + (1024 + h * 256) * 2; const unsigned lo_ = (unsigned)(tid >> 6) * kp_ + (unsigned)(tid & 63) * 16u; \
;         _Pragma("unroll") for (int i_ = 0; i_ < 8; ++i_) vr[i_] = *(const u32x4*)(vb_ + (size_t)(8u * i_) * kp_ + lo_); } while (0)
; #define RET_STOREV() do { _Pragma("unroll") for (int i_ = 0; i_ < 8; ++i_) *(LAS u32x4*)(Vs + ((tid >> 6) + 8 * i_) * 1040 + (tid & 63) * 16) = vr[i_]; } while (0)
; __device__ __forceinline__ void ret_unit(ldsp lds, bf16_t* R, const bf16_t* RC, int b, int h, int qblk, float lgf2, float lgb2, const int tid_in) {
;     ...
;     for (int t = 0; t < 36; ++t) {
;         int tl_ = tid_outer; asm volatile("" : "+v"(tl_));
;         const int tid = tl_, lane = tid & 63, l15 = lane & 15, lg = lane >> 4;
;         if (wid < 4) { RET_PV(t); if (t + 1 < 36) RET_S(t + 1, TI(t + 1)); }
;         else { if (t + 1 < 36) RET_S(t + 1, TI(t + 1)); RET_PV(t); }
;         RET_BAR();
;         asm volatile("s_waitcnt vmcnt(0)" ::: "memory");
;         if (t + 1 < 36) RET_STOREV();
;         if (t + 2 < 36) RET_LOADV(TI(t + 2));
;         if (t + 3 < 36) RET_DMAK(TI(t + 3), (t + 1) & 1);
.Lret_regY_39:
	ds_read_b128 v[134:137], v187 offset:0
	ds_read_b128 v[138:141], v187 offset:1280
	ds_read_b128 v[142:145], v187 offset:2560
	ds_read_b128 v[146:149], v187 offset:3840
	ds_read_b128 v[102:105], v182 offset:32768
	ds_read_b128 v[106:109], v246 offset:32768
	ds_read_b128 v[110:113], v247 offset:32768
	ds_read_b128 v[114:117], v248 offset:32768
	ds_read_b128 v[118:121], v182 offset:33024
	ds_read_b128 v[122:125], v246 offset:33024
	ds_read_b128 v[126:129], v247 offset:33024
	ds_read_b128 v[130:133], v248 offset:33024
	s_add_i32 s41, s27, 3
	v_readlane_b32 s42, v240, s41
	v_readlane_b32 s43, v241, s41
	v_readlane_b32 s4, v237, s41
	s_mov_b32 s5, s4
	s_nop 0
	v_cndmask_b32_e64 v230, v191, v189, s[4:5]
	v_cndmask_b32_e64 v231, v192, v190, s[4:5]
	v_cndmask_b32_e64 v232, v198, v193, s[4:5]
	v_cndmask_b32_e64 v233, v199, v194, s[4:5]
	v_cndmask_b32_e64 v234, v200, v195, s[4:5]
	v_cndmask_b32_e64 v235, v202, v197, s[4:5]
	s_add_i32 m0, s54, 16384
	s_nop 0
	global_load_lds_dwordx4 v230, s[42:43]
	s_add_i32 m0, s54, 17408
	s_nop 0
	global_load_lds_dwordx4 v231, s[42:43]
	s_waitcnt lgkmcnt(8)
	s_add_i32 m0, s55, 4096
	v_mfma_f32_16x16x32_bf16 v[0:3], v[150:153], v[134:137], v[0:3]
	v_mfma_f32_16x16x32_bf16 v[16:19], v[154:157], v[134:137], v[16:19]
	global_load_lds_dwordx4 v232, s[42:43]
	v_mfma_f32_16x16x32_bf16 v[32:35], v[158:161], v[134:137], v[32:35]
	v_mfma_f32_16x16x32_bf16 v[48:51], v[162:165], v[134:137], v[48:51]
	s_add_i32 m0, s55, 5120
	v_mfma_f32_16x16x32_bf16 v[4:7], v[150:153], v[138:141], v[4:7]
	v_mfma_f32_16x16x32_bf16 v[20:23], v[154:157], v[138:141], v[20:23]
	global_load_lds_dwordx4 v233, s[42:43]
	v_mfma_f32_16x16x32_bf16 v[36:39], v[158:161], v[138:141], v[36:39]
	v_mfma_f32_16x16x32_bf16 v[52:55], v[162:165], v[138:141], v[52:55]
	s_add_i32 m0, s55, 6144
	v_mfma_f32_16x16x32_bf16 v[8:11], v[150:153], v[142:145], v[8:11]
	v_mfma_f32_16x16x32_bf16 v[24:27], v[154:157], v[142:145], v[24:27]
	global_load_lds_dwordx4 v234, s[42:43]
	v_mfma_f32_16x16x32_bf16 v[40:43], v[158:161], v[142:145], v[40:43]
	v_mfma_f32_16x16x32_bf16 v[56:59], v[162:165], v[142:145], v[56:59]
	s_add_i32 m0, s55, 7168
	v_mfma_f32_16x16x32_bf16 v[12:15], v[150:153], v[146:149], v[12:15]
	v_mfma_f32_16x16x32_bf16 v[28:31], v[154:157], v[146:149], v[28:31]
	global_load_lds_dwordx4 v235, s[42:43]
	v_mfma_f32_16x16x32_bf16 v[44:47], v[158:161], v[146:149], v[44:47]
	v_mfma_f32_16x16x32_bf16 v[60:63], v[162:165], v[146:149], v[60:63]
	s_waitcnt lgkmcnt(7)
	v_mfma_f32_16x16x32_bf16 v[98:101], v[102:105], v[64:67], 0
	s_waitcnt lgkmcnt(6)
	v_mfma_f32_16x16x32_bf16 v[98:101], v[106:109], v[68:71], v[98:101]
	s_waitcnt lgkmcnt(5)
	v_mfma_f32_16x16x32_bf16 v[98:101], v[110:113], v[72:75], v[98:101]
	s_waitcnt lgkmcnt(4)
	v_mfma_f32_16x16x32_bf16 v[98:101], v[114:117], v[76:79], v[98:101]
	s_waitcnt lgkmcnt(3)
	v_mfma_f32_16x16x32_bf16 v[98:101], v[118:121], v[80:83], v[98:101]
	s_waitcnt lgkmcnt(2)
	v_mfma_f32_16x16x32_bf16 v[98:101], v[122:125], v[84:87], v[98:101]
	s_waitcnt lgkmcnt(1)
	v_mfma_f32_16x16x32_bf16 v[98:101], v[126:129], v[88:91], v[98:101]
	s_waitcnt lgkmcnt(0)
	v_mfma_f32_16x16x32_bf16 v[98:101], v[130:133], v[92:95], v[98:101]
	s_add_i32 s41, s27, 3
	v_readlane_b32 s37, v236, s41
	s_cmp_lt_u32 s37, 32
	s_cbranch_scc0 .Lret_wctx_44
	s_lshl_b32 s100, s37, 6
	s_cmp_eq_u32 s37, s9
	s_cbranch_scc1 .Lret_wdiag_45
	s_cmp_lt_u32 s37, s9
	s_cselect_b32 s101, s11, s12
	v_subrev_u32_e32 v170, s100, v203
	v_subrev_u32_e32 v171, s100, v204
	v_subrev_u32_e32 v172, s100, v205
	v_subrev_u32_e32 v173, s100, v206
	v_cvt_f32_i32_e32 v174, v170
	v_cvt_f32_i32_e32 v175, v171
	v_cvt_f32_i32_e32 v176, v172
	v_cvt_f32_i32_e32 v177, v173
	v_mul_f32_e64 v178, s101, |v174|
	v_mul_f32_e64 v179, s101, |v175|
	v_mul_f32_e64 v180, s101, |v176|
	v_mul_f32_e64 v181, s101, |v177|
	v_exp_f32_e32 v166, v178
	v_exp_f32_e32 v167, v179
	v_exp_f32_e32 v168, v180
	v_exp_f32_e32 v169, v181
	s_branch .Lret_wdone_46

; #define RET_BAR() do { asm volatile("s_waitcnt lgkmcnt(0)" ::: "memory"); __builtin_amdgcn_s_barrier(); asm volatile("" ::: "memory"); } while (0)
; #define RET_LOADV(t) do { RET_KV(t) const char* vb_ = kb_ + (1024 + h * 256) * 2; const unsigned lo_ = (unsigned)(tid >> 6) * kp_ + (unsigned)(tid & 63) * 16u; \
;         _Pragma("unroll") for (int i_ = 0; i_ < 8; ++i_) vr[i_] = *(const u32x4*)(vb_ + (size_t)(8u * i_) * kp_ + lo_); } while (0)
; #define RET_STOREV() do { _Pragma("unroll") for (int i_ = 0; i_ < 8; ++i_) *(LAS u32x4*)(Vs + ((tid >> 6) + 8 * i_) * 1040 + (tid & 63) * 16) = vr[i_]; } while (0)
; __device__ __forceinline__ void ret_unit(ldsp lds, bf16_t* R, const bf16_t* RC, int b, int h, int qblk, float lgf2, float lgb2, const int tid_in) {
;     ...
;     for (int t = 0; t < 36; ++t) {
;         int tl_ = tid_outer; asm volatile("" : "+v"(tl_));
;         const int tid = tl_, lane = tid & 63, l15 = lane & 15, lg = lane >> 4;
;         if (wid < 4) { RET_PV(t); if (t + 1 < 36) RET_S(t + 1, TI(t + 1)); }
;         else { if (t + 1 < 36) RET_S(t + 1, TI(t + 1)); RET_PV(t); }
;         RET_BAR();
;         asm volatile("s_waitcnt vmcnt(0)" ::: "memory");
;         if (t + 1 < 36) RET_STOREV();
;         if (t + 2 < 36) RET_LOADV(TI(t + 2));
;         if (t + 3 < 36) RET_DMAK(TI(t + 3), (t + 1) & 1);
.Lret_wdone_46:
	v_mul_f32_e32 v170, v98, v242
	v_mul_f32_e32 v171, v99, v243
	v_mul_f32_e32 v172, v100, v244
	v_mul_f32_e32 v173, v101, v245
	v_cvt_pk_bf16_f32 v174, v170, v171
	v_cvt_pk_bf16_f32 v175, v172, v173
	ds_write_b64 v188, v[174:175] offset:5120
	s_waitcnt vmcnt(10)
	ds_read_b64_tr_b16 v[150:151], v183 offset:8192
	ds_read_b64_tr_b16 v[152:153], v183 offset:8704
	ds_read_b64_tr_b16 v[154:155], v184 offset:8192
	ds_read_b64_tr_b16 v[156:157], v184 offset:8704
	ds_read_b64_tr_b16 v[158:159], v185 offset:8192
	ds_read_b64_tr_b16 v[160:161], v185 offset:8704
	ds_read_b64_tr_b16 v[162:163], v186 offset:8192
	ds_read_b64_tr_b16 v[164:165], v186 offset:8704
	s_waitcnt lgkmcnt(8)
.Lret_regJ_40:
	s_barrier
	s_cmp_eq_u32 s38, 0
	s_cbranch_scc0 .Lret_regY_47
	ds_read_b128 v[102:105], v182 offset:0
	ds_read_b128 v[106:109], v246 offset:0
	ds_read_b128 v[110:113], v247 offset:0
	ds_read_b128 v[114:117], v248 offset:0
	ds_read_b128 v[118:121], v182 offset:256
	ds_read_b128 v[122:125], v246 offset:256
	ds_read_b128 v[126:129], v247 offset:256
	ds_read_b128 v[130:133], v248 offset:256
	ds_read_b128 v[134:137], v187 offset:5120
	ds_read_b128 v[138:141], v187 offset:6400
	ds_read_b128 v[142:145], v187 offset:7680
	ds_read_b128 v[146:149], v187 offset:8960
	s_add_i32 s41, s27, 4
	v_readlane_b32 s42, v238, s41
	v_readlane_b32 s43, v239, s41
	v_readlane_b32 s4, v237, s41
	s_mov_b32 s5, s4
	s_nop 0
	v_cndmask_b32_e64 v230, v191, v189, s[4:5]
	v_cndmask_b32_e64 v231, v192, v190, s[4:5]
	v_cndmask_b32_e64 v232, v198, v193, s[4:5]
	v_cndmask_b32_e64 v233, v199, v194, s[4:5]
	v_cndmask_b32_e64 v234, v200, v195, s[4:5]
	v_cndmask_b32_e64 v235, v202, v197, s[4:5]
	s_add_i32 m0, s54, 32768
	s_nop 0
	global_load_lds_dwordx4 v230, s[42:43]
	s_add_i32 m0, s54, 33792
	s_nop 0
	global_load_lds_dwordx4 v231, s[42:43]
	s_waitcnt lgkmcnt(11)
	v_mfma_f32_16x16x32_bf16 v[98:101], v[102:105], v[64:67], 0
	s_waitcnt lgkmcnt(10)
	s_add_i32 m0, s55, 8192
	v_mfma_f32_16x16x32_bf16 v[98:101], v[106:109], v[68:71], v[98:101]
	global_load_lds_dwordx4 v232, s[42:43]
	s_waitcnt lgkmcnt(9)
	s_add_i32 m0, s55, 9216
	v_mfma_f32_16x16x32_bf16 v[98:101], v[110:113], v[72:75], v[98:101]
	global_load_lds_dwordx4 v233, s[42:43]
	s_waitcnt lgkmcnt(8)
	s_add_i32 m0, s55, 10240
	v_mfma_f32_16x16x32_bf16 v[98:101], v[114:117], v[76:79], v[98:101]
	global_load_lds_dwordx4 v234, s[42:43]
	s_waitcnt lgkmcnt(7)
	s_add_i32 m0, s55, 11264
	v_mfma_f32_16x16x32_bf16 v[98:101], v[118:121], v[80:83], v[98:101]
	global_load_lds_dwordx4 v235, s[42:43]
	s_waitcnt lgkmcnt(6)
	v_mfma_f32_16x16x32_bf16 v[98:101], v[122:125], v[84:87], v[98:101]
	s_waitcnt lgkmcnt(5)
	v_mfma_f32_16x16x32_bf16 v[98:101], v[126:129], v[88:91], v[98:101]
	s_waitcnt lgkmcnt(4)
	v_mfma_f32_16x16x32_bf16 v[98:101], v[130:133], v[92:95], v[98:101]
	s_waitcnt lgkmcnt(0)
	v_mfma_f32_16x16x32_bf16 v[0:3], v[150:153], v[134:137], v[0:3]
	v_mfma_f32_16x16x32_bf16 v[16:19], v[154:157], v[134:137], v[16:19]
	v_mfma_f32_16x16x32_bf16 v[32:35], v[158:161], v[134:137], v[32:35]
	v_mfma_f32_16x16x32_bf16 v[48:51], v[162:165], v[134:137], v[48:51]
	v_mfma_f32_16x16x32_bf16 v[4:7], v[150:153], v[138:141], v[4:7]
	v_mfma_f32_16x16x32_bf16 v[20:23], v[154:157], v[138:141], v[20:23]
	v_mfma_f32_16x16x32_bf16 v[36:39], v[158:161], v[138:141], v[36:39]
	v_mfma_f32_16x16x32_bf16 v[52:55], v[162:165], v[138:141], v[52:55]
	v_mfma_f32_16x16x32_bf16 v[8:11], v[150:153], v[142:145], v[8:11]
	v_mfma_f32_16x16x32_bf16 v[24:27], v[154:157], v[142:145], v[24:27]
	v_mfma_f32_16x16x32_bf16 v[40:43], v[158:161], v[142:145], v[40:43]
	v_mfma_f32_16x16x32_bf16 v[56:59], v[162:165], v[142:145], v[56:59]
	v_mfma_f32_16x16x32_bf16 v[12:15], v[150:153], v[146:149], v[12:15]
	v_mfma_f32_16x16x32_bf16 v[28:31], v[154:157], v[146:149], v[28:31]
	v_mfma_f32_16x16x32_bf16 v[44:47], v[158:161], v[146:149], v[44:47]
	v_mfma_f32_16x16x32_bf16 v[60:63], v[162:165], v[146:149], v[60:63]
	v_mul_f32_e32 v170, v98, v166
	v_mul_f32_e32 v171, v99, v167
	v_mul_f32_e32 v172, v100, v168
	v_mul_f32_e32 v173, v101, v169
	v_cvt_pk_bf16_f32 v174, v170, v171
	v_cvt_pk_bf16_f32 v175, v172, v173
	ds_write_b64 v188, v[174:175] offset:0
	s_waitcnt vmcnt(10)
	ds_read_b64_tr_b16 v[150:151], v183 offset:0
	ds_read_b64_tr_b16 v[152:153], v183 offset:512
	ds_read_b64_tr_b16 v[154:155], v184 offset:0
	ds_read_b64_tr_b16 v[156:157], v184 offset:512
	ds_read_b64_tr_b16 v[158:159], v185 offset:0
	ds_read_b64_tr_b16 v[160:161], v185 offset:512
	ds_read_b64_tr_b16 v[162:163], v186 offset:0
	ds_read_b64_tr_b16 v[164:165], v186 offset:512
	s_add_i32 s41, s27, 3
	v_readlane_b32 s37, v236, s41
	s_cmp_lt_u32 s37, 32
	s_cbranch_scc0 .Lret_wctx_49
	s_lshl_b32 s100, s37, 6
	s_add_i32 s100, s100, 32
	s_cmp_eq_u32 s37, s9
	s_cbranch_scc1 .Lret_wdiag_50
	s_cmp_lt_u32 s37, s9
	s_cselect_b32 s101, s11, s12
	v_subrev_u32_e32 v170, s100, v203
	v_subrev_u32_e32 v171, s100, v204
	v_subrev_u32_e32 v172, s100, v205
	v_subrev_u32_e32 v173, s100, v206
	v_cvt_f32_i32_e32 v174, v170
	v_cvt_f32_i32_e32 v175, v171
	v_cvt_f32_i32_e32 v176, v172
	v_cvt_f32_i32_e32 v177, v173
	v_mul_f32_e64 v178, s101, |v174|
	v_mul_f32_e64 v179, s101, |v175|
	v_mul_f32_e64 v180, s101, |v176|
	v_mul_f32_e64 v181, s101, |v177|
	v_exp_f32_e32 v242, v178
	v_exp_f32_e32 v243, v179
	v_exp_f32_e32 v244, v180
	v_exp_f32_e32 v245, v181
	s_branch .Lret_wdone_51

; #define RET_BAR() do { asm volatile("s_waitcnt lgkmcnt(0)" ::: "memory"); __builtin_amdgcn_s_barrier(); asm volatile("" ::: "memory"); } while (0)
; #define RET_LOADV(t) do { RET_KV(t) const char* vb_ = kb_ + (1024 + h * 256) * 2; const unsigned lo_ = (unsigned)(tid >> 6) * kp_ + (unsigned)(tid & 63) * 16u; \
;         _Pragma("unroll") for (int i_ = 0; i_ < 8; ++i_) vr[i_] = *(const u32x4*)(vb_ + (size_t)(8u * i_) * kp_ + lo_); } while (0)
; #define RET_STOREV() do { _Pragma("unroll") for (int i_ = 0; i_ < 8; ++i_) *(LAS u32x4*)(Vs + ((tid >> 6) + 8 * i_) * 1040 + (tid & 63) * 16) = vr[i_]; } while (0)
; __device__ __forceinline__ void ret_unit(ldsp lds, bf16_t* R, const bf16_t* RC, int b, int h, int qblk, float lgf2, float lgb2, const int tid_in) {
;     ...
;     for (int t = 0; t < 36; ++t) {
;         int tl_ = tid_outer; asm volatile("" : "+v"(tl_));
;         const int tid = tl_, lane = tid & 63, l15 = lane & 15, lg = lane >> 4;
;         if (wid < 4) { RET_PV(t); if (t + 1 < 36) RET_S(t + 1, TI(t + 1)); }
;         else { if (t + 1 < 36) RET_S(t + 1, TI(t + 1)); RET_PV(t); }
;         RET_BAR();
;         asm volatile("s_waitcnt vmcnt(0)" ::: "memory");
;         if (t + 1 < 36) RET_STOREV();
;         if (t + 2 < 36) RET_LOADV(TI(t + 2));
;         if (t + 3 < 36) RET_DMAK(TI(t + 3), (t + 1) & 1);
.Lret_regY_47:
	ds_read_b128 v[134:137], v187 offset:5120
	ds_read_b128 v[138:141], v187 offset:6400
	ds_read_b128 v[142:145], v187 offset:7680
	ds_read_b128 v[146:149], v187 offset:8960
	ds_read_b128 v[102:105], v182 offset:0
	ds_read_b128 v[106:109], v246 offset:0
	ds_read_b128 v[110:113], v247 offset:0
	ds_read_b128 v[114:117], v248 offset:0
	ds_read_b128 v[118:121], v182 offset:256
	ds_read_b128 v[122:125], v246 offset:256
	ds_read_b128 v[126:129], v247 offset:256
	ds_read_b128 v[130:133], v248 offset:256
	s_add_i32 s41, s27, 4
	v_readlane_b32 s42, v238, s41
	v_readlane_b32 s43, v239, s41
	v_readlane_b32 s4, v237, s41
	s_mov_b32 s5, s4
	s_nop 0
	v_cndmask_b32_e64 v230, v191, v189, s[4:5]
	v_cndmask_b32_e64 v231, v192, v190, s[4:5]
	v_cndmask_b32_e64 v232, v198, v193, s[4:5]
	v_cndmask_b32_e64 v233, v199, v194, s[4:5]
	v_cndmask_b32_e64 v234, v200, v195, s[4:5]
	v_cndmask_b32_e64 v235, v202, v197, s[4:5]
	s_add_i32 m0, s54, 32768
	s_nop 0
	global_load_lds_dwordx4 v230, s[42:43]
	s_add_i32 m0, s54, 33792
	s_nop 0
	global_load_lds_dwordx4 v231, s[42:43]
	s_waitcnt lgkmcnt(8)
	s_add_i32 m0, s55, 8192
	v_mfma_f32_16x16x32_bf16 v[0:3], v[150:153], v[134:137], v[0:3]
	v_mfma_f32_16x16x32_bf16 v[16:19], v[154:157], v[134:137], v[16:19]
	global_load_lds_dwordx4 v232, s[42:43]
	v_mfma_f32_16x16x32_bf16 v[32:35], v[158:161], v[134:137], v[32:35]
	v_mfma_f32_16x16x32_bf16 v[48:51], v[162:165], v[134:137], v[48:51]
	s_add_i32 m0, s55, 9216
	v_mfma_f32_16x16x32_bf16 v[4:7], v[150:153], v[138:141], v[4:7]
	v_mfma_f32_16x16x32_bf16 v[20:23], v[154:157], v[138:141], v[20:23]
	global_load_lds_dwordx4 v233, s[42:43]
	v_mfma_f32_16x16x32_bf16 v[36:39], v[158:161], v[138:141], v[36:39]
	v_mfma_f32_16x16x32_bf16 v[52:55], v[162:165], v[138:141], v[52:55]
	s_add_i32 m0, s55, 10240
	v_mfma_f32_16x16x32_bf16 v[8:11], v[150:153], v[142:145], v[8:11]
	v_mfma_f32_16x16x32_bf16 v[24:27], v[154:157], v[142:145], v[24:27]
	global_load_lds_dwordx4 v234, s[42:43]
	v_mfma_f32_16x16x32_bf16 v[40:43], v[158:161], v[142:145], v[40:43]
	v_mfma_f32_16x16x32_bf16 v[56:59], v[162:165], v[142:145], v[56:59]
	s_add_i32 m0, s55, 11264
	v_mfma_f32_16x16x32_bf16 v[12:15], v[150:153], v[146:149], v[12:15]
	v_mfma_f32_16x16x32_bf16 v[28:31], v[154:157], v[146:149], v[28:31]
	global_load_lds_dwordx4 v235, s[42:43]
	v_mfma_f32_16x16x32_bf16 v[44:47], v[158:161], v[146:149], v[44:47]
	v_mfma_f32_16x16x32_bf16 v[60:63], v[162:165], v[146:149], v[60:63]
	s_waitcnt lgkmcnt(7)
	v_mfma_f32_16x16x32_bf16 v[98:101], v[102:105], v[64:67], 0
	s_waitcnt lgkmcnt(6)
	v_mfma_f32_16x16x32_bf16 v[98:101], v[106:109], v[68:71], v[98:101]
	s_waitcnt lgkmcnt(5)
	v_mfma_f32_16x16x32_bf16 v[98:101], v[110:113], v[72:75], v[98:101]
	s_waitcnt lgkmcnt(4)
	v_mfma_f32_16x16x32_bf16 v[98:101], v[114:117], v[76:79], v[98:101]
	s_waitcnt lgkmcnt(3)
	v_mfma_f32_16x16x32_bf16 v[98:101], v[118:121], v[80:83], v[98:101]
	s_waitcnt lgkmcnt(2)
	v_mfma_f32_16x16x32_bf16 v[98:101], v[122:125], v[84:87], v[98:101]
	s_waitcnt lgkmcnt(1)
	v_mfma_f32_16x16x32_bf16 v[98:101], v[126:129], v[88:91], v[98:101]
	s_waitcnt lgkmcnt(0)
	v_mfma_f32_16x16x32_bf16 v[98:101], v[130:133], v[92:95], v[98:101]
	s_add_i32 s41, s27, 3
	v_readlane_b32 s37, v236, s41
	s_cmp_lt_u32 s37, 32
	s_cbranch_scc0 .Lret_wctx_52
	s_lshl_b32 s100, s37, 6
	s_add_i32 s100, s100, 32
	s_cmp_eq_u32 s37, s9
	s_cbranch_scc1 .Lret_wdiag_53
	s_cmp_lt_u32 s37, s9
	s_cselect_b32 s101, s11, s12
	v_subrev_u32_e32 v170, s100, v203
	v_subrev_u32_e32 v171, s100, v204
	v_subrev_u32_e32 v172, s100, v205
	v_subrev_u32_e32 v173, s100, v206
	v_cvt_f32_i32_e32 v174, v170
	v_cvt_f32_i32_e32 v175, v171
	v_cvt_f32_i32_e32 v176, v172
	v_cvt_f32_i32_e32 v177, v173
	v_mul_f32_e64 v178, s101, |v174|
	v_mul_f32_e64 v179, s101, |v175|
	v_mul_f32_e64 v180, s101, |v176|
	v_mul_f32_e64 v181, s101, |v177|
	v_exp_f32_e32 v242, v178
	v_exp_f32_e32 v243, v179
	v_exp_f32_e32 v244, v180
	v_exp_f32_e32 v245, v181
	s_branch .Lret_wdone_54

; #define RET_BAR() do { asm volatile("s_waitcnt lgkmcnt(0)" ::: "memory"); __builtin_amdgcn_s_barrier(); asm volatile("" ::: "memory"); } while (0)
; #define RET_LOADV(t) do { RET_KV(t) const char* vb_ = kb_ + (1024 + h * 256) * 2; const unsigned lo_ = (unsigned)(tid >> 6) * kp_ + (unsigned)(tid & 63) * 16u; \
;         _Pragma("unroll") for (int i_ = 0; i_ < 8; ++i_) vr[i_] = *(const u32x4*)(vb_ + (size_t)(8u * i_) * kp_ + lo_); } while (0)
; #define RET_STOREV() do { _Pragma("unroll") for (int i_ = 0; i_ < 8; ++i_) *(LAS u32x4*)(Vs + ((tid >> 6) + 8 * i_) * 1040 + (tid & 63) * 16) = vr[i_]; } while (0)
; __device__ __forceinline__ void ret_unit(ldsp lds, bf16_t* R, const bf16_t* RC, int b, int h, int qblk, float lgf2, float lgb2, const int tid_in) {
;     ...
;     for (int t = 0; t < 36; ++t) {
;         int tl_ = tid_outer; asm volatile("" : "+v"(tl_));
;         const int tid = tl_, lane = tid & 63, l15 = lane & 15, lg = lane >> 4;
;         if (wid < 4) { RET_PV(t); if (t + 1 < 36) RET_S(t + 1, TI(t + 1)); }
;         else { if (t + 1 < 36) RET_S(t + 1, TI(t + 1)); RET_PV(t); }
;         RET_BAR();
;         asm volatile("s_waitcnt vmcnt(0)" ::: "memory");
;         if (t + 1 < 36) RET_STOREV();
;         if (t + 2 < 36) RET_LOADV(TI(t + 2));
;         if (t + 3 < 36) RET_DMAK(TI(t + 3), (t + 1) & 1);
.Lret_wdone_54:
	v_mul_f32_e32 v170, v98, v166
	v_mul_f32_e32 v171, v99, v167
	v_mul_f32_e32 v172, v100, v168
	v_mul_f32_e32 v173, v101, v169
	v_cvt_pk_bf16_f32 v174, v170, v171
	v_cvt_pk_bf16_f32 v175, v172, v173
	ds_write_b64 v188, v[174:175] offset:0
	s_waitcnt vmcnt(10)
	ds_read_b64_tr_b16 v[150:151], v183 offset:0
	ds_read_b64_tr_b16 v[152:153], v183 offset:512
	ds_read_b64_tr_b16 v[154:155], v184 offset:0
	ds_read_b64_tr_b16 v[156:157], v184 offset:512
	ds_read_b64_tr_b16 v[158:159], v185 offset:0
	ds_read_b64_tr_b16 v[160:161], v185 offset:512
	ds_read_b64_tr_b16 v[162:163], v186 offset:0
	ds_read_b64_tr_b16 v[164:165], v186 offset:512
	s_waitcnt lgkmcnt(8)
.Lret_regJ_48:
	s_barrier
	s_add_i32 s27, s27, 3
	s_cmp_lt_u32 s27, 33
	s_cbranch_scc1 .Lret_loop
	s_cmp_eq_u32 s38, 0
	s_cbranch_scc0 .Lret_regY_55
	ds_read_b128 v[102:105], v182 offset:16384
	ds_read_b128 v[106:109], v246 offset:16384
	ds_read_b128 v[110:113], v247 offset:16384
	ds_read_b128 v[114:117], v248 offset:16384
	ds_read_b128 v[118:121], v182 offset:16640
	ds_read_b128 v[122:125], v246 offset:16640
	ds_read_b128 v[126:129], v247 offset:16640
	ds_read_b128 v[130:133], v248 offset:16640
	ds_read_b128 v[134:137], v187 offset:0
	ds_read_b128 v[138:141], v187 offset:1280
	ds_read_b128 v[142:145], v187 offset:2560
	ds_read_b128 v[146:149], v187 offset:3840
	s_add_i32 s41, s27, 1
	v_readlane_b32 s42, v240, s41
	v_readlane_b32 s43, v241, s41
	v_readlane_b32 s4, v237, s41
	s_mov_b32 s5, s4
	s_nop 0
	v_cndmask_b32_e64 v230, v191, v189, s[4:5]
	v_cndmask_b32_e64 v231, v192, v190, s[4:5]
	v_cndmask_b32_e64 v232, v198, v193, s[4:5]
	v_cndmask_b32_e64 v233, v199, v194, s[4:5]
	v_cndmask_b32_e64 v234, v200, v195, s[4:5]
	v_cndmask_b32_e64 v235, v202, v197, s[4:5]
	s_add_i32 m0, s54, 0
	s_nop 0
	global_load_lds_dwordx4 v230, s[42:43]
	s_add_i32 m0, s54, 1024
	s_nop 0
	global_load_lds_dwordx4 v231, s[42:43]
	s_waitcnt lgkmcnt(11)
	v_mfma_f32_16x16x32_bf16 v[98:101], v[102:105], v[64:67], 0
	s_waitcnt lgkmcnt(10)
	s_add_i32 m0, s55, 0
	v_mfma_f32_16x16x32_bf16 v[98:101], v[106:109], v[68:71], v[98:101]
	global_load_lds_dwordx4 v232, s[42:43]
	s_waitcnt lgkmcnt(9)
	s_add_i32 m0, s55, 1024
	v_mfma_f32_16x16x32_bf16 v[98:101], v[110:113], v[72:75], v[98:101]
	global_load_lds_dwordx4 v233, s[42:43]
	s_waitcnt lgkmcnt(8)
	s_add_i32 m0, s55, 2048
	v_mfma_f32_16x16x32_bf16 v[98:101], v[114:117], v[76:79], v[98:101]
	global_load_lds_dwordx4 v234, s[42:43]
	s_waitcnt lgkmcnt(7)
	s_add_i32 m0, s55, 3072
	v_mfma_f32_16x16x32_bf16 v[98:101], v[118:121], v[80:83], v[98:101]
	global_load_lds_dwordx4 v235, s[42:43]
	s_waitcnt lgkmcnt(6)
	v_mfma_f32_16x16x32_bf16 v[98:101], v[122:125], v[84:87], v[98:101]
	s_waitcnt lgkmcnt(5)
	v_mfma_f32_16x16x32_bf16 v[98:101], v[126:129], v[88:91], v[98:101]
	s_waitcnt lgkmcnt(4)
	v_mfma_f32_16x16x32_bf16 v[98:101], v[130:133], v[92:95], v[98:101]
	s_waitcnt lgkmcnt(0)
	v_mfma_f32_16x16x32_bf16 v[0:3], v[150:153], v[134:137], v[0:3]
	v_mfma_f32_16x16x32_bf16 v[16:19], v[154:157], v[134:137], v[16:19]
	v_mfma_f32_16x16x32_bf16 v[32:35], v[158:161], v[134:137], v[32:35]
	v_mfma_f32_16x16x32_bf16 v[48:51], v[162:165], v[134:137], v[48:51]
	v_mfma_f32_16x16x32_bf16 v[4:7], v[150:153], v[138:141], v[4:7]
	v_mfma_f32_16x16x32_bf16 v[20:23], v[154:157], v[138:141], v[20:23]
	v_mfma_f32_16x16x32_bf16 v[36:39], v[158:161], v[138:141], v[36:39]
	v_mfma_f32_16x16x32_bf16 v[52:55], v[162:165], v[138:141], v[52:55]
	v_mfma_f32_16x16x32_bf16 v[8:11], v[150:153], v[142:145], v[8:11]
	v_mfma_f32_16x16x32_bf16 v[24:27], v[154:157], v[142:145], v[24:27]
	v_mfma_f32_16x16x32_bf16 v[40:43], v[158:161], v[142:145], v[40:43]
	v_mfma_f32_16x16x32_bf16 v[56:59], v[162:165], v[142:145], v[56:59]
	v_mfma_f32_16x16x32_bf16 v[12:15], v[150:153], v[146:149], v[12:15]
	v_mfma_f32_16x16x32_bf16 v[28:31], v[154:157], v[146:149], v[28:31]
	v_mfma_f32_16x16x32_bf16 v[44:47], v[158:161], v[146:149], v[44:47]
	v_mfma_f32_16x16x32_bf16 v[60:63], v[162:165], v[146:149], v[60:63]
	v_mul_f32_e32 v170, v98, v242
	v_mul_f32_e32 v171, v99, v243
	v_mul_f32_e32 v172, v100, v244
	v_mul_f32_e32 v173, v101, v245
	v_cvt_pk_bf16_f32 v174, v170, v171
	v_cvt_pk_bf16_f32 v175, v172, v173
	ds_write_b64 v188, v[174:175] offset:5120
	s_waitcnt vmcnt(10)
	ds_read_b64_tr_b16 v[150:151], v183 offset:4096
	ds_read_b64_tr_b16 v[152:153], v183 offset:4608
	ds_read_b64_tr_b16 v[154:155], v184 offset:4096
	ds_read_b64_tr_b16 v[156:157], v184 offset:4608
	ds_read_b64_tr_b16 v[158:159], v185 offset:4096
	ds_read_b64_tr_b16 v[160:161], v185 offset:4608
	ds_read_b64_tr_b16 v[162:163], v186 offset:4096
	ds_read_b64_tr_b16 v[164:165], v186 offset:4608
	s_add_i32 s41, s27, 1
	v_readlane_b32 s37, v236, s41
	s_cmp_lt_u32 s37, 32
	s_cbranch_scc0 .Lret_wctx_57
	s_lshl_b32 s100, s37, 6
	s_cmp_eq_u32 s37, s9
	s_cbranch_scc1 .Lret_wdiag_58
	s_cmp_lt_u32 s37, s9
	s_cselect_b32 s101, s11, s12
	v_subrev_u32_e32 v170, s100, v203
	v_subrev_u32_e32 v171, s100, v204
	v_subrev_u32_e32 v172, s100, v205
	v_subrev_u32_e32 v173, s100, v206
	v_cvt_f32_i32_e32 v174, v170
	v_cvt_f32_i32_e32 v175, v171
	v_cvt_f32_i32_e32 v176, v172
	v_cvt_f32_i32_e32 v177, v173
	v_mul_f32_e64 v178, s101, |v174|
	v_mul_f32_e64 v179, s101, |v175|
	v_mul_f32_e64 v180, s101, |v176|
	v_mul_f32_e64 v181, s101, |v177|
	v_exp_f32_e32 v166, v178
	v_exp_f32_e32 v167, v179
	v_exp_f32_e32 v168, v180
	v_exp_f32_e32 v169, v181
	s_branch .Lret_wdone_59

; #define RET_BAR() do { asm volatile("s_waitcnt lgkmcnt(0)" ::: "memory"); __builtin_amdgcn_s_barrier(); asm volatile("" ::: "memory"); } while (0)
; __device__ __forceinline__ void ret_unit(ldsp lds, bf16_t* R, const bf16_t* RC, int b, int h, int qblk, float lgf2, float lgb2, const int tid_in) {
;     ...
;     for (int t = 0; t < 36; ++t) {
;         int tl_ = tid_outer; asm volatile("" : "+v"(tl_));
;         const int tid = tl_, lane = tid & 63, l15 = lane & 15, lg = lane >> 4;
;         if (wid < 4) { RET_PV(t); if (t + 1 < 36) RET_S(t + 1, TI(t + 1)); }
;         else { if (t + 1 < 36) RET_S(t + 1, TI(t + 1)); RET_PV(t); }
;         RET_BAR();
.Lret_regJ_72:
	s_barrier
	s_cmp_eq_u32 s38, 0
	s_cbranch_scc0 .Lret_regY_79
	ds_read_b128 v[102:105], v182 offset:16384
	ds_read_b128 v[106:109], v246 offset:16384
	ds_read_b128 v[110:113], v247 offset:16384
	ds_read_b128 v[114:117], v248 offset:16384
	ds_read_b128 v[118:121], v182 offset:16640
	ds_read_b128 v[122:125], v246 offset:16640
	ds_read_b128 v[126:129], v247 offset:16640
	ds_read_b128 v[130:133], v248 offset:16640
	ds_read_b128 v[134:137], v187 offset:5120
	ds_read_b128 v[138:141], v187 offset:6400
	ds_read_b128 v[142:145], v187 offset:7680
	ds_read_b128 v[146:149], v187 offset:8960
	s_waitcnt lgkmcnt(11)
	v_mfma_f32_16x16x32_bf16 v[98:101], v[102:105], v[64:67], 0
	s_waitcnt lgkmcnt(10)
	v_mfma_f32_16x16x32_bf16 v[98:101], v[106:109], v[68:71], v[98:101]
	s_waitcnt lgkmcnt(9)
	v_mfma_f32_16x16x32_bf16 v[98:101], v[110:113], v[72:75], v[98:101]
	s_waitcnt lgkmcnt(8)
	v_mfma_f32_16x16x32_bf16 v[98:101], v[114:117], v[76:79], v[98:101]
	s_waitcnt lgkmcnt(7)
	v_mfma_f32_16x16x32_bf16 v[98:101], v[118:121], v[80:83], v[98:101]
	s_waitcnt lgkmcnt(6)
	v_mfma_f32_16x16x32_bf16 v[98:101], v[122:125], v[84:87], v[98:101]
	s_waitcnt lgkmcnt(5)
	v_mfma_f32_16x16x32_bf16 v[98:101], v[126:129], v[88:91], v[98:101]
	s_waitcnt lgkmcnt(4)
	v_mfma_f32_16x16x32_bf16 v[98:101], v[130:133], v[92:95], v[98:101]
	s_waitcnt lgkmcnt(0)
	v_mfma_f32_16x16x32_bf16 v[0:3], v[150:153], v[134:137], v[0:3]
	v_mfma_f32_16x16x32_bf16 v[16:19], v[154:157], v[134:137], v[16:19]
	v_mfma_f32_16x16x32_bf16 v[32:35], v[158:161], v[134:137], v[32:35]
	v_mfma_f32_16x16x32_bf16 v[48:51], v[162:165], v[134:137], v[48:51]
	v_mfma_f32_16x16x32_bf16 v[4:7], v[150:153], v[138:141], v[4:7]
	v_mfma_f32_16x16x32_bf16 v[20:23], v[154:157], v[138:141], v[20:23]
	v_mfma_f32_16x16x32_bf16 v[36:39], v[158:161], v[138:141], v[36:39]
	v_mfma_f32_16x16x32_bf16 v[52:55], v[162:165], v[138:141], v[52:55]
	v_mfma_f32_16x16x32_bf16 v[8:11], v[150:153], v[142:145], v[8:11]
	v_mfma_f32_16x16x32_bf16 v[24:27], v[154:157], v[142:145], v[24:27]
	v_mfma_f32_16x16x32_bf16 v[40:43], v[158:161], v[142:145], v[40:43]
	v_mfma_f32_16x16x32_bf16 v[56:59], v[162:165], v[142:145], v[56:59]
	v_mfma_f32_16x16x32_bf16 v[12:15], v[150:153], v[146:149], v[12:15]
	v_mfma_f32_16x16x32_bf16 v[28:31], v[154:157], v[146:149], v[28:31]
	v_mfma_f32_16x16x32_bf16 v[44:47], v[158:161], v[146:149], v[44:47]
	v_mfma_f32_16x16x32_bf16 v[60:63], v[162:165], v[146:149], v[60:63]
	v_mul_f32_e32 v170, v98, v166
	v_mul_f32_e32 v171, v99, v167
	v_mul_f32_e32 v172, v100, v168
	v_mul_f32_e32 v173, v101, v169
	v_cvt_pk_bf16_f32 v174, v170, v171
	v_cvt_pk_bf16_f32 v175, v172, v173
	ds_write_b64 v188, v[174:175] offset:0
	s_waitcnt vmcnt(4)
	ds_read_b64_tr_b16 v[150:151], v183 offset:4096
	ds_read_b64_tr_b16 v[152:153], v183 offset:4608
	ds_read_b64_tr_b16 v[154:155], v184 offset:4096
	ds_read_b64_tr_b16 v[156:157], v184 offset:4608
	ds_read_b64_tr_b16 v[158:159], v185 offset:4096
	ds_read_b64_tr_b16 v[160:161], v185 offset:4608
	ds_read_b64_tr_b16 v[162:163], v186 offset:4096
	ds_read_b64_tr_b16 v[164:165], v186 offset:4608
	s_add_i32 s41, s27, 2
	v_readlane_b32 s37, v236, s41
	s_cmp_lt_u32 s37, 32
	s_cbranch_scc0 .Lret_wctx_81
	s_lshl_b32 s100, s37, 6
	s_add_i32 s100, s100, 32
	s_cmp_eq_u32 s37, s9
	s_cbranch_scc1 .Lret_wdiag_82
	s_cmp_lt_u32 s37, s9
	s_cselect_b32 s101, s11, s12
	v_subrev_u32_e32 v170, s100, v203
	v_subrev_u32_e32 v171, s100, v204
	v_subrev_u32_e32 v172, s100, v205
	v_subrev_u32_e32 v173, s100, v206
	v_cvt_f32_i32_e32 v174, v170
	v_cvt_f32_i32_e32 v175, v171
	v_cvt_f32_i32_e32 v176, v172
	v_cvt_f32_i32_e32 v177, v173
	v_mul_f32_e64 v178, s101, |v174|
	v_mul_f32_e64 v179, s101, |v175|
	v_mul_f32_e64 v180, s101, |v176|
	v_mul_f32_e64 v181, s101, |v177|
	v_exp_f32_e32 v242, v178
	v_exp_f32_e32 v243, v179
	v_exp_f32_e32 v244, v180
	v_exp_f32_e32 v245, v181
	s_branch .Lret_wdone_83

; #define RET_BAR() do { asm volatile("s_waitcnt lgkmcnt(0)" ::: "memory"); __builtin_amdgcn_s_barrier(); asm volatile("" ::: "memory"); } while (0)
; __device__ __forceinline__ void ret_unit(ldsp lds, bf16_t* R, const bf16_t* RC, int b, int h, int qblk, float lgf2, float lgb2, const int tid_in) {
;     ...
;     for (int t = 0; t < 36; ++t) {
;         int tl_ = tid_outer; asm volatile("" : "+v"(tl_));
;         const int tid = tl_, lane = tid & 63, l15 = lane & 15, lg = lane >> 4;
;         if (wid < 4) { RET_PV(t); if (t + 1 < 36) RET_S(t + 1, TI(t + 1)); }
;         else { if (t + 1 < 36) RET_S(t + 1, TI(t + 1)); RET_PV(t); }
;         RET_BAR();
.Lret_regY_79:
	ds_read_b128 v[134:137], v187 offset:5120
	ds_read_b128 v[138:141], v187 offset:6400
	ds_read_b128 v[142:145], v187 offset:7680
	ds_read_b128 v[146:149], v187 offset:8960
	ds_read_b128 v[102:105], v182 offset:16384
	ds_read_b128 v[106:109], v246 offset:16384
	ds_read_b128 v[110:113], v247 offset:16384
	ds_read_b128 v[114:117], v248 offset:16384
	ds_read_b128 v[118:121], v182 offset:16640
	ds_read_b128 v[122:125], v246 offset:16640
	ds_read_b128 v[126:129], v247 offset:16640
	ds_read_b128 v[130:133], v248 offset:16640
	s_waitcnt lgkmcnt(8)
	v_mfma_f32_16x16x32_bf16 v[0:3], v[150:153], v[134:137], v[0:3]
	v_mfma_f32_16x16x32_bf16 v[16:19], v[154:157], v[134:137], v[16:19]
	v_mfma_f32_16x16x32_bf16 v[32:35], v[158:161], v[134:137], v[32:35]
	v_mfma_f32_16x16x32_bf16 v[48:51], v[162:165], v[134:137], v[48:51]
	v_mfma_f32_16x16x32_bf16 v[4:7], v[150:153], v[138:141], v[4:7]
	v_mfma_f32_16x16x32_bf16 v[20:23], v[154:157], v[138:141], v[20:23]
	v_mfma_f32_16x16x32_bf16 v[36:39], v[158:161], v[138:141], v[36:39]
	v_mfma_f32_16x16x32_bf16 v[52:55], v[162:165], v[138:141], v[52:55]
	v_mfma_f32_16x16x32_bf16 v[8:11], v[150:153], v[142:145], v[8:11]
	v_mfma_f32_16x16x32_bf16 v[24:27], v[154:157], v[142:145], v[24:27]
	v_mfma_f32_16x16x32_bf16 v[40:43], v[158:161], v[142:145], v[40:43]
	v_mfma_f32_16x16x32_bf16 v[56:59], v[162:165], v[142:145], v[56:59]
	v_mfma_f32_16x16x32_bf16 v[12:15], v[150:153], v[146:149], v[12:15]
	v_mfma_f32_16x16x32_bf16 v[28:31], v[154:157], v[146:149], v[28:31]
	v_mfma_f32_16x16x32_bf16 v[44:47], v[158:161], v[146:149], v[44:47]
	v_mfma_f32_16x16x32_bf16 v[60:63], v[162:165], v[146:149], v[60:63]
	s_waitcnt lgkmcnt(7)
	v_mfma_f32_16x16x32_bf16 v[98:101], v[102:105], v[64:67], 0
	s_waitcnt lgkmcnt(6)
	v_mfma_f32_16x16x32_bf16 v[98:101], v[106:109], v[68:71], v[98:101]
	s_waitcnt lgkmcnt(5)
	v_mfma_f32_16x16x32_bf16 v[98:101], v[110:113], v[72:75], v[98:101]
	s_waitcnt lgkmcnt(4)
	v_mfma_f32_16x16x32_bf16 v[98:101], v[114:117], v[76:79], v[98:101]
	s_waitcnt lgkmcnt(3)
	v_mfma_f32_16x16x32_bf16 v[98:101], v[118:121], v[80:83], v[98:101]
	s_waitcnt lgkmcnt(2)
	v_mfma_f32_16x16x32_bf16 v[98:101], v[122:125], v[84:87], v[98:101]
	s_waitcnt lgkmcnt(1)
	v_mfma_f32_16x16x32_bf16 v[98:101], v[126:129], v[88:91], v[98:101]
	s_waitcnt lgkmcnt(0)
	v_mfma_f32_16x16x32_bf16 v[98:101], v[130:133], v[92:95], v[98:101]
	s_add_i32 s41, s27, 2
	v_readlane_b32 s37, v236, s41
	s_cmp_lt_u32 s37, 32
	s_cbranch_scc0 .Lret_wctx_84
	s_lshl_b32 s100, s37, 6
	s_add_i32 s100, s100, 32
	s_cmp_eq_u32 s37, s9
	s_cbranch_scc1 .Lret_wdiag_85
	s_cmp_lt_u32 s37, s9
	s_cselect_b32 s101, s11, s12
	v_subrev_u32_e32 v170, s100, v203
	v_subrev_u32_e32 v171, s100, v204
	v_subrev_u32_e32 v172, s100, v205
	v_subrev_u32_e32 v173, s100, v206
	v_cvt_f32_i32_e32 v174, v170
	v_cvt_f32_i32_e32 v175, v171
	v_cvt_f32_i32_e32 v176, v172
	v_cvt_f32_i32_e32 v177, v173
	v_mul_f32_e64 v178, s101, |v174|
	v_mul_f32_e64 v179, s101, |v175|
	v_mul_f32_e64 v180, s101, |v176|
	v_mul_f32_e64 v181, s101, |v177|
	v_exp_f32_e32 v242, v178
	v_exp_f32_e32 v243, v179
	v_exp_f32_e32 v244, v180
	v_exp_f32_e32 v245, v181
	s_branch .Lret_wdone_86

; #define RET_BAR() do { asm volatile("s_waitcnt lgkmcnt(0)" ::: "memory"); __builtin_amdgcn_s_barrier(); asm volatile("" ::: "memory"); } while (0)
; __device__ __forceinline__ void ret_unit(ldsp lds, bf16_t* R, const bf16_t* RC, int b, int h, int qblk, float lgf2, float lgb2, const int tid_in) {
;     ...
;     for (int t = 0; t < 36; ++t) {
;         int tl_ = tid_outer; asm volatile("" : "+v"(tl_));
;         const int tid = tl_, lane = tid & 63, l15 = lane & 15, lg = lane >> 4;
;         if (wid < 4) { RET_PV(t); if (t + 1 < 36) RET_S(t + 1, TI(t + 1)); }
;         else { if (t + 1 < 36) RET_S(t + 1, TI(t + 1)); RET_PV(t); }
;         RET_BAR();
.Lret_wdone_86:
	v_mul_f32_e32 v170, v98, v166
	v_mul_f32_e32 v171, v99, v167
	v_mul_f32_e32 v172, v100, v168
	v_mul_f32_e32 v173, v101, v169
	v_cvt_pk_bf16_f32 v174, v170, v171
	v_cvt_pk_bf16_f32 v175, v172, v173
	ds_write_b64 v188, v[174:175] offset:0
	s_waitcnt vmcnt(4)
	ds_read_b64_tr_b16 v[150:151], v183 offset:4096
	ds_read_b64_tr_b16 v[152:153], v183 offset:4608
	ds_read_b64_tr_b16 v[154:155], v184 offset:4096
	ds_read_b64_tr_b16 v[156:157], v184 offset:4608
	ds_read_b64_tr_b16 v[158:159], v185 offset:4096
	ds_read_b64_tr_b16 v[160:161], v185 offset:4608
	ds_read_b64_tr_b16 v[162:163], v186 offset:4096
	ds_read_b64_tr_b16 v[164:165], v186 offset:4608
	s_waitcnt lgkmcnt(8)
.Lret_regJ_80:
	s_barrier
	s_cmp_eq_u32 s38, 0
	s_cbranch_scc0 .Lret_regY_87
	ds_read_b128 v[102:105], v182 offset:32768
	ds_read_b128 v[106:109], v246 offset:32768
	ds_read_b128 v[110:113], v247 offset:32768
	ds_read_b128 v[114:117], v248 offset:32768
	ds_read_b128 v[118:121], v182 offset:33024
	ds_read_b128 v[122:125], v246 offset:33024
	ds_read_b128 v[126:129], v247 offset:33024
	ds_read_b128 v[130:133], v248 offset:33024
	ds_read_b128 v[134:137], v187 offset:0
	ds_read_b128 v[138:141], v187 offset:1280
	ds_read_b128 v[142:145], v187 offset:2560
	ds_read_b128 v[146:149], v187 offset:3840
	s_waitcnt lgkmcnt(11)
	v_mfma_f32_16x16x32_bf16 v[98:101], v[102:105], v[64:67], 0
	s_waitcnt lgkmcnt(10)
	v_mfma_f32_16x16x32_bf16 v[98:101], v[106:109], v[68:71], v[98:101]
	s_waitcnt lgkmcnt(9)
	v_mfma_f32_16x16x32_bf16 v[98:101], v[110:113], v[72:75], v[98:101]
	s_waitcnt lgkmcnt(8)
	v_mfma_f32_16x16x32_bf16 v[98:101], v[114:117], v[76:79], v[98:101]
	s_waitcnt lgkmcnt(7)
	v_mfma_f32_16x16x32_bf16 v[98:101], v[118:121], v[80:83], v[98:101]
	s_waitcnt lgkmcnt(6)
	v_mfma_f32_16x16x32_bf16 v[98:101], v[122:125], v[84:87], v[98:101]
	s_waitcnt lgkmcnt(5)
	v_mfma_f32_16x16x32_bf16 v[98:101], v[126:129], v[88:91], v[98:101]
	s_waitcnt lgkmcnt(4)
	v_mfma_f32_16x16x32_bf16 v[98:101], v[130:133], v[92:95], v[98:101]
	s_waitcnt lgkmcnt(0)
	v_mfma_f32_16x16x32_bf16 v[0:3], v[150:153], v[134:137], v[0:3]
	v_mfma_f32_16x16x32_bf16 v[16:19], v[154:157], v[134:137], v[16:19]
	v_mfma_f32_16x16x32_bf16 v[32:35], v[158:161], v[134:137], v[32:35]
	v_mfma_f32_16x16x32_bf16 v[48:51], v[162:165], v[134:137], v[48:51]
	v_mfma_f32_16x16x32_bf16 v[4:7], v[150:153], v[138:141], v[4:7]
	v_mfma_f32_16x16x32_bf16 v[20:23], v[154:157], v[138:141], v[20:23]
	v_mfma_f32_16x16x32_bf16 v[36:39], v[158:161], v[138:141], v[36:39]
	v_mfma_f32_16x16x32_bf16 v[52:55], v[162:165], v[138:141], v[52:55]
	v_mfma_f32_16x16x32_bf16 v[8:11], v[150:153], v[142:145], v[8:11]
	v_mfma_f32_16x16x32_bf16 v[24:27], v[154:157], v[142:145], v[24:27]
	v_mfma_f32_16x16x32_bf16 v[40:43], v[158:161], v[142:145], v[40:43]
	v_mfma_f32_16x16x32_bf16 v[56:59], v[162:165], v[142:145], v[56:59]
	v_mfma_f32_16x16x32_bf16 v[12:15], v[150:153], v[146:149], v[12:15]
	v_mfma_f32_16x16x32_bf16 v[28:31], v[154:157], v[146:149], v[28:31]
	v_mfma_f32_16x16x32_bf16 v[44:47], v[158:161], v[146:149], v[44:47]
	v_mfma_f32_16x16x32_bf16 v[60:63], v[162:165], v[146:149], v[60:63]
	v_mul_f32_e32 v170, v98, v242
	v_mul_f32_e32 v171, v99, v243
	v_mul_f32_e32 v172, v100, v244
	v_mul_f32_e32 v173, v101, v245
	v_cvt_pk_bf16_f32 v174, v170, v171
	v_cvt_pk_bf16_f32 v175, v172, v173
	ds_write_b64 v188, v[174:175] offset:5120
	s_waitcnt vmcnt(0)
	ds_read_b64_tr_b16 v[150:151], v183 offset:8192
	ds_read_b64_tr_b16 v[152:153], v183 offset:8704
	ds_read_b64_tr_b16 v[154:155], v184 offset:8192
	ds_read_b64_tr_b16 v[156:157], v184 offset:8704
	ds_read_b64_tr_b16 v[158:159], v185 offset:8192
	ds_read_b64_tr_b16 v[160:161], v185 offset:8704
	ds_read_b64_tr_b16 v[162:163], v186 offset:8192
	ds_read_b64_tr_b16 v[164:165], v186 offset:8704
	s_waitcnt lgkmcnt(8)
	s_branch .Lret_regJ_88
.Lret_regY_87:
	ds_read_b128 v[134:137], v187 offset:0
	ds_read_b128 v[138:141], v187 offset:1280
	ds_read_b128 v[142:145], v187 offset:2560
	ds_read_b128 v[146:149], v187 offset:3840
	ds_read_b128 v[102:105], v182 offset:32768
	ds_read_b128 v[106:109], v246 offset:32768
	ds_read_b128 v[110:113], v247 offset:32768
	ds_read_b128 v[114:117], v248 offset:32768
	ds_read_b128 v[118:121], v182 offset:33024
	ds_read_b128 v[122:125], v246 offset:33024
	ds_read_b128 v[126:129], v247 offset:33024
	ds_read_b128 v[130:133], v248 offset:33024
	s_waitcnt lgkmcnt(8)
	v_mfma_f32_16x16x32_bf16 v[0:3], v[150:153], v[134:137], v[0:3]
	v_mfma_f32_16x16x32_bf16 v[16:19], v[154:157], v[134:137], v[16:19]
	v_mfma_f32_16x16x32_bf16 v[32:35], v[158:161], v[134:137], v[32:35]
	v_mfma_f32_16x16x32_bf16 v[48:51], v[162:165], v[134:137], v[48:51]
	v_mfma_f32_16x16x32_bf16 v[4:7], v[150:153], v[138:141], v[4:7]
	v_mfma_f32_16x16x32_bf16 v[20:23], v[154:157], v[138:141], v[20:23]
	v_mfma_f32_16x16x32_bf16 v[36:39], v[158:161], v[138:141], v[36:39]
	v_mfma_f32_16x16x32_bf16 v[52:55], v[162:165], v[138:141], v[52:55]
	v_mfma_f32_16x16x32_bf16 v[8:11], v[150:153], v[142:145], v[8:11]
	v_mfma_f32_16x16x32_bf16 v[24:27], v[154:157], v[142:145], v[24:27]
	v_mfma_f32_16x16x32_bf16 v[40:43], v[158:161], v[142:145], v[40:43]
	v_mfma_f32_16x16x32_bf16 v[56:59], v[162:165], v[142:145], v[56:59]
	v_mfma_f32_16x16x32_bf16 v[12:15], v[150:153], v[146:149], v[12:15]
	v_mfma_f32_16x16x32_bf16 v[28:31], v[154:157], v[146:149], v[28:31]
	v_mfma_f32_16x16x32_bf16 v[44:47], v[158:161], v[146:149], v[44:47]
	v_mfma_f32_16x16x32_bf16 v[60:63], v[162:165], v[146:149], v[60:63]
	s_waitcnt lgkmcnt(7)
	v_mfma_f32_16x16x32_bf16 v[98:101], v[102:105], v[64:67], 0
	s_waitcnt lgkmcnt(6)
	v_mfma_f32_16x16x32_bf16 v[98:101], v[106:109], v[68:71], v[98:101]
	s_waitcnt lgkmcnt(5)
	v_mfma_f32_16x16x32_bf16 v[98:101], v[110:113], v[72:75], v[98:101]
	s_waitcnt lgkmcnt(4)
	v_mfma_f32_16x16x32_bf16 v[98:101], v[114:117], v[76:79], v[98:101]
	s_waitcnt lgkmcnt(3)
	v_mfma_f32_16x16x32_bf16 v[98:101], v[118:121], v[80:83], v[98:101]
	s_waitcnt lgkmcnt(2)
	v_mfma_f32_16x16x32_bf16 v[98:101], v[122:125], v[84:87], v[98:101]
	s_waitcnt lgkmcnt(1)
	v_mfma_f32_16x16x32_bf16 v[98:101], v[126:129], v[88:91], v[98:101]
	s_waitcnt lgkmcnt(0)
	v_mfma_f32_16x16x32_bf16 v[98:101], v[130:133], v[92:95], v[98:101]
	s_nop 7
	v_mul_f32_e32 v170, v98, v242
	v_mul_f32_e32 v171, v99, v243
	v_mul_f32_e32 v172, v100, v244
	v_mul_f32_e32 v173, v101, v245
	v_cvt_pk_bf16_f32 v174, v170, v171
	v_cvt_pk_bf16_f32 v175, v172, v173
	ds_write_b64 v188, v[174:175] offset:5120
	s_waitcnt vmcnt(0)
	ds_read_b64_tr_b16 v[150:151], v183 offset:8192
	ds_read_b64_tr_b16 v[152:153], v183 offset:8704
	ds_read_b64_tr_b16 v[154:155], v184 offset:8192
	ds_read_b64_tr_b16 v[156:157], v184 offset:8704
	ds_read_b64_tr_b16 v[158:159], v185 offset:8192
	ds_read_b64_tr_b16 v[160:161], v185 offset:8704
	ds_read_b64_tr_b16 v[162:163], v186 offset:8192
	ds_read_b64_tr_b16 v[164:165], v186 offset:8704
	s_waitcnt lgkmcnt(8)
; #define LAS __attribute__((address_space(3)))
; #define RET_BAR() do { asm volatile("s_waitcnt lgkmcnt(0)" ::: "memory"); __builtin_amdgcn_s_barrier(); asm volatile("" ::: "memory"); } while (0)
; __device__ __forceinline__ void ret_unit(ldsp lds, bf16_t* R, const bf16_t* RC, int b, int h, int qblk, float lgf2, float lgb2, const int tid_in) {
;     ...
;     for (int t = 0; t < 36; ++t) {
;         int tl_ = tid_outer; asm volatile("" : "+v"(tl_));
;         const int tid = tl_, lane = tid & 63, l15 = lane & 15, lg = lane >> 4;
;         if (wid < 4) { RET_PV(t); if (t + 1 < 36) RET_S(t + 1, TI(t + 1)); }
;         else { if (t + 1 < 36) RET_S(t + 1, TI(t + 1)); RET_PV(t); }
;         RET_BAR();
;     ...
;     const int lane = tid_outer & 63, l15 = lane & 15, lg = lane >> 4;
;     LAS float* red = (LAS float*)Ps;
; #pragma unroll
;     for (int q4 = 0; q4 < 4; ++q4) {
;         float ss = 0.f;
; #pragma unroll
;         for (int db = 0; db < 4; ++db)
; #pragma unroll
;             for (int j = 0; j < 4; ++j) ss += o[db][q4][j] * o[db][q4][j];
;         ss += __shfl_xor(ss, 16); ss += __shfl_xor(ss, 32);
;         if (lg == 0) red[wid * 64 + 16 * q4 + l15] = ss;
;     }
;     RET_BAR();
.Lret_regJ_88:
	s_barrier
	ds_read_b128 v[134:137], v187 offset:5120
	ds_read_b128 v[138:141], v187 offset:6400
	ds_read_b128 v[142:145], v187 offset:7680
	ds_read_b128 v[146:149], v187 offset:8960
	s_waitcnt lgkmcnt(0)
	v_mfma_f32_16x16x32_bf16 v[0:3], v[150:153], v[134:137], v[0:3]
	v_mfma_f32_16x16x32_bf16 v[16:19], v[154:157], v[134:137], v[16:19]
	v_mfma_f32_16x16x32_bf16 v[32:35], v[158:161], v[134:137], v[32:35]
	v_mfma_f32_16x16x32_bf16 v[48:51], v[162:165], v[134:137], v[48:51]
	v_mfma_f32_16x16x32_bf16 v[4:7], v[150:153], v[138:141], v[4:7]
	v_mfma_f32_16x16x32_bf16 v[20:23], v[154:157], v[138:141], v[20:23]
	v_mfma_f32_16x16x32_bf16 v[36:39], v[158:161], v[138:141], v[36:39]
	v_mfma_f32_16x16x32_bf16 v[52:55], v[162:165], v[138:141], v[52:55]
	v_mfma_f32_16x16x32_bf16 v[8:11], v[150:153], v[142:145], v[8:11]
	v_mfma_f32_16x16x32_bf16 v[24:27], v[154:157], v[142:145], v[24:27]
	v_mfma_f32_16x16x32_bf16 v[40:43], v[158:161], v[142:145], v[40:43]
	v_mfma_f32_16x16x32_bf16 v[56:59], v[162:165], v[142:145], v[56:59]
	v_mfma_f32_16x16x32_bf16 v[12:15], v[150:153], v[146:149], v[12:15]
	v_mfma_f32_16x16x32_bf16 v[28:31], v[154:157], v[146:149], v[28:31]
	v_mfma_f32_16x16x32_bf16 v[44:47], v[158:161], v[146:149], v[44:47]
	v_mfma_f32_16x16x32_bf16 v[60:63], v[162:165], v[146:149], v[60:63]
	s_waitcnt lgkmcnt(0)
	s_barrier
	s_lshl_b32 s46, s7, 10
	s_mul_i32 s41, s13, 0x3000
	s_add_u32 s86, s22, s41
	s_addc_u32 s87, s23, 0
	s_add_u32 s86, s86, s46
	s_addc_u32 s87, s87, 0
	s_add_u32 s86, s86, 0x2000
	s_addc_u32 s87, s87, 0
	global_load_dwordx2 v[102:103], v226, s[86:87] offset:0
	global_load_dwordx2 v[104:105], v226, s[86:87] offset:32
	global_load_dwordx2 v[106:107], v226, s[86:87] offset:64
	global_load_dwordx2 v[108:109], v226, s[86:87] offset:96
	global_load_dwordx2 v[110:111], v227, s[86:87] offset:0
	global_load_dwordx2 v[112:113], v227, s[86:87] offset:32
	global_load_dwordx2 v[114:115], v227, s[86:87] offset:64
	global_load_dwordx2 v[116:117], v227, s[86:87] offset:96
	global_load_dwordx2 v[118:119], v228, s[86:87] offset:0
	global_load_dwordx2 v[120:121], v228, s[86:87] offset:32
	global_load_dwordx2 v[122:123], v228, s[86:87] offset:64
	global_load_dwordx2 v[124:125], v228, s[86:87] offset:96
	global_load_dwordx2 v[126:127], v229, s[86:87] offset:0
	global_load_dwordx2 v[128:129], v229, s[86:87] offset:32
	global_load_dwordx2 v[130:131], v229, s[86:87] offset:64
	global_load_dwordx2 v[132:133], v229, s[86:87] offset:96
	v_xor_b32_e32 v212, 16, v211
	v_lshlrev_b32_e32 v212, 2, v212
	v_xor_b32_e32 v213, 32, v211
	v_lshlrev_b32_e32 v213, 2, v213
	s_lshl_b32 s46, s10, 8
	v_lshl_add_u32 v214, v209, 2, s46
	v_cmp_gt_u32_e64 s[4:5], 16, v211
	v_mul_f32_e32 v230, v1, v1
	v_fmac_f32_e32 v230, v0, v0
	v_fmac_f32_e32 v230, v2, v2
	v_fmac_f32_e32 v230, v3, v3
	v_fmac_f32_e32 v230, v16, v16
	v_fmac_f32_e32 v230, v17, v17
	v_fmac_f32_e32 v230, v18, v18
	v_fmac_f32_e32 v230, v19, v19
	v_fmac_f32_e32 v230, v32, v32
	v_fmac_f32_e32 v230, v33, v33
	v_fmac_f32_e32 v230, v34, v34
	v_fmac_f32_e32 v230, v35, v35
	v_fmac_f32_e32 v230, v48, v48
	v_fmac_f32_e32 v230, v49, v49
	v_fmac_f32_e32 v230, v50, v50
	v_fmac_f32_e32 v230, v51, v51
	v_mul_f32_e32 v231, v5, v5
	v_fmac_f32_e32 v231, v4, v4
	v_fmac_f32_e32 v231, v6, v6
	v_fmac_f32_e32 v231, v7, v7
	v_fmac_f32_e32 v231, v20, v20
	v_fmac_f32_e32 v231, v21, v21
	v_fmac_f32_e32 v231, v22, v22
	v_fmac_f32_e32 v231, v23, v23
	v_fmac_f32_e32 v231, v36, v36
	v_fmac_f32_e32 v231, v37, v37
	v_fmac_f32_e32 v231, v38, v38
	v_fmac_f32_e32 v231, v39, v39
	v_fmac_f32_e32 v231, v52, v52
	v_fmac_f32_e32 v231, v53, v53
	v_fmac_f32_e32 v231, v54, v54
	v_fmac_f32_e32 v231, v55, v55
	v_mul_f32_e32 v232, v9, v9
	v_fmac_f32_e32 v232, v8, v8
	v_fmac_f32_e32 v232, v10, v10
	v_fmac_f32_e32 v232, v11, v11
	v_fmac_f32_e32 v232, v24, v24
	v_fmac_f32_e32 v232, v25, v25
	v_fmac_f32_e32 v232, v26, v26
	v_fmac_f32_e32 v232, v27, v27
	v_fmac_f32_e32 v232, v40, v40
	v_fmac_f32_e32 v232, v41, v41
	v_fmac_f32_e32 v232, v42, v42
	v_fmac_f32_e32 v232, v43, v43
	v_fmac_f32_e32 v232, v56, v56
	v_fmac_f32_e32 v232, v57, v57
	v_fmac_f32_e32 v232, v58, v58
	v_fmac_f32_e32 v232, v59, v59
	v_mul_f32_e32 v233, v13, v13
	v_fmac_f32_e32 v233, v12, v12
	v_fmac_f32_e32 v233, v14, v14
	v_fmac_f32_e32 v233, v15, v15
	v_fmac_f32_e32 v233, v28, v28
	v_fmac_f32_e32 v233, v29, v29
	v_fmac_f32_e32 v233, v30, v30
	v_fmac_f32_e32 v233, v31, v31
	v_fmac_f32_e32 v233, v44, v44
	v_fmac_f32_e32 v233, v45, v45
	v_fmac_f32_e32 v233, v46, v46
	v_fmac_f32_e32 v233, v47, v47
	v_fmac_f32_e32 v233, v60, v60
	v_fmac_f32_e32 v233, v61, v61
	v_fmac_f32_e32 v233, v62, v62
	v_fmac_f32_e32 v233, v63, v63
	ds_bpermute_b32 v234, v212, v230
	ds_bpermute_b32 v235, v212, v231
	ds_bpermute_b32 v236, v212, v232
	ds_bpermute_b32 v237, v212, v233
	s_waitcnt lgkmcnt(0)
	v_add_f32_e32 v230, v230, v234
	v_add_f32_e32 v231, v231, v235
	v_add_f32_e32 v232, v232, v236
	v_add_f32_e32 v233, v233, v237
	ds_bpermute_b32 v234, v213, v230
	ds_bpermute_b32 v235, v213, v231
	ds_bpermute_b32 v236, v213, v232
	ds_bpermute_b32 v237, v213, v233
	s_waitcnt lgkmcnt(0)
	v_add_f32_e32 v230, v230, v234
	v_add_f32_e32 v231, v231, v235
	v_add_f32_e32 v232, v232, v236
	v_add_f32_e32 v233, v233, v237
	s_mov_b64 s[42:43], exec
	s_and_b64 exec, exec, s[4:5]
	ds_write_b32 v214, v230 offset:0
	ds_write_b32 v214, v231 offset:64
	ds_write_b32 v214, v232 offset:128
	ds_write_b32 v214, v233 offset:192
	s_mov_b64 exec, s[42:43]
	s_waitcnt lgkmcnt(0)
	s_barrier
; __device__ __forceinline__ void ret_unit(ldsp lds, bf16_t* R, const bf16_t* RC, int b, int h, int qblk, float lgf2, float lgb2, const int tid_in) {
;     ...
; #pragma unroll
;     for (int q4 = 0; q4 < 4; ++q4) {
;         float tot = 0.f;
; #pragma unroll
;         for (int w = 0; w < 8; ++w) tot += red[w * 64 + 16 * q4 + l15];
;         const float rstd = 1.0f / sqrtf(tot * (1.f / 512.f) + EPS);
	v_lshlrev_b32_e32 v214, 2, v209
	ds_read_b32 v134, v214 offset:0
	ds_read_b32 v135, v214 offset:256
	ds_read_b32 v136, v214 offset:512
	ds_read_b32 v137, v214 offset:768
	ds_read_b32 v138, v214 offset:1024
	ds_read_b32 v139, v214 offset:1280
	ds_read_b32 v140, v214 offset:1536
	ds_read_b32 v141, v214 offset:1792
	ds_read_b32 v142, v214 offset:64
	ds_read_b32 v143, v214 offset:320
	ds_read_b32 v144, v214 offset:576
	ds_read_b32 v145, v214 offset:832
	ds_read_b32 v146, v214 offset:1088
	ds_read_b32 v147, v214 offset:1344
	ds_read_b32 v148, v214 offset:1600
	ds_read_b32 v149, v214 offset:1856
	ds_read_b32 v150, v214 offset:128
	ds_read_b32 v151, v214 offset:384
	ds_read_b32 v152, v214 offset:640
	ds_read_b32 v153, v214 offset:896
	ds_read_b32 v154, v214 offset:1152
	ds_read_b32 v155, v214 offset:1408
	ds_read_b32 v156, v214 offset:1664
	ds_read_b32 v157, v214 offset:1920
	ds_read_b32 v158, v214 offset:192
	ds_read_b32 v159, v214 offset:448
	ds_read_b32 v160, v214 offset:704
	ds_read_b32 v161, v214 offset:960
	ds_read_b32 v162, v214 offset:1216
	ds_read_b32 v163, v214 offset:1472
	ds_read_b32 v164, v214 offset:1728
	ds_read_b32 v165, v214 offset:1984
	s_waitcnt lgkmcnt(0)
	v_add_f32_e32 v230, 0, v134
	v_add_f32_e32 v230, v230, v135
	v_add_f32_e32 v230, v230, v136
	v_add_f32_e32 v230, v230, v137
	v_add_f32_e32 v230, v230, v138
	v_add_f32_e32 v230, v230, v139
	v_add_f32_e32 v230, v230, v140
	v_add_f32_e32 v230, v230, v141
	v_fmamk_f32 v230, v230, 0x3b000000, v221
	v_cmp_gt_f32_e32 vcc, s83, v230
	v_mul_f32_e32 v238, 0x4f800000, v230
	s_nop 0
	v_cndmask_b32_e32 v230, v230, v238, vcc
	v_sqrt_f32_e32 v238, v230
	s_nop 0
	v_add_u32_e32 v239, -1, v238
	v_fma_f32 v240, -v239, v238, v230
	v_cmp_ge_f32_e64 s[4:5], 0, v240
	v_add_u32_e32 v240, 1, v238
	s_nop 0
	v_cndmask_b32_e64 v239, v238, v239, s[4:5]
	v_fma_f32 v238, -v240, v238, v230
	v_cmp_lt_f32_e64 s[4:5], 0, v238
	s_nop 1
	v_cndmask_b32_e64 v238, v239, v240, s[4:5]
	v_mul_f32_e32 v239, 0x37800000, v238
	v_cndmask_b32_e32 v238, v238, v239, vcc
	v_cmp_class_f32_e32 vcc, v230, v222
	s_nop 1
	v_cndmask_b32_e32 v230, v238, v230, vcc
	v_div_scale_f32 v238, s[4:5], v230, v230, 1.0
	v_rcp_f32_e32 v239, v238
	s_nop 0
	v_fma_f32 v240, -v238, v239, 1.0
	v_fmac_f32_e32 v239, v240, v239
	v_div_scale_f32 v240, vcc, 1.0, v230, 1.0
	v_mul_f32_e32 v241, v240, v239
	v_fma_f32 v242, -v238, v241, v240
	v_fmac_f32_e32 v241, v242, v239
	v_fma_f32 v238, -v238, v241, v240
	s_nop 1
	v_div_fmas_f32 v238, v238, v239, v241
	v_div_fixup_f32 v250, v238, v230, 1.0
	v_add_f32_e32 v231, 0, v142
	v_add_f32_e32 v231, v231, v143
	v_add_f32_e32 v231, v231, v144
	v_add_f32_e32 v231, v231, v145
	v_add_f32_e32 v231, v231, v146
	v_add_f32_e32 v231, v231, v147
	v_add_f32_e32 v231, v231, v148
	v_add_f32_e32 v231, v231, v149
	v_fmamk_f32 v231, v231, 0x3b000000, v221
	v_cmp_gt_f32_e32 vcc, s83, v231
	v_mul_f32_e32 v238, 0x4f800000, v231
	s_nop 0
	v_cndmask_b32_e32 v231, v231, v238, vcc
	v_sqrt_f32_e32 v238, v231
	s_nop 0
	v_add_u32_e32 v239, -1, v238
	v_fma_f32 v240, -v239, v238, v231
	v_cmp_ge_f32_e64 s[4:5], 0, v240
	v_add_u32_e32 v240, 1, v238
	s_nop 0
	v_cndmask_b32_e64 v239, v238, v239, s[4:5]
	v_fma_f32 v238, -v240, v238, v231
	v_cmp_lt_f32_e64 s[4:5], 0, v238
	s_nop 1
	v_cndmask_b32_e64 v238, v239, v240, s[4:5]
	v_mul_f32_e32 v239, 0x37800000, v238
	v_cndmask_b32_e32 v238, v238, v239, vcc
	v_cmp_class_f32_e32 vcc, v231, v222
	s_nop 1
	v_cndmask_b32_e32 v231, v238, v231, vcc
	v_div_scale_f32 v238, s[4:5], v231, v231, 1.0
	v_rcp_f32_e32 v239, v238
	s_nop 0
	v_fma_f32 v240, -v238, v239, 1.0
	v_fmac_f32_e32 v239, v240, v239
	v_div_scale_f32 v240, vcc, 1.0, v231, 1.0
	v_mul_f32_e32 v241, v240, v239
	v_fma_f32 v242, -v238, v241, v240
	v_fmac_f32_e32 v241, v242, v239
	v_fma_f32 v238, -v238, v241, v240
	s_nop 1
	v_div_fmas_f32 v238, v238, v239, v241
	v_div_fixup_f32 v251, v238, v231, 1.0
	v_add_f32_e32 v232, 0, v150
	v_add_f32_e32 v232, v232, v151
	v_add_f32_e32 v232, v232, v152
	v_add_f32_e32 v232, v232, v153
	v_add_f32_e32 v232, v232, v154
	v_add_f32_e32 v232, v232, v155
	v_add_f32_e32 v232, v232, v156
	v_add_f32_e32 v232, v232, v157
	v_fmamk_f32 v232, v232, 0x3b000000, v221
	v_cmp_gt_f32_e32 vcc, s83, v232
	v_mul_f32_e32 v238, 0x4f800000, v232
	s_nop 0
	v_cndmask_b32_e32 v232, v232, v238, vcc
	v_sqrt_f32_e32 v238, v232
	s_nop 0
	v_add_u32_e32 v239, -1, v238
	v_fma_f32 v240, -v239, v238, v232
	v_cmp_ge_f32_e64 s[4:5], 0, v240
	v_add_u32_e32 v240, 1, v238
	s_nop 0
	v_cndmask_b32_e64 v239, v238, v239, s[4:5]
	v_fma_f32 v238, -v240, v238, v232
	v_cmp_lt_f32_e64 s[4:5], 0, v238
	s_nop 1
	v_cndmask_b32_e64 v238, v239, v240, s[4:5]
	v_mul_f32_e32 v239, 0x37800000, v238
	v_cndmask_b32_e32 v238, v238, v239, vcc
	v_cmp_class_f32_e32 vcc, v232, v222
	s_nop 1
	v_cndmask_b32_e32 v232, v238, v232, vcc
	v_div_scale_f32 v238, s[4:5], v232, v232, 1.0
	v_rcp_f32_e32 v239, v238
	s_nop 0
	v_fma_f32 v240, -v238, v239, 1.0
	v_fmac_f32_e32 v239, v240, v239
	v_div_scale_f32 v240, vcc, 1.0, v232, 1.0
	v_mul_f32_e32 v241, v240, v239
	v_fma_f32 v242, -v238, v241, v240
	v_fmac_f32_e32 v241, v242, v239
	v_fma_f32 v238, -v238, v241, v240
	s_nop 1
	v_div_fmas_f32 v238, v238, v239, v241
	v_div_fixup_f32 v252, v238, v232, 1.0
	v_add_f32_e32 v233, 0, v158
	v_add_f32_e32 v233, v233, v159
	v_add_f32_e32 v233, v233, v160
	v_add_f32_e32 v233, v233, v161
	v_add_f32_e32 v233, v233, v162
	v_add_f32_e32 v233, v233, v163
	v_add_f32_e32 v233, v233, v164
	v_add_f32_e32 v233, v233, v165
	v_fmamk_f32 v233, v233, 0x3b000000, v221
	v_cmp_gt_f32_e32 vcc, s83, v233
	v_mul_f32_e32 v238, 0x4f800000, v233
	s_nop 0
	v_cndmask_b32_e32 v233, v233, v238, vcc
	v_sqrt_f32_e32 v238, v233
	s_nop 0
	v_add_u32_e32 v239, -1, v238
	v_fma_f32 v240, -v239, v238, v233
	v_cmp_ge_f32_e64 s[4:5], 0, v240
	v_add_u32_e32 v240, 1, v238
	s_nop 0
	v_cndmask_b32_e64 v239, v238, v239, s[4:5]
	v_fma_f32 v238, -v240, v238, v233
	v_cmp_lt_f32_e64 s[4:5], 0, v238
	s_nop 1
	v_cndmask_b32_e64 v238, v239, v240, s[4:5]
	v_mul_f32_e32 v239, 0x37800000, v238
	v_cndmask_b32_e32 v238, v238, v239, vcc
	v_cmp_class_f32_e32 vcc, v233, v222
	s_nop 1
	v_cndmask_b32_e32 v233, v238, v233, vcc
	v_div_scale_f32 v238, s[4:5], v233, v233, 1.0
	v_rcp_f32_e32 v239, v238
	s_nop 0
	v_fma_f32 v240, -v238, v239, 1.0
	v_fmac_f32_e32 v239, v240, v239
	v_div_scale_f32 v240, vcc, 1.0, v233, 1.0
	v_mul_f32_e32 v241, v240, v239
	v_fma_f32 v242, -v238, v241, v240
	v_fmac_f32_e32 v241, v242, v239
	v_fma_f32 v238, -v238, v241, v240
	s_nop 1
	v_div_fmas_f32 v238, v238, v239, v241
	v_div_fixup_f32 v253, v238, v233, 1.0
	s_waitcnt vmcnt(0)
; __device__ __forceinline__ unsigned cvt_pk_bf16(float lo, float hi) { unsigned r; asm volatile("v_cvt_pk_bf16_f32 %0, %1, %2" : "=v"(r) : "v"(lo), "v"(hi)); return r; }
; __device__ __forceinline__ float bflo(unsigned w) { return __uint_as_float(w << 16); }
; __device__ __forceinline__ float bfhi(unsigned w) { return __uint_as_float(w & 0xffff0000u); }
; __device__ __forceinline__ float silu_f(float x) { return x * __builtin_amdgcn_rcpf(1.0f + __builtin_amdgcn_exp2f(x * -1.4426950408889634f)); }
; __device__ __forceinline__ void ret_unit(ldsp lds, bf16_t* R, const bf16_t* RC, int b, int h, int qblk, float lgf2, float lgb2, const int tid_in) {
;     ...
;         bf16_t* gp = R + (size_t)(rowq0 + 16 * q4 + l15) * 6144 + 4096 + h * 512 + 64 * wid + 4 * lg;
; #pragma unroll
;         for (int db = 0; db < 4; ++db) { const u32x2 g2 = *(const u32x2*)(gp + 16 * db);
;             u32x2 w; w.x = cvt_pk_bf16(o[db][q4][0] * rstd * silu_f(bflo(g2.x)), o[db][q4][1] * rstd * silu_f(bfhi(g2.x)));
;             w.y = cvt_pk_bf16(o[db][q4][2] * rstd * silu_f(bflo(g2.y)), o[db][q4][3] * rstd * silu_f(bfhi(g2.y)));
;             *(u32x2*)(gp + 16 * db) = w; }
	v_lshlrev_b32_e32 v238, 16, v102
	v_and_b32_e32 v239, 0xffff0000, v102
	v_lshlrev_b32_e32 v240, 16, v103
	v_and_b32_e32 v241, 0xffff0000, v103
	v_mul_f32_e32 v242, 0xbfb8aa3b, v238
	v_mul_f32_e32 v243, 0xbfb8aa3b, v239
	v_mul_f32_e32 v244, 0xbfb8aa3b, v240
	v_mul_f32_e32 v245, 0xbfb8aa3b, v241
	v_exp_f32_e32 v242, v242
	v_exp_f32_e32 v243, v243
	v_exp_f32_e32 v244, v244
	v_exp_f32_e32 v245, v245
	s_nop 0
	v_add_f32_e32 v242, 1.0, v242
	v_add_f32_e32 v243, 1.0, v243
	v_add_f32_e32 v244, 1.0, v244
	v_add_f32_e32 v245, 1.0, v245
	v_rcp_f32_e32 v242, v242
	v_rcp_f32_e32 v243, v243
	v_rcp_f32_e32 v244, v244
	v_rcp_f32_e32 v245, v245
	s_nop 0
	v_mul_f32_e32 v242, v242, v238
	v_mul_f32_e32 v243, v243, v239
	v_mul_f32_e32 v244, v244, v240
	v_mul_f32_e32 v245, v245, v241
	v_mul_f32_e32 v238, v0, v250
	v_mul_f32_e32 v239, v1, v250
	v_mul_f32_e32 v240, v2, v250
	v_mul_f32_e32 v241, v3, v250
	v_mul_f32_e32 v238, v238, v242
	v_mul_f32_e32 v239, v239, v243
	v_mul_f32_e32 v240, v240, v244
	v_mul_f32_e32 v241, v241, v245
	v_cvt_pk_bf16_f32 v102, v238, v239
	v_cvt_pk_bf16_f32 v103, v240, v241
	global_store_dwordx2 v226, v[102:103], s[86:87] offset:0
	v_lshlrev_b32_e32 v238, 16, v104
	v_and_b32_e32 v239, 0xffff0000, v104
	v_lshlrev_b32_e32 v240, 16, v105
	v_and_b32_e32 v241, 0xffff0000, v105
	v_mul_f32_e32 v242, 0xbfb8aa3b, v238
	v_mul_f32_e32 v243, 0xbfb8aa3b, v239
	v_mul_f32_e32 v244, 0xbfb8aa3b, v240
	v_mul_f32_e32 v245, 0xbfb8aa3b, v241
	v_exp_f32_e32 v242, v242
	v_exp_f32_e32 v243, v243
	v_exp_f32_e32 v244, v244
	v_exp_f32_e32 v245, v245
	s_nop 0
	v_add_f32_e32 v242, 1.0, v242
	v_add_f32_e32 v243, 1.0, v243
	v_add_f32_e32 v244, 1.0, v244
	v_add_f32_e32 v245, 1.0, v245
	v_rcp_f32_e32 v242, v242
	v_rcp_f32_e32 v243, v243
	v_rcp_f32_e32 v244, v244
	v_rcp_f32_e32 v245, v245
	s_nop 0
	v_mul_f32_e32 v242, v242, v238
	v_mul_f32_e32 v243, v243, v239
	v_mul_f32_e32 v244, v244, v240
	v_mul_f32_e32 v245, v245, v241
	v_mul_f32_e32 v238, v16, v250
	v_mul_f32_e32 v239, v17, v250
	v_mul_f32_e32 v240, v18, v250
	v_mul_f32_e32 v241, v19, v250
	v_mul_f32_e32 v238, v238, v242
	v_mul_f32_e32 v239, v239, v243
	v_mul_f32_e32 v240, v240, v244
	v_mul_f32_e32 v241, v241, v245
	v_cvt_pk_bf16_f32 v104, v238, v239
	v_cvt_pk_bf16_f32 v105, v240, v241
	global_store_dwordx2 v226, v[104:105], s[86:87] offset:32
	v_lshlrev_b32_e32 v238, 16, v106
	v_and_b32_e32 v239, 0xffff0000, v106
	v_lshlrev_b32_e32 v240, 16, v107
	v_and_b32_e32 v241, 0xffff0000, v107
	v_mul_f32_e32 v242, 0xbfb8aa3b, v238
	v_mul_f32_e32 v243, 0xbfb8aa3b, v239
	v_mul_f32_e32 v244, 0xbfb8aa3b, v240
	v_mul_f32_e32 v245, 0xbfb8aa3b, v241
	v_exp_f32_e32 v242, v242
	v_exp_f32_e32 v243, v243
	v_exp_f32_e32 v244, v244
	v_exp_f32_e32 v245, v245
	s_nop 0
	v_add_f32_e32 v242, 1.0, v242
	v_add_f32_e32 v243, 1.0, v243
	v_add_f32_e32 v244, 1.0, v244
	v_add_f32_e32 v245, 1.0, v245
	v_rcp_f32_e32 v242, v242
	v_rcp_f32_e32 v243, v243
	v_rcp_f32_e32 v244, v244
	v_rcp_f32_e32 v245, v245
	s_nop 0
	v_mul_f32_e32 v242, v242, v238
	v_mul_f32_e32 v243, v243, v239
	v_mul_f32_e32 v244, v244, v240
	v_mul_f32_e32 v245, v245, v241
	v_mul_f32_e32 v238, v32, v250
	v_mul_f32_e32 v239, v33, v250
	v_mul_f32_e32 v240, v34, v250
	v_mul_f32_e32 v241, v35, v250
	v_mul_f32_e32 v238, v238, v242
	v_mul_f32_e32 v239, v239, v243
	v_mul_f32_e32 v240, v240, v244
	v_mul_f32_e32 v241, v241, v245
	v_cvt_pk_bf16_f32 v106, v238, v239
	v_cvt_pk_bf16_f32 v107, v240, v241
	global_store_dwordx2 v226, v[106:107], s[86:87] offset:64
	v_lshlrev_b32_e32 v238, 16, v108
	v_and_b32_e32 v239, 0xffff0000, v108
	v_lshlrev_b32_e32 v240, 16, v109
	v_and_b32_e32 v241, 0xffff0000, v109
	v_mul_f32_e32 v242, 0xbfb8aa3b, v238
	v_mul_f32_e32 v243, 0xbfb8aa3b, v239
	v_mul_f32_e32 v244, 0xbfb8aa3b, v240
	v_mul_f32_e32 v245, 0xbfb8aa3b, v241
	v_exp_f32_e32 v242, v242
	v_exp_f32_e32 v243, v243
	v_exp_f32_e32 v244, v244
	v_exp_f32_e32 v245, v245
	s_nop 0
	v_add_f32_e32 v242, 1.0, v242
	v_add_f32_e32 v243, 1.0, v243
	v_add_f32_e32 v244, 1.0, v244
	v_add_f32_e32 v245, 1.0, v245
	v_rcp_f32_e32 v242, v242
	v_rcp_f32_e32 v243, v243
	v_rcp_f32_e32 v244, v244
	v_rcp_f32_e32 v245, v245
	s_nop 0
	v_mul_f32_e32 v242, v242, v238
	v_mul_f32_e32 v243, v243, v239
	v_mul_f32_e32 v244, v244, v240
	v_mul_f32_e32 v245, v245, v241
	v_mul_f32_e32 v238, v48, v250
	v_mul_f32_e32 v239, v49, v250
	v_mul_f32_e32 v240, v50, v250
	v_mul_f32_e32 v241, v51, v250
	v_mul_f32_e32 v238, v238, v242
	v_mul_f32_e32 v239, v239, v243
	v_mul_f32_e32 v240, v240, v244
	v_mul_f32_e32 v241, v241, v245
	v_cvt_pk_bf16_f32 v108, v238, v239
	v_cvt_pk_bf16_f32 v109, v240, v241
	global_store_dwordx2 v226, v[108:109], s[86:87] offset:96
	v_lshlrev_b32_e32 v238, 16, v110
	v_and_b32_e32 v239, 0xffff0000, v110
	v_lshlrev_b32_e32 v240, 16, v111
	v_and_b32_e32 v241, 0xffff0000, v111
	v_mul_f32_e32 v242, 0xbfb8aa3b, v238
	v_mul_f32_e32 v243, 0xbfb8aa3b, v239
	v_mul_f32_e32 v244, 0xbfb8aa3b, v240
	v_mul_f32_e32 v245, 0xbfb8aa3b, v241
	v_exp_f32_e32 v242, v242
	v_exp_f32_e32 v243, v243
	v_exp_f32_e32 v244, v244
	v_exp_f32_e32 v245, v245
	s_nop 0
	v_add_f32_e32 v242, 1.0, v242
	v_add_f32_e32 v243, 1.0, v243
	v_add_f32_e32 v244, 1.0, v244
	v_add_f32_e32 v245, 1.0, v245
	v_rcp_f32_e32 v242, v242
	v_rcp_f32_e32 v243, v243
	v_rcp_f32_e32 v244, v244
	v_rcp_f32_e32 v245, v245
	s_nop 0
	v_mul_f32_e32 v242, v242, v238
	v_mul_f32_e32 v243, v243, v239
	v_mul_f32_e32 v244, v244, v240
	v_mul_f32_e32 v245, v245, v241
	v_mul_f32_e32 v238, v4, v251
	v_mul_f32_e32 v239, v5, v251
	v_mul_f32_e32 v240, v6, v251
	v_mul_f32_e32 v241, v7, v251
	v_mul_f32_e32 v238, v238, v242
	v_mul_f32_e32 v239, v239, v243
	v_mul_f32_e32 v240, v240, v244
	v_mul_f32_e32 v241, v241, v245
; __device__ __forceinline__ unsigned cvt_pk_bf16(float lo, float hi) { unsigned r; asm volatile("v_cvt_pk_bf16_f32 %0, %1, %2" : "=v"(r) : "v"(lo), "v"(hi)); return r; }
; __device__ __forceinline__ float bflo(unsigned w) { return __uint_as_float(w << 16); }
; __device__ __forceinline__ float bfhi(unsigned w) { return __uint_as_float(w & 0xffff0000u); }
; __device__ __forceinline__ float silu_f(float x) { return x * __builtin_amdgcn_rcpf(1.0f + __builtin_amdgcn_exp2f(x * -1.4426950408889634f)); }
; __device__ __forceinline__ void ret_unit(ldsp lds, bf16_t* R, const bf16_t* RC, int b, int h, int qblk, float lgf2, float lgb2, const int tid_in) {
;     ...
; #pragma unroll
;         for (int db = 0; db < 4; ++db) { const u32x2 g2 = *(const u32x2*)(gp + 16 * db);
;             u32x2 w; w.x = cvt_pk_bf16(o[db][q4][0] * rstd * silu_f(bflo(g2.x)), o[db][q4][1] * rstd * silu_f(bfhi(g2.x)));
;             w.y = cvt_pk_bf16(o[db][q4][2] * rstd * silu_f(bflo(g2.y)), o[db][q4][3] * rstd * silu_f(bfhi(g2.y)));
;             *(u32x2*)(gp + 16 * db) = w; }
	v_cvt_pk_bf16_f32 v110, v238, v239
	v_cvt_pk_bf16_f32 v111, v240, v241
	global_store_dwordx2 v227, v[110:111], s[86:87] offset:0
	v_lshlrev_b32_e32 v238, 16, v112
	v_and_b32_e32 v239, 0xffff0000, v112
	v_lshlrev_b32_e32 v240, 16, v113
	v_and_b32_e32 v241, 0xffff0000, v113
	v_mul_f32_e32 v242, 0xbfb8aa3b, v238
	v_mul_f32_e32 v243, 0xbfb8aa3b, v239
	v_mul_f32_e32 v244, 0xbfb8aa3b, v240
	v_mul_f32_e32 v245, 0xbfb8aa3b, v241
	v_exp_f32_e32 v242, v242
	v_exp_f32_e32 v243, v243
	v_exp_f32_e32 v244, v244
	v_exp_f32_e32 v245, v245
	s_nop 0
	v_add_f32_e32 v242, 1.0, v242
	v_add_f32_e32 v243, 1.0, v243
	v_add_f32_e32 v244, 1.0, v244
	v_add_f32_e32 v245, 1.0, v245
	v_rcp_f32_e32 v242, v242
	v_rcp_f32_e32 v243, v243
	v_rcp_f32_e32 v244, v244
	v_rcp_f32_e32 v245, v245
	s_nop 0
	v_mul_f32_e32 v242, v242, v238
	v_mul_f32_e32 v243, v243, v239
	v_mul_f32_e32 v244, v244, v240
	v_mul_f32_e32 v245, v245, v241
	v_mul_f32_e32 v238, v20, v251
	v_mul_f32_e32 v239, v21, v251
	v_mul_f32_e32 v240, v22, v251
	v_mul_f32_e32 v241, v23, v251
	v_mul_f32_e32 v238, v238, v242
	v_mul_f32_e32 v239, v239, v243
	v_mul_f32_e32 v240, v240, v244
	v_mul_f32_e32 v241, v241, v245
	v_cvt_pk_bf16_f32 v112, v238, v239
	v_cvt_pk_bf16_f32 v113, v240, v241
	global_store_dwordx2 v227, v[112:113], s[86:87] offset:32
	v_lshlrev_b32_e32 v238, 16, v114
	v_and_b32_e32 v239, 0xffff0000, v114
	v_lshlrev_b32_e32 v240, 16, v115
	v_and_b32_e32 v241, 0xffff0000, v115
	v_mul_f32_e32 v242, 0xbfb8aa3b, v238
	v_mul_f32_e32 v243, 0xbfb8aa3b, v239
	v_mul_f32_e32 v244, 0xbfb8aa3b, v240
	v_mul_f32_e32 v245, 0xbfb8aa3b, v241
	v_exp_f32_e32 v242, v242
	v_exp_f32_e32 v243, v243
	v_exp_f32_e32 v244, v244
	v_exp_f32_e32 v245, v245
	s_nop 0
	v_add_f32_e32 v242, 1.0, v242
	v_add_f32_e32 v243, 1.0, v243
	v_add_f32_e32 v244, 1.0, v244
	v_add_f32_e32 v245, 1.0, v245
	v_rcp_f32_e32 v242, v242
	v_rcp_f32_e32 v243, v243
	v_rcp_f32_e32 v244, v244
	v_rcp_f32_e32 v245, v245
	s_nop 0
	v_mul_f32_e32 v242, v242, v238
	v_mul_f32_e32 v243, v243, v239
	v_mul_f32_e32 v244, v244, v240
	v_mul_f32_e32 v245, v245, v241
	v_mul_f32_e32 v238, v36, v251
	v_mul_f32_e32 v239, v37, v251
	v_mul_f32_e32 v240, v38, v251
	v_mul_f32_e32 v241, v39, v251
	v_mul_f32_e32 v238, v238, v242
	v_mul_f32_e32 v239, v239, v243
	v_mul_f32_e32 v240, v240, v244
	v_mul_f32_e32 v241, v241, v245
	v_cvt_pk_bf16_f32 v114, v238, v239
	v_cvt_pk_bf16_f32 v115, v240, v241
	global_store_dwordx2 v227, v[114:115], s[86:87] offset:64
	v_lshlrev_b32_e32 v238, 16, v116
	v_and_b32_e32 v239, 0xffff0000, v116
	v_lshlrev_b32_e32 v240, 16, v117
	v_and_b32_e32 v241, 0xffff0000, v117
	v_mul_f32_e32 v242, 0xbfb8aa3b, v238
	v_mul_f32_e32 v243, 0xbfb8aa3b, v239
	v_mul_f32_e32 v244, 0xbfb8aa3b, v240
	v_mul_f32_e32 v245, 0xbfb8aa3b, v241
	v_exp_f32_e32 v242, v242
	v_exp_f32_e32 v243, v243
	v_exp_f32_e32 v244, v244
	v_exp_f32_e32 v245, v245
	s_nop 0
	v_add_f32_e32 v242, 1.0, v242
	v_add_f32_e32 v243, 1.0, v243
	v_add_f32_e32 v244, 1.0, v244
	v_add_f32_e32 v245, 1.0, v245
	v_rcp_f32_e32 v242, v242
	v_rcp_f32_e32 v243, v243
	v_rcp_f32_e32 v244, v244
	v_rcp_f32_e32 v245, v245
	s_nop 0
	v_mul_f32_e32 v242, v242, v238
	v_mul_f32_e32 v243, v243, v239
	v_mul_f32_e32 v244, v244, v240
	v_mul_f32_e32 v245, v245, v241
	v_mul_f32_e32 v238, v52, v251
	v_mul_f32_e32 v239, v53, v251
	v_mul_f32_e32 v240, v54, v251
	v_mul_f32_e32 v241, v55, v251
	v_mul_f32_e32 v238, v238, v242
	v_mul_f32_e32 v239, v239, v243
	v_mul_f32_e32 v240, v240, v244
	v_mul_f32_e32 v241, v241, v245
	v_cvt_pk_bf16_f32 v116, v238, v239
	v_cvt_pk_bf16_f32 v117, v240, v241
	global_store_dwordx2 v227, v[116:117], s[86:87] offset:96
	v_lshlrev_b32_e32 v238, 16, v118
	v_and_b32_e32 v239, 0xffff0000, v118
	v_lshlrev_b32_e32 v240, 16, v119
	v_and_b32_e32 v241, 0xffff0000, v119
	v_mul_f32_e32 v242, 0xbfb8aa3b, v238
	v_mul_f32_e32 v243, 0xbfb8aa3b, v239
	v_mul_f32_e32 v244, 0xbfb8aa3b, v240
	v_mul_f32_e32 v245, 0xbfb8aa3b, v241
	v_exp_f32_e32 v242, v242
	v_exp_f32_e32 v243, v243
	v_exp_f32_e32 v244, v244
	v_exp_f32_e32 v245, v245
	s_nop 0
	v_add_f32_e32 v242, 1.0, v242
	v_add_f32_e32 v243, 1.0, v243
	v_add_f32_e32 v244, 1.0, v244
	v_add_f32_e32 v245, 1.0, v245
	v_rcp_f32_e32 v242, v242
	v_rcp_f32_e32 v243, v243
	v_rcp_f32_e32 v244, v244
	v_rcp_f32_e32 v245, v245
	s_nop 0
	v_mul_f32_e32 v242, v242, v238
	v_mul_f32_e32 v243, v243, v239
	v_mul_f32_e32 v244, v244, v240
	v_mul_f32_e32 v245, v245, v241
	v_mul_f32_e32 v238, v8, v252
	v_mul_f32_e32 v239, v9, v252
	v_mul_f32_e32 v240, v10, v252
	v_mul_f32_e32 v241, v11, v252
	v_mul_f32_e32 v238, v238, v242
	v_mul_f32_e32 v239, v239, v243
	v_mul_f32_e32 v240, v240, v244
	v_mul_f32_e32 v241, v241, v245
	v_cvt_pk_bf16_f32 v118, v238, v239
	v_cvt_pk_bf16_f32 v119, v240, v241
	global_store_dwordx2 v228, v[118:119], s[86:87] offset:0
	v_lshlrev_b32_e32 v238, 16, v120
	v_and_b32_e32 v239, 0xffff0000, v120
	v_lshlrev_b32_e32 v240, 16, v121
	v_and_b32_e32 v241, 0xffff0000, v121
	v_mul_f32_e32 v242, 0xbfb8aa3b, v238
	v_mul_f32_e32 v243, 0xbfb8aa3b, v239
	v_mul_f32_e32 v244, 0xbfb8aa3b, v240
	v_mul_f32_e32 v245, 0xbfb8aa3b, v241
	v_exp_f32_e32 v242, v242
	v_exp_f32_e32 v243, v243
	v_exp_f32_e32 v244, v244
	v_exp_f32_e32 v245, v245
	s_nop 0
	v_add_f32_e32 v242, 1.0, v242
	v_add_f32_e32 v243, 1.0, v243
	v_add_f32_e32 v244, 1.0, v244
	v_add_f32_e32 v245, 1.0, v245
	v_rcp_f32_e32 v242, v242
	v_rcp_f32_e32 v243, v243
	v_rcp_f32_e32 v244, v244
	v_rcp_f32_e32 v245, v245
	s_nop 0
	v_mul_f32_e32 v242, v242, v238
	v_mul_f32_e32 v243, v243, v239
	v_mul_f32_e32 v244, v244, v240
	v_mul_f32_e32 v245, v245, v241
	v_mul_f32_e32 v238, v24, v252
	v_mul_f32_e32 v239, v25, v252
	v_mul_f32_e32 v240, v26, v252
	v_mul_f32_e32 v241, v27, v252
; __device__ __forceinline__ unsigned cvt_pk_bf16(float lo, float hi) { unsigned r; asm volatile("v_cvt_pk_bf16_f32 %0, %1, %2" : "=v"(r) : "v"(lo), "v"(hi)); return r; }
; __device__ __forceinline__ float bflo(unsigned w) { return __uint_as_float(w << 16); }
; __device__ __forceinline__ float bfhi(unsigned w) { return __uint_as_float(w & 0xffff0000u); }
; __device__ __forceinline__ float silu_f(float x) { return x * __builtin_amdgcn_rcpf(1.0f + __builtin_amdgcn_exp2f(x * -1.4426950408889634f)); }
; __device__ __forceinline__ void ret_unit(ldsp lds, bf16_t* R, const bf16_t* RC, int b, int h, int qblk, float lgf2, float lgb2, const int tid_in) {
;     ...
; #pragma unroll
;         for (int db = 0; db < 4; ++db) { const u32x2 g2 = *(const u32x2*)(gp + 16 * db);
;             u32x2 w; w.x = cvt_pk_bf16(o[db][q4][0] * rstd * silu_f(bflo(g2.x)), o[db][q4][1] * rstd * silu_f(bfhi(g2.x)));
;             w.y = cvt_pk_bf16(o[db][q4][2] * rstd * silu_f(bflo(g2.y)), o[db][q4][3] * rstd * silu_f(bfhi(g2.y)));
;             *(u32x2*)(gp + 16 * db) = w; }
	v_mul_f32_e32 v238, v238, v242
	v_mul_f32_e32 v239, v239, v243
	v_mul_f32_e32 v240, v240, v244
	v_mul_f32_e32 v241, v241, v245
	v_cvt_pk_bf16_f32 v120, v238, v239
	v_cvt_pk_bf16_f32 v121, v240, v241
	global_store_dwordx2 v228, v[120:121], s[86:87] offset:32
	v_lshlrev_b32_e32 v238, 16, v122
	v_and_b32_e32 v239, 0xffff0000, v122
	v_lshlrev_b32_e32 v240, 16, v123
	v_and_b32_e32 v241, 0xffff0000, v123
	v_mul_f32_e32 v242, 0xbfb8aa3b, v238
	v_mul_f32_e32 v243, 0xbfb8aa3b, v239
	v_mul_f32_e32 v244, 0xbfb8aa3b, v240
	v_mul_f32_e32 v245, 0xbfb8aa3b, v241
	v_exp_f32_e32 v242, v242
	v_exp_f32_e32 v243, v243
	v_exp_f32_e32 v244, v244
	v_exp_f32_e32 v245, v245
	s_nop 0
	v_add_f32_e32 v242, 1.0, v242
	v_add_f32_e32 v243, 1.0, v243
	v_add_f32_e32 v244, 1.0, v244
	v_add_f32_e32 v245, 1.0, v245
	v_rcp_f32_e32 v242, v242
	v_rcp_f32_e32 v243, v243
	v_rcp_f32_e32 v244, v244
	v_rcp_f32_e32 v245, v245
	s_nop 0
	v_mul_f32_e32 v242, v242, v238
	v_mul_f32_e32 v243, v243, v239
	v_mul_f32_e32 v244, v244, v240
	v_mul_f32_e32 v245, v245, v241
	v_mul_f32_e32 v238, v40, v252
	v_mul_f32_e32 v239, v41, v252
	v_mul_f32_e32 v240, v42, v252
	v_mul_f32_e32 v241, v43, v252
	v_mul_f32_e32 v238, v238, v242
	v_mul_f32_e32 v239, v239, v243
	v_mul_f32_e32 v240, v240, v244
	v_mul_f32_e32 v241, v241, v245
	v_cvt_pk_bf16_f32 v122, v238, v239
	v_cvt_pk_bf16_f32 v123, v240, v241
	global_store_dwordx2 v228, v[122:123], s[86:87] offset:64
	v_lshlrev_b32_e32 v238, 16, v124
	v_and_b32_e32 v239, 0xffff0000, v124
	v_lshlrev_b32_e32 v240, 16, v125
	v_and_b32_e32 v241, 0xffff0000, v125
	v_mul_f32_e32 v242, 0xbfb8aa3b, v238
	v_mul_f32_e32 v243, 0xbfb8aa3b, v239
	v_mul_f32_e32 v244, 0xbfb8aa3b, v240
	v_mul_f32_e32 v245, 0xbfb8aa3b, v241
	v_exp_f32_e32 v242, v242
	v_exp_f32_e32 v243, v243
	v_exp_f32_e32 v244, v244
	v_exp_f32_e32 v245, v245
	s_nop 0
	v_add_f32_e32 v242, 1.0, v242
	v_add_f32_e32 v243, 1.0, v243
	v_add_f32_e32 v244, 1.0, v244
	v_add_f32_e32 v245, 1.0, v245
	v_rcp_f32_e32 v242, v242
	v_rcp_f32_e32 v243, v243
	v_rcp_f32_e32 v244, v244
	v_rcp_f32_e32 v245, v245
	s_nop 0
	v_mul_f32_e32 v242, v242, v238
	v_mul_f32_e32 v243, v243, v239
	v_mul_f32_e32 v244, v244, v240
	v_mul_f32_e32 v245, v245, v241
	v_mul_f32_e32 v238, v56, v252
	v_mul_f32_e32 v239, v57, v252
	v_mul_f32_e32 v240, v58, v252
	v_mul_f32_e32 v241, v59, v252
	v_mul_f32_e32 v238, v238, v242
	v_mul_f32_e32 v239, v239, v243
	v_mul_f32_e32 v240, v240, v244
	v_mul_f32_e32 v241, v241, v245
	v_cvt_pk_bf16_f32 v124, v238, v239
	v_cvt_pk_bf16_f32 v125, v240, v241
	global_store_dwordx2 v228, v[124:125], s[86:87] offset:96
	v_lshlrev_b32_e32 v238, 16, v126
	v_and_b32_e32 v239, 0xffff0000, v126
	v_lshlrev_b32_e32 v240, 16, v127
	v_and_b32_e32 v241, 0xffff0000, v127
	v_mul_f32_e32 v242, 0xbfb8aa3b, v238
	v_mul_f32_e32 v243, 0xbfb8aa3b, v239
	v_mul_f32_e32 v244, 0xbfb8aa3b, v240
	v_mul_f32_e32 v245, 0xbfb8aa3b, v241
	v_exp_f32_e32 v242, v242
	v_exp_f32_e32 v243, v243
	v_exp_f32_e32 v244, v244
	v_exp_f32_e32 v245, v245
	s_nop 0
	v_add_f32_e32 v242, 1.0, v242
	v_add_f32_e32 v243, 1.0, v243
	v_add_f32_e32 v244, 1.0, v244
	v_add_f32_e32 v245, 1.0, v245
	v_rcp_f32_e32 v242, v242
	v_rcp_f32_e32 v243, v243
	v_rcp_f32_e32 v244, v244
	v_rcp_f32_e32 v245, v245
	s_nop 0
	v_mul_f32_e32 v242, v242, v238
	v_mul_f32_e32 v243, v243, v239
	v_mul_f32_e32 v244, v244, v240
	v_mul_f32_e32 v245, v245, v241
	v_mul_f32_e32 v238, v12, v253
	v_mul_f32_e32 v239, v13, v253
	v_mul_f32_e32 v240, v14, v253
	v_mul_f32_e32 v241, v15, v253
	v_mul_f32_e32 v238, v238, v242
	v_mul_f32_e32 v239, v239, v243
	v_mul_f32_e32 v240, v240, v244
	v_mul_f32_e32 v241, v241, v245
	v_cvt_pk_bf16_f32 v126, v238, v239
; __device__ __forceinline__ unsigned cvt_pk_bf16(float lo, float hi) { unsigned r; asm volatile("v_cvt_pk_bf16_f32 %0, %1, %2" : "=v"(r) : "v"(lo), "v"(hi)); return r; }
; __device__ __forceinline__ float bflo(unsigned w) { return __uint_as_float(w << 16); }
; __device__ __forceinline__ float bfhi(unsigned w) { return __uint_as_float(w & 0xffff0000u); }
; __device__ __forceinline__ float silu_f(float x) { return x * __builtin_amdgcn_rcpf(1.0f + __builtin_amdgcn_exp2f(x * -1.4426950408889634f)); }
; __device__ __forceinline__ void ret_unit(ldsp lds, bf16_t* R, const bf16_t* RC, int b, int h, int qblk, float lgf2, float lgb2, const int tid_in) {
;     ...
; #pragma unroll
;         for (int db = 0; db < 4; ++db) { const u32x2 g2 = *(const u32x2*)(gp + 16 * db);
;             u32x2 w; w.x = cvt_pk_bf16(o[db][q4][0] * rstd * silu_f(bflo(g2.x)), o[db][q4][1] * rstd * silu_f(bfhi(g2.x)));
;             w.y = cvt_pk_bf16(o[db][q4][2] * rstd * silu_f(bflo(g2.y)), o[db][q4][3] * rstd * silu_f(bfhi(g2.y)));
;             *(u32x2*)(gp + 16 * db) = w; }
; __device__ __forceinline__ void ret_phase(ldsp lds, bf16_t* R, const bf16_t* RC, const float* decay, const int tid, const int bx) {
;     ...
;     for (int i = 0; i < 4; ++i) {
;         const int bh = 8 * i + xcd, b = bh >> 2, h = bh & 3;
;         const float lgf2 = decay[h], lgb2 = decay[4 + h];
;         ret_unit(lds, R, RC, b, h, slot, lgf2, lgb2, tid);
;     }
	v_cvt_pk_bf16_f32 v127, v240, v241
	global_store_dwordx2 v229, v[126:127], s[86:87] offset:0
	v_lshlrev_b32_e32 v238, 16, v128
	v_and_b32_e32 v239, 0xffff0000, v128
	v_lshlrev_b32_e32 v240, 16, v129
	v_and_b32_e32 v241, 0xffff0000, v129
	v_mul_f32_e32 v242, 0xbfb8aa3b, v238
	v_mul_f32_e32 v243, 0xbfb8aa3b, v239
	v_mul_f32_e32 v244, 0xbfb8aa3b, v240
	v_mul_f32_e32 v245, 0xbfb8aa3b, v241
	v_exp_f32_e32 v242, v242
	v_exp_f32_e32 v243, v243
	v_exp_f32_e32 v244, v244
	v_exp_f32_e32 v245, v245
	s_nop 0
	v_add_f32_e32 v242, 1.0, v242
	v_add_f32_e32 v243, 1.0, v243
	v_add_f32_e32 v244, 1.0, v244
	v_add_f32_e32 v245, 1.0, v245
	v_rcp_f32_e32 v242, v242
	v_rcp_f32_e32 v243, v243
	v_rcp_f32_e32 v244, v244
	v_rcp_f32_e32 v245, v245
	s_nop 0
	v_mul_f32_e32 v242, v242, v238
	v_mul_f32_e32 v243, v243, v239
	v_mul_f32_e32 v244, v244, v240
	v_mul_f32_e32 v245, v245, v241
	v_mul_f32_e32 v238, v28, v253
	v_mul_f32_e32 v239, v29, v253
	v_mul_f32_e32 v240, v30, v253
	v_mul_f32_e32 v241, v31, v253
	v_mul_f32_e32 v238, v238, v242
	v_mul_f32_e32 v239, v239, v243
	v_mul_f32_e32 v240, v240, v244
	v_mul_f32_e32 v241, v241, v245
	v_cvt_pk_bf16_f32 v128, v238, v239
	v_cvt_pk_bf16_f32 v129, v240, v241
	global_store_dwordx2 v229, v[128:129], s[86:87] offset:32
	v_lshlrev_b32_e32 v238, 16, v130
	v_and_b32_e32 v239, 0xffff0000, v130
	v_lshlrev_b32_e32 v240, 16, v131
	v_and_b32_e32 v241, 0xffff0000, v131
	v_mul_f32_e32 v242, 0xbfb8aa3b, v238
	v_mul_f32_e32 v243, 0xbfb8aa3b, v239
	v_mul_f32_e32 v244, 0xbfb8aa3b, v240
	v_mul_f32_e32 v245, 0xbfb8aa3b, v241
	v_exp_f32_e32 v242, v242
	v_exp_f32_e32 v243, v243
	v_exp_f32_e32 v244, v244
	v_exp_f32_e32 v245, v245
	s_nop 0
	v_add_f32_e32 v242, 1.0, v242
	v_add_f32_e32 v243, 1.0, v243
	v_add_f32_e32 v244, 1.0, v244
	v_add_f32_e32 v245, 1.0, v245
	v_rcp_f32_e32 v242, v242
	v_rcp_f32_e32 v243, v243
	v_rcp_f32_e32 v244, v244
	v_rcp_f32_e32 v245, v245
	s_nop 0
	v_mul_f32_e32 v242, v242, v238
	v_mul_f32_e32 v243, v243, v239
	v_mul_f32_e32 v244, v244, v240
	v_mul_f32_e32 v245, v245, v241
	v_mul_f32_e32 v238, v44, v253
	v_mul_f32_e32 v239, v45, v253
	v_mul_f32_e32 v240, v46, v253
	v_mul_f32_e32 v241, v47, v253
	v_mul_f32_e32 v238, v238, v242
	v_mul_f32_e32 v239, v239, v243
	v_mul_f32_e32 v240, v240, v244
	v_mul_f32_e32 v241, v241, v245
	v_cvt_pk_bf16_f32 v130, v238, v239
	v_cvt_pk_bf16_f32 v131, v240, v241
	global_store_dwordx2 v229, v[130:131], s[86:87] offset:64
	v_lshlrev_b32_e32 v238, 16, v132
	v_and_b32_e32 v239, 0xffff0000, v132
	v_lshlrev_b32_e32 v240, 16, v133
	v_and_b32_e32 v241, 0xffff0000, v133
	v_mul_f32_e32 v242, 0xbfb8aa3b, v238
	v_mul_f32_e32 v243, 0xbfb8aa3b, v239
	v_mul_f32_e32 v244, 0xbfb8aa3b, v240
	v_mul_f32_e32 v245, 0xbfb8aa3b, v241
	v_exp_f32_e32 v242, v242
	v_exp_f32_e32 v243, v243
	v_exp_f32_e32 v244, v244
	v_exp_f32_e32 v245, v245
	s_nop 0
	v_add_f32_e32 v242, 1.0, v242
	v_add_f32_e32 v243, 1.0, v243
	v_add_f32_e32 v244, 1.0, v244
	v_add_f32_e32 v245, 1.0, v245
	v_rcp_f32_e32 v242, v242
	v_rcp_f32_e32 v243, v243
	v_rcp_f32_e32 v244, v244
	v_rcp_f32_e32 v245, v245
	s_nop 0
	v_mul_f32_e32 v242, v242, v238
	v_mul_f32_e32 v243, v243, v239
	v_mul_f32_e32 v244, v244, v240
	v_mul_f32_e32 v245, v245, v241
	v_mul_f32_e32 v238, v60, v253
	v_mul_f32_e32 v239, v61, v253
	v_mul_f32_e32 v240, v62, v253
	v_mul_f32_e32 v241, v63, v253
	v_mul_f32_e32 v238, v238, v242
	v_mul_f32_e32 v239, v239, v243
	v_mul_f32_e32 v240, v240, v244
	v_mul_f32_e32 v241, v241, v245
	v_cvt_pk_bf16_f32 v132, v238, v239
	v_cvt_pk_bf16_f32 v133, v240, v241
	global_store_dwordx2 v229, v[132:133], s[86:87] offset:96
	s_add_i32 s3, s3, 1
	s_cmp_lt_u32 s3, 4
	s_cbranch_scc1 .Lret_unit
